# mid phase: cross-lane shuffles (xor 1/2/4/8) via DPP v_mov instead of ds_bpermute round trips (bitwise-identical reductions)
# speedup vs baseline: 1.0137x; 1.0010x over previous
.LBB0_247:
	s_or_b64 exec, exec, s[10:11]
	v_cndmask_b32_e64 v0, 8, 11, s[48:49]
	v_ashrrev_i32_e32 v128, v0, v141
	s_waitcnt vmcnt(4)
	v_lshlrev_b32_e32 v0, 16, v74
	v_and_b32_e32 v129, 0xffff0000, v74
	v_lshlrev_b32_e32 v142, 16, v75
	v_and_b32_e32 v143, 0xffff0000, v75
	s_waitcnt vmcnt(3)
	v_lshlrev_b32_e32 v74, 16, v82
	s_waitcnt vmcnt(2)
	v_lshlrev_b32_e32 v75, 16, v78
	v_lshlrev_b32_e32 v144, 16, v76
	v_and_b32_e32 v145, 0xffff0000, v76
	v_lshlrev_b32_e32 v146, 16, v77
	v_and_b32_e32 v147, 0xffff0000, v77
	v_mul_f32_e32 v154, v74, v75
	v_lshlrev_b32_e32 v75, 16, v66
	v_lshlrev_b32_e32 v74, 16, v54
	v_lshlrev_b32_e32 v77, 16, v58
	v_lshlrev_b32_e32 v76, 16, v50
	v_pk_mul_f32 v[74:75], v[76:77], v[74:75]
	v_and_b32_e32 v77, 0xffff0000, v58
	v_pk_mul_f32 v[74:75], v[108:109], v[74:75]
	v_and_b32_e32 v76, 0xffff0000, v50
	v_fma_f32 v74, v2, v154, v74
	v_add_f32_e32 v74, v74, v75
	v_mul_f32_e32 v0, v74, v0
	v_and_b32_e32 v75, 0xffff0000, v66
	v_and_b32_e32 v74, 0xffff0000, v54
	v_and_b32_e32 v82, 0xffff0000, v82
	v_and_b32_e32 v78, 0xffff0000, v78
	v_pk_mul_f32 v[74:75], v[76:77], v[74:75]
	v_mul_f32_e32 v78, v82, v78
	v_pk_mul_f32 v[74:75], v[26:27], v[74:75]
	v_lshlrev_b32_e32 v77, 16, v59
	v_fma_f32 v50, v3, v78, v74
	v_add_f32_e32 v50, v50, v75
	v_lshlrev_b32_e32 v75, 16, v67
	v_lshlrev_b32_e32 v74, 16, v55
	v_lshlrev_b32_e32 v76, 16, v51
	v_lshlrev_b32_e32 v148, 16, v79
	v_lshlrev_b32_e32 v149, 16, v83
	v_pk_mul_f32 v[74:75], v[76:77], v[74:75]
	v_mul_f32_e32 v78, v50, v129
	v_mul_f32_e32 v50, v149, v148
	v_pk_mul_f32 v[74:75], v[106:107], v[74:75]
	v_and_b32_e32 v67, 0xffff0000, v67
	v_fma_f32 v50, v4, v50, v74
	v_add_f32_e32 v50, v50, v75
	v_and_b32_e32 v66, 0xffff0000, v55
	v_and_b32_e32 v55, 0xffff0000, v59
	v_and_b32_e32 v54, 0xffff0000, v51
	v_and_b32_e32 v83, 0xffff0000, v83
	v_and_b32_e32 v79, 0xffff0000, v79
	v_mul_f32_e32 v74, v50, v142
	v_pk_mul_f32 v[50:51], v[54:55], v[66:67]
	v_mul_f32_e32 v58, v83, v79
	v_pk_mul_f32 v[50:51], v[28:29], v[50:51]
	v_lshlrev_b32_e32 v55, 16, v60
	v_fma_f32 v50, v5, v58, v50
	v_add_f32_e32 v50, v50, v51
	v_mul_f32_e32 v75, v50, v143
	v_lshlrev_b32_e32 v51, 16, v68
	v_lshlrev_b32_e32 v50, 16, v56
	v_lshlrev_b32_e32 v54, 16, v52
	v_lshlrev_b32_e32 v150, 16, v84
	v_lshlrev_b32_e32 v151, 16, v80
	v_pk_mul_f32 v[50:51], v[54:55], v[50:51]
	v_mul_f32_e32 v58, v150, v151
	v_pk_mul_f32 v[50:51], v[104:105], v[50:51]
	v_and_b32_e32 v55, 0xffff0000, v60
	v_fma_f32 v50, v6, v58, v50
	v_add_f32_e32 v50, v50, v51
	v_mul_f32_e32 v76, v50, v144
	v_and_b32_e32 v51, 0xffff0000, v68
	v_and_b32_e32 v50, 0xffff0000, v56
	v_and_b32_e32 v54, 0xffff0000, v52
	v_and_b32_e32 v84, 0xffff0000, v84
	v_and_b32_e32 v80, 0xffff0000, v80
	v_pk_mul_f32 v[50:51], v[54:55], v[50:51]
	v_mul_f32_e32 v58, v84, v80
	v_pk_mul_f32 v[50:51], v[30:31], v[50:51]
	s_waitcnt vmcnt(1)
	v_and_b32_e32 v68, 0xffff0000, v70
	v_fma_f32 v50, v7, v58, v50
	v_lshlrev_b32_e32 v60, 16, v70
	v_mul_f32_e32 v54, v68, v68
	v_and_b32_e32 v58, 0xffff0000, v71
	v_lshlrev_b32_e32 v59, 16, v71
	v_fmac_f32_e32 v54, v60, v60
	v_pk_mul_f32 v[66:67], v[58:59], v[58:59]
	v_and_b32_e32 v70, 0xffff0000, v72
	v_add_f32_e32 v54, v67, v54
	v_lshlrev_b32_e32 v71, 16, v72
	v_add_f32_e32 v54, v66, v54
	v_pk_mul_f32 v[66:67], v[70:71], v[70:71]
	v_and_b32_e32 v72, 0xffff0000, v73
	v_add_f32_e32 v54, v67, v54
	v_lshlrev_b32_e32 v73, 16, v73
	v_add_f32_e32 v54, v66, v54
	v_pk_mul_f32 v[66:67], v[72:73], v[72:73]
	v_mbcnt_hi_u32_b32 v77, -1, v244
	v_add_f32_e32 v54, v67, v54
	v_add_f32_e32 v66, v66, v54
	v_and_b32_e32 v54, 64, v77
	v_add_u32_e32 v79, 64, v54
	v_xor_b32_e32 v54, 1, v77
	v_cmp_lt_i32_e32 vcc, v54, v79
	v_add_f32_e32 v50, v50, v51
	v_mul_f32_e32 v52, v50, v145
	v_cndmask_b32_e32 v54, v77, v54, vcc
	v_lshlrev_b32_e32 v67, 2, v54
	s_nop 1
	v_mov_b32_dpp v80, v66 quad_perm:[1,0,3,2] row_mask:0xf bank_mask:0xf
	v_lshlrev_b32_e32 v51, 16, v69
	v_lshlrev_b32_e32 v50, 16, v57
	v_lshlrev_b32_e32 v55, 16, v61
	v_lshlrev_b32_e32 v54, 16, v53
	v_pk_mul_f32 v[50:51], v[54:55], v[50:51]
	v_xor_b32_e32 v55, 2, v77
	v_cmp_lt_i32_e32 vcc, v55, v79
	v_lshlrev_b32_e32 v152, 16, v81
	v_lshlrev_b32_e32 v153, 16, v85
	v_cndmask_b32_e32 v55, v77, v55, vcc
	v_mul_f32_e32 v56, v153, v152
	v_pk_mul_f32 v[50:51], v[102:103], v[50:51]
	s_waitcnt lgkmcnt(0)
	v_add_f32_e32 v54, v66, v80
	v_lshlrev_b32_e32 v66, 2, v55
	v_fma_f32 v50, v8, v56, v50
	s_nop 1
	v_mov_b32_dpp v55, v54 quad_perm:[2,3,0,1] row_mask:0xf bank_mask:0xf
	v_add_f32_e32 v50, v50, v51
	v_mul_f32_e32 v56, v50, v146
	v_xor_b32_e32 v50, 4, v77
	v_cmp_lt_i32_e32 vcc, v50, v79
	v_and_b32_e32 v85, 0xffff0000, v85
	v_and_b32_e32 v81, 0xffff0000, v81
	v_cndmask_b32_e32 v50, v77, v50, vcc
	v_mul_f32_e32 v80, v85, v81
	v_and_b32_e32 v51, 0xffff0000, v69
	s_waitcnt lgkmcnt(0)
	v_add_f32_e32 v69, v54, v55
	v_lshlrev_b32_e32 v81, 2, v50
	s_nop 1
	v_mov_b32_dpp v82, v69 row_half_mirror row_mask:0xf bank_mask:0xf
	v_and_b32_e32 v50, 0xffff0000, v57
	v_and_b32_e32 v55, 0xffff0000, v61
	v_and_b32_e32 v54, 0xffff0000, v53
	v_pk_mul_f32 v[50:51], v[54:55], v[50:51]
	v_xor_b32_e32 v54, 8, v77
	v_cmp_lt_i32_e32 vcc, v54, v79
	s_waitcnt lgkmcnt(0)
	v_add_f32_e32 v53, v69, v82
	v_pk_mul_f32 v[50:51], v[32:33], v[50:51]
	v_cndmask_b32_e32 v54, v77, v54, vcc
	v_lshlrev_b32_e32 v82, 2, v54
	s_nop 1
	v_mov_b32_dpp v54, v53 row_mirror row_mask:0xf bank_mask:0xf
	v_fma_f32 v50, v9, v80, v50
	v_add_f32_e32 v50, v50, v51
	v_mul_f32_e32 v57, v50, v147
	v_xor_b32_e32 v50, 16, v77
	v_cmp_lt_i32_e32 vcc, v50, v79
	s_waitcnt lgkmcnt(0)
	v_add_f32_e32 v53, v53, v54
	v_ashrrev_i32_e32 v127, 31, v126
	v_cndmask_b32_e32 v50, v77, v50, vcc
	v_lshlrev_b32_e32 v77, 2, v50
	ds_bpermute_b32 v61, v77, v53
	v_lshlrev_b64 v[50:51], 11, v[126:127]
	v_lshl_add_u64 v[54:55], v[88:89], 0, v[50:51]
	v_cvt_pk_bf16_f32 v50, v0, v78
	v_cvt_pk_bf16_f32 v51, v74, v75
	s_waitcnt lgkmcnt(0)
	v_add_f32_e32 v0, v53, v61
	v_fmamk_f32 v0, v0, 0x3b800000, v243
	v_mul_f32_e32 v53, 0x4b800000, v0
	v_cmp_gt_f32_e32 vcc, s3, v0
	v_cvt_pk_bf16_f32 v52, v76, v52
	v_and_b32_e32 v61, 0xffff0000, v64
	s_nop 0
	v_cndmask_b32_e32 v0, v0, v53, vcc
	v_rsq_f32_e32 v0, v0
	v_cvt_pk_bf16_f32 v53, v56, v57
	global_store_dwordx4 v[54:55], v[50:53], off
	s_nop 1
	v_mul_f32_e32 v50, 0x45800000, v0
	v_cndmask_b32_e32 v0, v0, v50, vcc
	v_mul_f32_e32 v50, v0, v60
	v_mul_f32_e32 v74, v10, v50
	v_mul_f32_e32 v50, v0, v68
	v_mul_f32_e32 v75, v11, v50
	v_lshlrev_b32_e32 v50, 16, v62
	v_and_b32_e32 v51, 0xffff0000, v62
	v_pk_mul_f32 v[54:55], v[50:51], v[50:51]
	v_lshlrev_b32_e32 v52, 16, v63
	v_and_b32_e32 v53, 0xffff0000, v63
	v_pk_mul_f32 v[56:57], v[52:53], v[52:53]
	v_add_f32_e32 v54, v54, v55
	v_lshlrev_b32_e32 v60, 16, v64
	v_add_f32_e32 v54, v56, v54
	v_pk_mul_f32 v[68:69], v[60:61], v[60:61]
	v_add_f32_e32 v54, v57, v54
	v_lshlrev_b32_e32 v62, 16, v65
	v_and_b32_e32 v63, 0xffff0000, v65
	v_add_f32_e32 v54, v68, v54
	v_pk_mul_f32 v[64:65], v[62:63], v[62:63]
	v_add_f32_e32 v54, v69, v54
	v_add_f32_e32 v54, v64, v54
	v_add_f32_e32 v54, v65, v54
	s_nop 1
	v_mov_b32_dpp v55, v54 quad_perm:[1,0,3,2] row_mask:0xf bank_mask:0xf
	v_mul_f32_e32 v56, v0, v59
	v_mul_f32_e32 v64, v12, v56
	v_mul_f32_e32 v56, v0, v58
	v_mul_f32_e32 v65, v13, v56
	s_waitcnt lgkmcnt(0)
	v_add_f32_e32 v54, v54, v55
	s_nop 1
	v_mov_b32_dpp v55, v54 quad_perm:[2,3,0,1] row_mask:0xf bank_mask:0xf
	v_mul_f32_e32 v56, v0, v71
	v_mul_f32_e32 v71, v14, v56
	v_mul_f32_e32 v56, v0, v70
	v_mul_f32_e32 v70, v15, v56
	s_waitcnt lgkmcnt(0)
	v_add_f32_e32 v54, v54, v55
	s_nop 1
	v_mov_b32_dpp v55, v54 row_half_mirror row_mask:0xf bank_mask:0xf
	v_mul_f32_e32 v56, v0, v73
	v_mul_f32_e32 v0, v0, v72
	v_mul_f32_e32 v72, v17, v0
	v_mul_f32_e32 v73, v16, v56
	s_waitcnt lgkmcnt(0)
	v_add_f32_e32 v0, v54, v55
	s_nop 1
	v_mov_b32_dpp v69, v0 row_mirror row_mask:0xf bank_mask:0xf
	v_lshlrev_b64 v[54:55], 9, v[126:127]
	v_lshl_add_u64 v[56:57], v[90:91], 0, v[54:55]
	v_lshlrev_b64 v[58:59], 8, v[126:127]
	v_cvt_pk_bf16_f32 v68, v74, v75
	s_waitcnt lgkmcnt(0)
	v_add_f32_e32 v0, v0, v69
	ds_bpermute_b32 v54, v77, v0
	v_cvt_pk_bf16_f32 v69, v64, v65
	v_cvt_pk_bf16_f32 v70, v71, v70
	v_cvt_pk_bf16_f32 v71, v73, v72
	global_store_dwordx4 v[56:57], v[68:71], off
	s_and_saveexec_b64 s[10:11], s[42:43]
	s_cbranch_execz .LBB0_250
	s_waitcnt lgkmcnt(0)
	v_add_f32_e32 v0, v0, v54
	v_fmamk_f32 v0, v0, 0x3c000000, v243
	v_mul_f32_e32 v54, 0x4b800000, v0
	v_cmp_gt_f32_e32 vcc, s3, v0
	v_lshl_add_u64 v[64:65], v[92:93], 0, v[58:59]
	s_nop 0
	v_cndmask_b32_e32 v0, v0, v54, vcc
	v_rsq_f32_e32 v0, v0
	s_nop 0
	v_mul_f32_e32 v54, 0x45800000, v0
	v_cndmask_b32_e32 v0, v0, v54, vcc
	v_pk_mul_f32 v[50:51], v[0:1], v[50:51] op_sel_hi:[0,1]
	v_pk_mul_f32 v[52:53], v[0:1], v[52:53] op_sel_hi:[0,1]
	v_pk_mul_f32 v[54:55], v[22:23], v[50:51]
	v_pk_mul_f32 v[56:57], v[24:25], v[52:53]
	v_pk_mul_f32 v[50:51], v[0:1], v[60:61] op_sel_hi:[0,1]
	v_pk_mul_f32 v[52:53], v[0:1], v[62:63] op_sel_hi:[0,1]
	v_pk_mul_f32 v[50:51], v[18:19], v[50:51]
	v_pk_mul_f32 v[52:53], v[20:21], v[52:53]
	v_cvt_pk_bf16_f32 v60, v54, v55
	v_cvt_pk_bf16_f32 v61, v56, v57
	v_cvt_pk_bf16_f32 v62, v50, v51
	s_nop 0
	v_cvt_pk_bf16_f32 v63, v52, v53
	global_store_dwordx4 v[64:65], v[60:63], off
	s_and_b64 exec, exec, s[46:47]
	s_cbranch_execz .LBB0_250
	v_lshl_or_b32 v60, v128, 2, s12
	v_ashrrev_i32_e32 v61, 31, v60
	v_lshlrev_b64 v[60:61], 17, v[60:61]
	v_lshl_add_u64 v[60:61], s[56:57], 0, v[60:61]
	v_lshlrev_b32_e32 v0, 9, v140
	v_lshl_add_u64 v[60:61], v[60:61], 0, v[0:1]
	v_lshlrev_b32_e32 v0, 2, v86
	v_lshl_add_u64 v[60:61], v[60:61], 0, v[0:1]
	global_store_dwordx4 v[60:61], v[54:57], off
	global_store_dwordx4 v[60:61], v[50:53], off offset:16
.LBB0_250:
	s_or_b64 exec, exec, s[10:11]
	s_waitcnt vmcnt(2)
	v_lshlrev_b32_e32 v50, 16, v46
	s_nop 1
	v_mov_b32_dpp v51, v50 quad_perm:[1,0,3,2] row_mask:0xf bank_mask:0xf
	v_lshrrev_b32_e32 v0, 6, v140
	v_cvt_f32_ubyte0_e32 v64, v0
	v_and_b32_e32 v0, 63, v141
	v_cvt_f32_ubyte0_e32 v65, v0
	s_and_b64 vcc, s[44:45], s[48:49]
	v_cndmask_b32_e64 v0, v65, v64, s[38:39]
	v_mov_b32_e32 v68, v50
	s_and_saveexec_b64 s[10:11], vcc
	s_cbranch_execz .LBB0_252
	v_mul_f32_e32 v52, 0.15915494, v0
	v_rndne_f32_e32 v52, v52
	v_fmamk_f32 v53, v52, 0xc0c90fdb, v0
	v_fmac_f32_e32 v53, 0x343bbd2e, v52
	v_mul_f32_e32 v52, 0.15915494, v53
	v_sin_f32_e32 v53, v52
	v_cos_f32_e32 v52, v52
	s_waitcnt lgkmcnt(0)
	v_cndmask_b32_e64 v51, v51, -v51, s[40:41]
	v_pk_mul_f32 v[52:53], v[52:53], v[50:51]
	s_nop 0
	v_add_f32_e32 v68, v52, v53
.LBB0_252:
	s_or_b64 exec, exec, s[10:11]
	v_and_b32_e32 v60, 0xffff0000, v46
	s_nop 1
	v_mov_b32_dpp v46, v60 quad_perm:[1,0,3,2] row_mask:0xf bank_mask:0xf
	v_mov_b32_e32 v61, v60
	s_and_saveexec_b64 s[10:11], vcc
	s_cbranch_execz .LBB0_254
	s_waitcnt lgkmcnt(1)
	v_mul_f32_e32 v51, 0x3ea1e89b, v0
	v_mul_f32_e32 v52, 0.15915494, v51
	v_rndne_f32_e32 v52, v52
	v_fmac_f32_e32 v51, 0xc0c90fdb, v52
	v_fmac_f32_e32 v51, 0x343bbd2e, v52
	v_mul_f32_e32 v51, 0.15915494, v51
	v_sin_f32_e32 v53, v51
	v_cos_f32_e32 v52, v51
	s_waitcnt lgkmcnt(0)
	v_cndmask_b32_e64 v61, v46, -v46, s[40:41]
	v_pk_mul_f32 v[52:53], v[52:53], v[60:61]
	s_nop 0
	v_add_f32_e32 v61, v52, v53
.LBB0_254:
	s_or_b64 exec, exec, s[10:11]
	v_lshlrev_b32_e32 v52, 16, v47
	s_waitcnt lgkmcnt(0)
	s_nop 1
	v_mov_b32_dpp v46, v52 quad_perm:[1,0,3,2] row_mask:0xf bank_mask:0xf
	v_mov_b32_e32 v69, v52
	s_and_saveexec_b64 s[10:11], vcc
	s_cbranch_execz .LBB0_256
	v_mul_f32_e32 v51, 0x3dcccccd, v0
	v_mul_f32_e32 v53, 0.15915494, v51
	v_rndne_f32_e32 v53, v53
	v_fmac_f32_e32 v51, 0xc0c90fdb, v53
	v_fmac_f32_e32 v51, 0x343bbd2e, v53
	v_mul_f32_e32 v51, 0.15915494, v51
	v_sin_f32_e32 v55, v51
	v_cos_f32_e32 v54, v51
	s_waitcnt lgkmcnt(0)
	v_cndmask_b32_e64 v53, v46, -v46, s[40:41]
	v_pk_mul_f32 v[54:55], v[54:55], v[52:53]
	s_nop 0
	v_add_f32_e32 v69, v54, v55
.LBB0_256:
	s_or_b64 exec, exec, s[10:11]
	s_waitcnt lgkmcnt(0)
	v_and_b32_e32 v46, 0xffff0000, v47
	s_nop 1
	v_mov_b32_dpp v51, v46 quad_perm:[1,0,3,2] row_mask:0xf bank_mask:0xf
	v_mov_b32_e32 v47, v46
	s_and_saveexec_b64 s[10:11], vcc
	s_cbranch_execz .LBB0_258
	v_mul_f32_e32 v47, 0x3d0186e3, v0
	v_mul_f32_e32 v53, 0.15915494, v47
	v_rndne_f32_e32 v53, v53
	v_fmac_f32_e32 v47, 0xc0c90fdb, v53
	v_fmac_f32_e32 v47, 0x343bbd2e, v53
	v_mul_f32_e32 v47, 0.15915494, v47
	v_sin_f32_e32 v55, v47
	v_cos_f32_e32 v54, v47
	s_waitcnt lgkmcnt(0)
	v_cndmask_b32_e64 v47, v51, -v51, s[40:41]
	v_pk_mul_f32 v[54:55], v[54:55], v[46:47]
	s_nop 0
	v_add_f32_e32 v47, v54, v55
.LBB0_258:
	s_or_b64 exec, exec, s[10:11]
	v_lshlrev_b32_e32 v54, 16, v48
	s_waitcnt lgkmcnt(0)
	s_nop 1
	v_mov_b32_dpp v51, v54 quad_perm:[1,0,3,2] row_mask:0xf bank_mask:0xf
	v_mov_b32_e32 v70, v54
	s_and_saveexec_b64 s[10:11], vcc
	s_cbranch_execz .LBB0_260
	v_mul_f32_e32 v53, 0x3c23d70b, v0
	v_mul_f32_e32 v55, 0.15915494, v53
	v_rndne_f32_e32 v55, v55
	v_fmac_f32_e32 v53, 0xc0c90fdb, v55
	v_fmac_f32_e32 v53, 0x343bbd2e, v55
	v_mul_f32_e32 v53, 0.15915494, v53
	v_sin_f32_e32 v57, v53
	v_cos_f32_e32 v56, v53
	s_waitcnt lgkmcnt(0)
	v_cndmask_b32_e64 v55, v51, -v51, s[40:41]
	v_pk_mul_f32 v[56:57], v[56:57], v[54:55]
	s_nop 0
	v_add_f32_e32 v70, v56, v57
.LBB0_260:
	s_or_b64 exec, exec, s[10:11]
	v_and_b32_e32 v62, 0xffff0000, v48
	s_nop 1
	v_mov_b32_dpp v48, v62 quad_perm:[1,0,3,2] row_mask:0xf bank_mask:0xf
	v_mov_b32_e32 v63, v62
	s_and_saveexec_b64 s[10:11], vcc
	s_cbranch_execz .LBB0_262
	s_waitcnt lgkmcnt(1)
	v_mul_f32_e32 v51, 0x3b4f3e39, v0
	v_mul_f32_e32 v53, 0.15915494, v51
	v_rndne_f32_e32 v53, v53
	v_fmac_f32_e32 v51, 0xc0c90fdb, v53
	v_fmac_f32_e32 v51, 0x343bbd2e, v53
	v_mul_f32_e32 v51, 0.15915494, v51
	v_sin_f32_e32 v57, v51
	v_cos_f32_e32 v56, v51
	s_waitcnt lgkmcnt(0)
	v_cndmask_b32_e64 v63, v48, -v48, s[40:41]
	v_pk_mul_f32 v[56:57], v[56:57], v[62:63]
	s_nop 0
	v_add_f32_e32 v63, v56, v57
.LBB0_262:
	s_or_b64 exec, exec, s[10:11]
	v_lshlrev_b32_e32 v56, 16, v49
	s_waitcnt lgkmcnt(0)
	s_nop 1
	v_mov_b32_dpp v48, v56 quad_perm:[1,0,3,2] row_mask:0xf bank_mask:0xf
	v_mov_b32_e32 v71, v56
	s_and_saveexec_b64 s[10:11], vcc
	s_cbranch_execz .LBB0_264
	v_mul_f32_e32 v51, 0x3a831270, v0
	v_mul_f32_e32 v53, 0.15915494, v51
	v_rndne_f32_e32 v53, v53
	v_fmac_f32_e32 v51, 0xc0c90fdb, v53
	v_fmac_f32_e32 v51, 0x343bbd2e, v53
	v_mul_f32_e32 v51, 0.15915494, v51
	v_sin_f32_e32 v73, v51
	v_cos_f32_e32 v72, v51
	s_waitcnt lgkmcnt(0)
	v_cndmask_b32_e64 v57, v48, -v48, s[40:41]
	v_pk_mul_f32 v[72:73], v[72:73], v[56:57]
	s_nop 0
	v_add_f32_e32 v71, v72, v73
.LBB0_264:
	s_or_b64 exec, exec, s[10:11]
	s_waitcnt lgkmcnt(0)
	v_and_b32_e32 v48, 0xffff0000, v49
	s_nop 1
	v_mov_b32_dpp v51, v48 quad_perm:[1,0,3,2] row_mask:0xf bank_mask:0xf
	v_mov_b32_e32 v49, v48
	s_and_saveexec_b64 s[10:11], vcc
	s_cbranch_execnz .LBB0_271
	s_or_b64 exec, exec, s[10:11]
	s_and_saveexec_b64 s[10:11], s[44:45]
	s_cbranch_execnz .LBB0_272

.LBB0_268:
	s_or_b64 exec, exec, s[10:11]
	v_lshlrev_b32_e32 v62, 16, v38
	v_lshlrev_b32_e32 v68, 16, v39
	v_and_b32_e32 v70, 0xffff0000, v39
	s_nop 1
	v_mov_b32_dpp v39, v62 quad_perm:[2,3,0,1] row_mask:0xf bank_mask:0xf
	v_lshlrev_b32_e32 v46, 16, v42
	v_and_b32_e32 v54, 0xffff0000, v42
	v_lshlrev_b32_e32 v48, 16, v43
	v_and_b32_e32 v56, 0xffff0000, v43
	s_waitcnt lgkmcnt(0)
	v_mul_f32_e32 v63, v139, v39
	v_pk_mul_f32 v[42:43], v[110:111], v[62:63]
	v_and_b32_e32 v64, 0xffff0000, v38
	v_add_f32_e32 v39, v42, v43
	v_lshlrev_b32_e32 v38, 16, v44
	v_and_b32_e32 v50, 0xffff0000, v44
	v_cndmask_b32_e64 v44, v62, v39, s[48:49]
	s_nop 1
	v_mov_b32_dpp v39, v64 quad_perm:[2,3,0,1] row_mask:0xf bank_mask:0xf
	v_lshlrev_b32_e32 v72, 16, v40
	v_and_b32_e32 v74, 0xffff0000, v40
	v_lshlrev_b32_e32 v40, 16, v45
	v_and_b32_e32 v52, 0xffff0000, v45
	s_waitcnt lgkmcnt(0)
	v_mul_f32_e32 v65, v139, v39
	v_pk_mul_f32 v[42:43], v[112:113], v[64:65]
	v_lshlrev_b32_e32 v76, 16, v41
	v_add_f32_e32 v39, v42, v43
	v_cndmask_b32_e64 v45, v64, v39, s[48:49]
	s_nop 1
	v_mov_b32_dpp v39, v68 quad_perm:[2,3,0,1] row_mask:0xf bank_mask:0xf
	v_and_b32_e32 v60, 0xffff0000, v41
	s_nop 1
	v_mov_b32_dpp v41, v72 quad_perm:[2,3,0,1] row_mask:0xf bank_mask:0xf
	s_nop 1
	v_mov_b32_dpp v0, v46 quad_perm:[2,3,0,1] row_mask:0xf bank_mask:0xf
	s_nop 1
	v_mov_b32_dpp v47, v54 quad_perm:[2,3,0,1] row_mask:0xf bank_mask:0xf
	s_waitcnt lgkmcnt(3)
	v_mul_f32_e32 v69, v139, v39
	v_pk_mul_f32 v[42:43], v[114:115], v[68:69]
	s_waitcnt lgkmcnt(2)
	v_mul_f32_e32 v73, v139, v41
	v_add_f32_e32 v39, v42, v43
	v_cndmask_b32_e64 v57, v68, v39, s[48:49]
	s_nop 1
	v_mov_b32_dpp v39, v70 quad_perm:[2,3,0,1] row_mask:0xf bank_mask:0xf
	s_nop 1
	v_mov_b32_dpp v49, v48 quad_perm:[2,3,0,1] row_mask:0xf bank_mask:0xf
	s_nop 1
	v_mov_b32_dpp v55, v56 quad_perm:[2,3,0,1] row_mask:0xf bank_mask:0xf
	s_nop 1
	v_mov_b32_dpp v51, v50 quad_perm:[2,3,0,1] row_mask:0xf bank_mask:0xf
	s_nop 1
	v_mov_b32_dpp v53, v52 quad_perm:[2,3,0,1] row_mask:0xf bank_mask:0xf
	s_waitcnt lgkmcnt(4)
	v_mul_f32_e32 v71, v139, v39
	v_pk_mul_f32 v[42:43], v[116:117], v[70:71]
	s_nop 0
	v_add_f32_e32 v39, v42, v43
	v_pk_mul_f32 v[42:43], v[118:119], v[72:73]
	v_cndmask_b32_e64 v62, v70, v39, s[48:49]
	v_add_f32_e32 v41, v42, v43
	v_cndmask_b32_e64 v63, v72, v41, s[48:49]
	s_nop 1
	v_mov_b32_dpp v41, v74 quad_perm:[2,3,0,1] row_mask:0xf bank_mask:0xf
	s_nop 1
	v_mov_b32_dpp v39, v38 quad_perm:[2,3,0,1] row_mask:0xf bank_mask:0xf
	s_waitcnt lgkmcnt(1)
	v_mul_f32_e32 v75, v139, v41
	v_pk_mul_f32 v[42:43], v[120:121], v[74:75]
	s_nop 0
	v_add_f32_e32 v41, v42, v43
	s_nop 1
	v_mov_b32_dpp v42, v76 quad_perm:[2,3,0,1] row_mask:0xf bank_mask:0xf
	v_cndmask_b32_e64 v64, v74, v41, s[48:49]
	s_nop 1
	v_mov_b32_dpp v41, v40 quad_perm:[2,3,0,1] row_mask:0xf bank_mask:0xf
	s_waitcnt lgkmcnt(1)
	v_mul_f32_e32 v77, v139, v42
	v_pk_mul_f32 v[42:43], v[122:123], v[76:77]
	s_nop 0
	v_add_f32_e32 v42, v42, v43
	v_cndmask_b32_e64 v65, v76, v42, s[48:49]
	s_nop 1
	v_mov_b32_dpp v42, v60 quad_perm:[2,3,0,1] row_mask:0xf bank_mask:0xf
	s_waitcnt lgkmcnt(0)
	v_mul_f32_e32 v61, v139, v42
	v_pk_mul_f32 v[42:43], v[124:125], v[60:61]
	s_nop 0
	v_add_f32_e32 v42, v42, v43
	v_cndmask_b32_e64 v66, v60, v42, s[48:49]
	v_lshl_add_u64 v[60:61], v[58:59], 1, v[96:97]
	v_cvt_pk_bf16_f32 v42, v44, v45
	v_cvt_pk_bf16_f32 v43, v57, v62
	v_cvt_pk_bf16_f32 v44, v63, v64
	v_cvt_pk_bf16_f32 v45, v65, v66
	global_store_dwordx4 v[60:61], v[42:45], off
	s_and_saveexec_b64 s[10:11], s[42:43]
	s_cbranch_execz .LBB0_238
	v_mul_f32_e32 v53, v139, v53
	v_pk_mul_f32 v[60:61], v[124:125], v[52:53]
	v_mul_f32_e32 v41, v139, v41
	v_add_f32_e32 v53, v60, v61
	v_pk_mul_f32 v[60:61], v[122:123], v[40:41]
	v_mul_f32_e32 v51, v139, v51
	v_add_f32_e32 v41, v60, v61
	v_pk_mul_f32 v[60:61], v[120:121], v[50:51]
	v_mul_f32_e32 v39, v139, v39
	v_add_f32_e32 v51, v60, v61
	v_pk_mul_f32 v[60:61], v[118:119], v[38:39]
	v_mul_f32_e32 v57, v139, v55
	v_add_f32_e32 v39, v60, v61
	v_pk_mul_f32 v[60:61], v[116:117], v[56:57]
	v_mul_f32_e32 v49, v139, v49
	v_add_f32_e32 v55, v60, v61
	v_cndmask_b32_e64 v57, v56, v55, s[48:49]
	v_pk_mul_f32 v[60:61], v[114:115], v[48:49]
	v_mul_f32_e32 v55, v139, v47
	v_add_f32_e32 v49, v60, v61
	v_pk_mul_f32 v[60:61], v[112:113], v[54:55]
	v_cndmask_b32_e64 v53, v52, v53, s[48:49]
	v_add_f32_e32 v47, v60, v61
	v_cndmask_b32_e64 v55, v54, v47, s[48:49]
	v_mul_f32_e32 v47, v139, v0
	v_pk_mul_f32 v[60:61], v[110:111], v[46:47]
	v_cndmask_b32_e64 v41, v40, v41, s[48:49]
	v_add_f32_e32 v0, v60, v61
	v_cndmask_b32_e64 v51, v50, v51, s[48:49]
	v_cndmask_b32_e64 v39, v38, v39, s[48:49]
	v_cndmask_b32_e64 v49, v48, v49, s[48:49]
	v_cndmask_b32_e64 v0, v46, v0, s[48:49]
	v_lshl_add_u64 v[64:65], v[98:99], 0, v[58:59]
	v_cvt_pk_bf16_f32 v60, v0, v55
	v_cvt_pk_bf16_f32 v61, v49, v57
	v_cvt_pk_bf16_f32 v62, v39, v51
	v_cvt_pk_bf16_f32 v63, v41, v53
	v_lshlrev_b32_e32 v42, 16, v34
	v_and_b32_e32 v43, 0xffff0000, v34
	v_lshlrev_b32_e32 v44, 16, v35
	v_and_b32_e32 v45, 0xffff0000, v35
	v_lshlrev_b32_e32 v34, 16, v36
	v_and_b32_e32 v35, 0xffff0000, v36
	v_lshlrev_b32_e32 v36, 16, v37
	v_and_b32_e32 v37, 0xffff0000, v37
	global_store_dwordx4 v[64:65], v[60:63], off
	s_nop 1
	v_lshl_add_u64 v[62:63], v[100:101], 0, v[58:59]
	v_cvt_pk_bf16_f32 v58, v42, v43
	v_cvt_pk_bf16_f32 v59, v44, v45
	v_cvt_pk_bf16_f32 v60, v34, v35
	v_cvt_pk_bf16_f32 v61, v36, v37
	global_store_dwordx4 v[62:63], v[58:61], off
	s_and_b64 exec, exec, s[46:47]
	s_cbranch_execz .LBB0_238
	v_lshl_or_b32 v58, v128, 2, s12
	v_ashrrev_i32_e32 v59, 31, v58
	v_lshlrev_b64 v[58:59], 15, v[58:59]
	v_lshlrev_b32_e32 v0, 7, v140
	v_lshl_add_u64 v[58:59], v[58:59], 0, v[0:1]
	v_or_b32_e32 v58, v58, v86
	v_lshlrev_b64 v[58:59], 2, v[58:59]
	v_lshl_add_u64 v[60:61], s[16:17], 0, v[58:59]
	v_mov_b32_e32 v47, v54
	v_mov_b32_e32 v49, v56
	global_store_dwordx4 v[60:61], v[46:49], off
	s_mov_b32 s24, 0x7400000
	v_mov_b32_e32 v39, v50
	v_lshl_add_u64 v[46:47], s[62:63], 0, v[58:59]
	v_add_co_u32_e32 v48, vcc, s24, v46
	v_mov_b32_e32 v41, v52
	s_nop 0
	v_addc_co_u32_e32 v49, vcc, 0, v47, vcc
	global_store_dwordx4 v[48:49], v[38:41], off offset:16
	s_nop 1
	v_lshl_add_u64 v[38:39], s[18:19], 0, v[58:59]
	global_store_dwordx4 v[38:39], v[42:45], off
	v_add_co_u32_e32 v38, vcc, 0x8400000, v46
	s_nop 1
	v_addc_co_u32_e32 v39, vcc, 0, v47, vcc
	global_store_dwordx4 v[38:39], v[34:37], off offset:16
	s_branch .LBB0_238

.LBB0_277:
	s_lshl_b32 s11, s10, 7
	v_add_u32_e32 v4, s11, v102
	v_mad_i64_i32 v[2:3], s[14:15], v4, s55, v[76:77]
	global_load_dwordx4 v[62:65], v[2:3], off offset:1536 nt
	global_load_dwordx4 v[58:61], v[2:3], off offset:2048 nt
	v_add_u32_e32 v2, 16, v4
	v_mad_i64_i32 v[2:3], s[14:15], v2, s55, v[76:77]
	global_load_dwordx4 v[54:57], v[2:3], off offset:1536 nt
	global_load_dwordx4 v[50:53], v[2:3], off offset:2048 nt
	v_add_u32_e32 v2, 32, v4
	v_mad_i64_i32 v[2:3], s[14:15], v2, s55, v[76:77]
	global_load_dwordx4 v[46:49], v[2:3], off offset:1536 nt
	global_load_dwordx4 v[42:45], v[2:3], off offset:2048 nt
	v_add_u32_e32 v2, 48, v4
	v_mad_i64_i32 v[2:3], s[14:15], v2, s55, v[76:77]
	global_load_dwordx4 v[38:41], v[2:3], off offset:1536 nt
	global_load_dwordx4 v[34:37], v[2:3], off offset:2048 nt
	v_add_u32_e32 v2, 64, v4
	v_mad_i64_i32 v[2:3], s[14:15], v2, s55, v[76:77]
	global_load_dwordx4 v[30:33], v[2:3], off offset:1536 nt
	global_load_dwordx4 v[26:29], v[2:3], off offset:2048 nt
	v_add_u32_e32 v2, 0x50, v4
	v_mad_i64_i32 v[2:3], s[14:15], v2, s55, v[76:77]
	global_load_dwordx4 v[22:25], v[2:3], off offset:1536 nt
	global_load_dwordx4 v[18:21], v[2:3], off offset:2048 nt
	v_add_u32_e32 v2, 0x60, v4
	v_mad_i64_i32 v[2:3], s[14:15], v2, s55, v[76:77]
	global_load_dwordx4 v[14:17], v[2:3], off offset:1536 nt
	global_load_dwordx4 v[10:13], v[2:3], off offset:2048 nt
	v_add_u32_e32 v2, 0x70, v4
	v_mad_i64_i32 v[2:3], s[14:15], v2, s55, v[76:77]
	global_load_dwordx4 v[6:9], v[2:3], off offset:1536 nt
	s_nop 0
	global_load_dwordx4 v[2:5], v[2:3], off offset:2048 nt
	s_mov_b32 s5, 0
	s_waitcnt vmcnt(0)
	v_lshlrev_b32_e32 v98, 16, v62
	v_mul_f32_e32 v99, 0x3d372713, v98
	v_mul_f32_e32 v99, v99, v98
	v_fma_f32 v99, v99, v98, v98
	v_mul_f32_e32 v99, 0x3f4c422a, v99
	v_add_f32_e32 v99, v99, v99
	v_mul_f32_e32 v99, 0x3fb8aa3b, v99
	v_exp_f32_e32 v99, v99
	v_mul_f32_e32 v98, 0.5, v98
	v_and_b32_e32 v62, 0xffff0000, v62
	v_add_f32_e32 v99, 1.0, v99
	v_div_scale_f32 v100, s[14:15], v99, v99, 2.0
	v_rcp_f32_e32 v101, v100
	s_nop 0
	v_fma_f32 v115, -v100, v101, 1.0
	v_fmac_f32_e32 v101, v115, v101
	v_div_scale_f32 v115, vcc, 2.0, v99, 2.0
	v_mul_f32_e32 v116, v115, v101
	v_fma_f32 v117, -v100, v116, v115
	v_fmac_f32_e32 v116, v117, v101
	v_fma_f32 v100, -v100, v116, v115
	v_div_fmas_f32 v100, v100, v101, v116
	v_div_fixup_f32 v99, v100, v99, 2.0
	v_sub_f32_e32 v99, 1.0, v99
	v_add_f32_e32 v99, 1.0, v99
	v_mul_f32_e32 v98, v98, v99
	v_mul_f32_e32 v99, 0x3d372713, v62
	v_mul_f32_e32 v99, v99, v62
	v_fma_f32 v99, v99, v62, v62
	v_mul_f32_e32 v99, 0x3f4c422a, v99
	v_add_f32_e32 v99, v99, v99
	v_mul_f32_e32 v99, 0x3fb8aa3b, v99
	v_exp_f32_e32 v99, v99
	v_mul_f32_e32 v62, 0.5, v62
	v_add_f32_e32 v99, 1.0, v99
	v_div_scale_f32 v100, s[14:15], v99, v99, 2.0
	v_rcp_f32_e32 v101, v100
	s_nop 0
	v_fma_f32 v115, -v100, v101, 1.0
	v_fmac_f32_e32 v101, v115, v101
	v_div_scale_f32 v115, vcc, 2.0, v99, 2.0
	v_mul_f32_e32 v116, v115, v101
	v_fma_f32 v117, -v100, v116, v115
	v_fmac_f32_e32 v116, v117, v101
	v_fma_f32 v100, -v100, v116, v115
	v_div_fmas_f32 v100, v100, v101, v116
	v_div_fixup_f32 v99, v100, v99, 2.0
	v_sub_f32_e32 v99, 1.0, v99
	v_add_f32_e32 v99, 1.0, v99
	v_mul_f32_e32 v99, v62, v99
	v_lshlrev_b32_e32 v62, 16, v58
	v_mul_f32_e32 v100, 0x3d372713, v62
	v_mul_f32_e32 v100, v100, v62
	v_fma_f32 v100, v100, v62, v62
	v_mul_f32_e32 v100, 0x3f4c422a, v100
	v_add_f32_e32 v100, v100, v100
	v_mul_f32_e32 v100, 0x3fb8aa3b, v100
	v_exp_f32_e32 v100, v100
	v_mul_f32_e32 v62, 0.5, v62
	v_and_b32_e32 v58, 0xffff0000, v58
	v_cvt_pk_bf16_f32 v98, v98, v99
	v_add_f32_e32 v100, 1.0, v100
	v_div_scale_f32 v101, s[14:15], v100, v100, 2.0
	v_rcp_f32_e32 v115, v101
	s_nop 0
	v_fma_f32 v116, -v101, v115, 1.0
	v_fmac_f32_e32 v115, v116, v115
	v_div_scale_f32 v116, vcc, 2.0, v100, 2.0
	v_mul_f32_e32 v117, v116, v115
	v_fma_f32 v118, -v101, v117, v116
	v_fmac_f32_e32 v117, v118, v115
	v_fma_f32 v101, -v101, v117, v116
	v_div_fmas_f32 v101, v101, v115, v117
	v_div_fixup_f32 v100, v101, v100, 2.0
	v_sub_f32_e32 v100, 1.0, v100
	v_add_f32_e32 v100, 1.0, v100
	v_mul_f32_e32 v100, v62, v100
	v_mul_f32_e32 v62, 0x3d372713, v58
	v_mul_f32_e32 v62, v62, v58
	v_fma_f32 v62, v62, v58, v58
	v_mul_f32_e32 v62, 0x3f4c422a, v62
	v_add_f32_e32 v62, v62, v62
	v_mul_f32_e32 v62, 0x3fb8aa3b, v62
	v_exp_f32_e32 v62, v62
	v_mul_f32_e32 v58, 0.5, v58
	v_add_f32_e32 v62, 1.0, v62
	v_div_scale_f32 v101, s[14:15], v62, v62, 2.0
	v_rcp_f32_e32 v115, v101
	s_nop 0
	v_fma_f32 v116, -v101, v115, 1.0
	v_fmac_f32_e32 v115, v116, v115
	v_div_scale_f32 v116, vcc, 2.0, v62, 2.0
	v_mul_f32_e32 v117, v116, v115
	v_fma_f32 v118, -v101, v117, v116
	v_fmac_f32_e32 v117, v118, v115
	v_fma_f32 v101, -v101, v117, v116
	v_div_fmas_f32 v101, v101, v115, v117
	v_div_fixup_f32 v62, v101, v62, 2.0
	v_sub_f32_e32 v62, 1.0, v62
	v_add_f32_e32 v62, 1.0, v62
	v_mul_f32_e32 v101, v58, v62
	v_lshlrev_b32_e32 v58, 16, v63
	v_mul_f32_e32 v62, 0x3d372713, v58
	v_mul_f32_e32 v62, v62, v58
	v_fma_f32 v62, v62, v58, v58
	v_mul_f32_e32 v62, 0x3f4c422a, v62
	v_add_f32_e32 v62, v62, v62
	v_mul_f32_e32 v62, 0x3fb8aa3b, v62
	v_exp_f32_e32 v62, v62
	v_mul_f32_e32 v58, 0.5, v58
	v_add_f32_e32 v62, 1.0, v62
	v_div_scale_f32 v115, s[14:15], v62, v62, 2.0
	v_rcp_f32_e32 v116, v115
	s_nop 0
	v_fma_f32 v117, -v115, v116, 1.0
	v_fmac_f32_e32 v116, v117, v116
	v_div_scale_f32 v117, vcc, 2.0, v62, 2.0
	v_mul_f32_e32 v118, v117, v116
	v_fma_f32 v119, -v115, v118, v117
	v_fmac_f32_e32 v118, v119, v116
	v_fma_f32 v115, -v115, v118, v117
	v_div_fmas_f32 v115, v115, v116, v118
	v_div_fixup_f32 v62, v115, v62, 2.0
	v_sub_f32_e32 v62, 1.0, v62
	v_add_f32_e32 v62, 1.0, v62
	v_mul_f32_e32 v115, v58, v62
	v_and_b32_e32 v58, 0xffff0000, v63
	v_mul_f32_e32 v62, 0x3d372713, v58
	v_mul_f32_e32 v62, v62, v58
	v_fma_f32 v62, v62, v58, v58
	v_mul_f32_e32 v62, 0x3f4c422a, v62
	v_add_f32_e32 v62, v62, v62
	v_mul_f32_e32 v62, 0x3fb8aa3b, v62
	v_exp_f32_e32 v62, v62
	v_mul_f32_e32 v58, 0.5, v58
	v_add_f32_e32 v62, 1.0, v62
	v_div_scale_f32 v63, s[14:15], v62, v62, 2.0
	v_rcp_f32_e32 v116, v63
	s_nop 0
	v_fma_f32 v117, -v63, v116, 1.0
	v_fmac_f32_e32 v116, v117, v116
	v_div_scale_f32 v117, vcc, 2.0, v62, 2.0
	v_mul_f32_e32 v118, v117, v116
	v_fma_f32 v119, -v63, v118, v117
	v_fmac_f32_e32 v118, v119, v116
	v_fma_f32 v63, -v63, v118, v117
	v_div_fmas_f32 v63, v63, v116, v118
	v_div_fixup_f32 v62, v63, v62, 2.0
	v_sub_f32_e32 v62, 1.0, v62
	v_add_f32_e32 v62, 1.0, v62
	v_mul_f32_e32 v116, v58, v62
	v_lshlrev_b32_e32 v58, 16, v64
	v_mul_f32_e32 v62, 0x3d372713, v58
	v_mul_f32_e32 v62, v62, v58
	v_fma_f32 v62, v62, v58, v58
	v_mul_f32_e32 v62, 0x3f4c422a, v62
	v_add_f32_e32 v62, v62, v62
	v_mul_f32_e32 v62, 0x3fb8aa3b, v62
	v_exp_f32_e32 v62, v62
	v_mul_f32_e32 v58, 0.5, v58
	v_add_f32_e32 v62, 1.0, v62
	v_div_scale_f32 v63, s[14:15], v62, v62, 2.0
	v_rcp_f32_e32 v117, v63
	s_nop 0
	v_fma_f32 v118, -v63, v117, 1.0
	v_fmac_f32_e32 v117, v118, v117
	v_div_scale_f32 v118, vcc, 2.0, v62, 2.0
	v_mul_f32_e32 v119, v118, v117
	v_fma_f32 v120, -v63, v119, v118
	v_fmac_f32_e32 v119, v120, v117
	v_fma_f32 v63, -v63, v119, v118
	v_div_fmas_f32 v63, v63, v117, v119
	v_div_fixup_f32 v62, v63, v62, 2.0
	v_sub_f32_e32 v62, 1.0, v62
	v_add_f32_e32 v62, 1.0, v62
	v_mul_f32_e32 v117, v58, v62
	v_and_b32_e32 v58, 0xffff0000, v64
	v_mul_f32_e32 v62, 0x3d372713, v58
	v_mul_f32_e32 v62, v62, v58
	v_fma_f32 v62, v62, v58, v58
	v_mul_f32_e32 v62, 0x3f4c422a, v62
	v_add_f32_e32 v62, v62, v62
	v_mul_f32_e32 v62, 0x3fb8aa3b, v62
	v_exp_f32_e32 v62, v62
	v_mul_f32_e32 v58, 0.5, v58
	v_add_f32_e32 v62, 1.0, v62
	v_div_scale_f32 v63, s[14:15], v62, v62, 2.0
	v_rcp_f32_e32 v64, v63
	s_nop 0
	v_fma_f32 v118, -v63, v64, 1.0
	v_fmac_f32_e32 v64, v118, v64
	v_div_scale_f32 v118, vcc, 2.0, v62, 2.0
	v_mul_f32_e32 v119, v118, v64
	v_fma_f32 v120, -v63, v119, v118
	v_fmac_f32_e32 v119, v120, v64
	v_fma_f32 v63, -v63, v119, v118
	v_div_fmas_f32 v63, v63, v64, v119
	v_div_fixup_f32 v62, v63, v62, 2.0
	v_sub_f32_e32 v62, 1.0, v62
	v_add_f32_e32 v62, 1.0, v62
	v_mul_f32_e32 v64, v58, v62
	v_lshlrev_b32_e32 v58, 16, v65
	v_mul_f32_e32 v62, 0x3d372713, v58
	v_mul_f32_e32 v62, v62, v58
	v_fma_f32 v62, v62, v58, v58
	v_mul_f32_e32 v62, 0x3f4c422a, v62
	v_add_f32_e32 v62, v62, v62
	v_mul_f32_e32 v62, 0x3fb8aa3b, v62
	v_exp_f32_e32 v62, v62
	v_mul_f32_e32 v58, 0.5, v58
	v_add_f32_e32 v62, 1.0, v62
	v_div_scale_f32 v63, s[14:15], v62, v62, 2.0
	v_rcp_f32_e32 v118, v63
	s_nop 0
	v_fma_f32 v119, -v63, v118, 1.0
	v_fmac_f32_e32 v118, v119, v118
	v_div_scale_f32 v119, vcc, 2.0, v62, 2.0
	v_mul_f32_e32 v120, v119, v118
	v_fma_f32 v121, -v63, v120, v119
	v_fmac_f32_e32 v120, v121, v118
	v_fma_f32 v63, -v63, v120, v119
	v_div_fmas_f32 v63, v63, v118, v120
	v_div_fixup_f32 v62, v63, v62, 2.0
	v_sub_f32_e32 v62, 1.0, v62
	v_add_f32_e32 v62, 1.0, v62
	v_mul_f32_e32 v118, v58, v62
	v_and_b32_e32 v58, 0xffff0000, v65
	v_mul_f32_e32 v62, 0x3d372713, v58
	v_mul_f32_e32 v62, v62, v58
	v_fma_f32 v62, v62, v58, v58
	v_mul_f32_e32 v62, 0x3f4c422a, v62
	v_add_f32_e32 v62, v62, v62
	v_mul_f32_e32 v62, 0x3fb8aa3b, v62
	v_exp_f32_e32 v62, v62
	v_mul_f32_e32 v58, 0.5, v58
	v_add_f32_e32 v62, 1.0, v62
	v_div_scale_f32 v63, s[14:15], v62, v62, 2.0
	v_rcp_f32_e32 v65, v63
	s_nop 0
	v_fma_f32 v119, -v63, v65, 1.0
	v_fmac_f32_e32 v65, v119, v65
	v_div_scale_f32 v119, vcc, 2.0, v62, 2.0
	v_mul_f32_e32 v120, v119, v65
	v_fma_f32 v121, -v63, v120, v119
	v_fmac_f32_e32 v120, v121, v65
	v_fma_f32 v63, -v63, v120, v119
	v_div_fmas_f32 v63, v63, v65, v120
	v_div_fixup_f32 v62, v63, v62, 2.0
	v_sub_f32_e32 v62, 1.0, v62
	v_add_f32_e32 v62, 1.0, v62
	v_mul_f32_e32 v65, v58, v62
	v_and_b32_e32 v58, 0xffff0000, v59
	v_lshlrev_b32_e32 v59, 16, v59
	v_mul_f32_e32 v62, 0x3d372713, v59
	v_mul_f32_e32 v62, v62, v59
	v_mov_b32_e32 v63, v59
	v_fmac_f32_e32 v63, v62, v63
	v_mul_f32_e32 v62, 0x3f4c422a, v63
	v_add_f32_e32 v62, v62, v62
	v_mul_f32_e32 v62, 0x3fb8aa3b, v62
	v_exp_f32_e32 v63, v62
	v_mul_f32_e32 v62, 0x3d372713, v58
	v_mul_f32_e32 v62, v62, v58
	v_mov_b32_e32 v120, v58
	v_fmac_f32_e32 v120, v62, v120
	v_mul_f32_e32 v62, 0x3f4c422a, v120
	v_add_f32_e32 v62, v62, v62
	v_mul_f32_e32 v62, 0x3fb8aa3b, v62
	v_exp_f32_e32 v62, v62
	v_pk_mul_f32 v[58:59], v[58:59], 0.5 op_sel_hi:[1,0]
	v_mul_f32_e32 v119, v101, v101
	v_fmac_f32_e32 v119, v100, v100
	v_pk_add_f32 v[62:63], v[62:63], 1.0 op_sel_hi:[1,0]
	s_nop 0
	v_div_scale_f32 v120, s[14:15], v63, v63, 2.0
	v_rcp_f32_e32 v121, v120
	s_nop 0
	v_fma_f32 v122, -v120, v121, 1.0
	v_fmac_f32_e32 v121, v122, v121
	v_div_scale_f32 v122, vcc, 2.0, v63, 2.0
	v_mul_f32_e32 v123, v122, v121
	v_fma_f32 v124, -v120, v123, v122
	v_fmac_f32_e32 v123, v124, v121
	v_fma_f32 v120, -v120, v123, v122
	v_div_fmas_f32 v120, v120, v121, v123
	v_div_fixup_f32 v63, v120, v63, 2.0
	v_div_scale_f32 v120, s[14:15], v62, v62, 2.0
	v_rcp_f32_e32 v121, v120
	s_nop 0
	v_fma_f32 v122, -v120, v121, 1.0
	v_fmac_f32_e32 v121, v122, v121
	v_div_scale_f32 v122, vcc, 2.0, v62, 2.0
	v_mul_f32_e32 v123, v122, v121
	v_fma_f32 v124, -v120, v123, v122
	v_fmac_f32_e32 v123, v124, v121
	v_fma_f32 v120, -v120, v123, v122
	v_div_fmas_f32 v120, v120, v121, v123
	v_div_fixup_f32 v62, v120, v62, 2.0
	v_pk_add_f32 v[62:63], v[62:63], 1.0 op_sel_hi:[1,0] neg_lo:[1,0] neg_hi:[1,0]
	s_nop 0
	v_pk_add_f32 v[62:63], v[62:63], 1.0 op_sel_hi:[1,0]
	s_nop 0
	v_pk_mul_f32 v[58:59], v[58:59], v[62:63]
	s_nop 0
	v_pk_mul_f32 v[62:63], v[58:59], v[58:59]
	s_nop 0
	v_add_f32_e32 v63, v63, v119
	v_add_f32_e32 v119, v62, v63
	v_lshlrev_b32_e32 v63, 16, v60
	v_and_b32_e32 v62, 0xffff0000, v60
	v_mul_f32_e32 v60, 0x3d372713, v63
	v_mul_f32_e32 v60, v60, v63
	v_mov_b32_e32 v120, v63
	v_fmac_f32_e32 v120, v60, v120
	v_mul_f32_e32 v60, 0x3f4c422a, v120
	v_add_f32_e32 v60, v60, v60
	v_mul_f32_e32 v60, 0x3fb8aa3b, v60
	v_exp_f32_e32 v121, v60
	v_mul_f32_e32 v60, 0x3d372713, v62
	v_mul_f32_e32 v60, v60, v62
	v_mov_b32_e32 v120, v62
	v_fmac_f32_e32 v120, v60, v120
	v_mul_f32_e32 v60, 0x3f4c422a, v120
	v_add_f32_e32 v60, v60, v60
	v_mul_f32_e32 v60, 0x3fb8aa3b, v60
	v_exp_f32_e32 v120, v60
	v_pk_mul_f32 v[62:63], v[62:63], 0.5 op_sel_hi:[1,0]
	v_pk_add_f32 v[120:121], v[120:121], 1.0 op_sel_hi:[1,0]
	s_nop 0
	v_div_scale_f32 v60, s[14:15], v121, v121, 2.0
	v_rcp_f32_e32 v122, v60
	s_nop 0
	v_fma_f32 v123, -v60, v122, 1.0
	v_fmac_f32_e32 v122, v123, v122
	v_div_scale_f32 v123, vcc, 2.0, v121, 2.0
	v_mul_f32_e32 v124, v123, v122
	v_fma_f32 v125, -v60, v124, v123
	v_fmac_f32_e32 v124, v125, v122
	v_fma_f32 v60, -v60, v124, v123
	v_div_fmas_f32 v60, v60, v122, v124
	v_div_fixup_f32 v121, v60, v121, 2.0
	v_div_scale_f32 v60, s[14:15], v120, v120, 2.0
	v_rcp_f32_e32 v122, v60
	s_nop 0
	v_fma_f32 v123, -v60, v122, 1.0
	v_fmac_f32_e32 v122, v123, v122
	v_div_scale_f32 v123, vcc, 2.0, v120, 2.0
	v_mul_f32_e32 v124, v123, v122
	v_fma_f32 v125, -v60, v124, v123
	v_fmac_f32_e32 v124, v125, v122
	v_fma_f32 v60, -v60, v124, v123
	v_div_fmas_f32 v60, v60, v122, v124
	v_div_fixup_f32 v120, v60, v120, 2.0
	v_pk_add_f32 v[120:121], v[120:121], 1.0 op_sel_hi:[1,0] neg_lo:[1,0] neg_hi:[1,0]
	s_nop 0
	v_pk_add_f32 v[120:121], v[120:121], 1.0 op_sel_hi:[1,0]
	s_nop 0
	v_pk_mul_f32 v[62:63], v[62:63], v[120:121]
	s_nop 0
	v_pk_mul_f32 v[120:121], v[62:63], v[62:63]
	s_nop 0
	v_add_f32_e32 v60, v121, v119
	v_add_f32_e32 v119, v120, v60
	v_and_b32_e32 v60, 0xffff0000, v61
	v_lshlrev_b32_e32 v61, 16, v61
	v_mul_f32_e32 v120, 0x3d372713, v61
	v_mul_f32_e32 v120, v120, v61
	v_mov_b32_e32 v121, v61
	v_fmac_f32_e32 v121, v120, v121
	v_mul_f32_e32 v120, 0x3f4c422a, v121
	v_add_f32_e32 v120, v120, v120
	v_mul_f32_e32 v120, 0x3fb8aa3b, v120
	v_exp_f32_e32 v121, v120
	v_mul_f32_e32 v120, 0x3d372713, v60
	v_mul_f32_e32 v120, v120, v60
	v_mov_b32_e32 v122, v60
	v_fmac_f32_e32 v122, v120, v122
	v_mul_f32_e32 v120, 0x3f4c422a, v122
	v_add_f32_e32 v120, v120, v120
	v_mul_f32_e32 v120, 0x3fb8aa3b, v120
	v_exp_f32_e32 v120, v120
	v_pk_mul_f32 v[60:61], v[60:61], 0.5 op_sel_hi:[1,0]
	v_pk_add_f32 v[120:121], v[120:121], 1.0 op_sel_hi:[1,0]
	s_nop 0
	v_div_scale_f32 v122, s[14:15], v121, v121, 2.0
	v_rcp_f32_e32 v123, v122
	s_nop 0
	v_fma_f32 v124, -v122, v123, 1.0
	v_fmac_f32_e32 v123, v124, v123
	v_div_scale_f32 v124, vcc, 2.0, v121, 2.0
	v_mul_f32_e32 v125, v124, v123
	v_fma_f32 v126, -v122, v125, v124
	v_fmac_f32_e32 v125, v126, v123
	v_fma_f32 v122, -v122, v125, v124
	v_div_fmas_f32 v122, v122, v123, v125
	v_div_fixup_f32 v121, v122, v121, 2.0
	v_div_scale_f32 v122, s[14:15], v120, v120, 2.0
	v_rcp_f32_e32 v123, v122
	s_nop 0
	v_fma_f32 v124, -v122, v123, 1.0
	v_fmac_f32_e32 v123, v124, v123
	v_div_scale_f32 v124, vcc, 2.0, v120, 2.0
	v_mul_f32_e32 v125, v124, v123
	v_fma_f32 v126, -v122, v125, v124
	v_fmac_f32_e32 v125, v126, v123
	v_fma_f32 v122, -v122, v125, v124
	v_div_fmas_f32 v122, v122, v123, v125
	v_div_fixup_f32 v120, v122, v120, 2.0
	v_pk_add_f32 v[120:121], v[120:121], 1.0 op_sel_hi:[1,0] neg_lo:[1,0] neg_hi:[1,0]
	s_nop 0
	v_pk_add_f32 v[120:121], v[120:121], 1.0 op_sel_hi:[1,0]
	s_nop 0
	v_pk_mul_f32 v[120:121], v[60:61], v[120:121]
	s_nop 0
	v_pk_mul_f32 v[60:61], v[120:121], v[120:121]
	s_nop 0
	v_add_f32_e32 v61, v61, v119
	v_add_f32_e32 v60, v60, v61
	s_nop 1
	v_mov_b32_dpp v61, v60 quad_perm:[1,0,3,2] row_mask:0xf bank_mask:0xf
	s_waitcnt lgkmcnt(0)
	v_add_f32_e32 v60, v60, v61
	s_nop 1
	v_mov_b32_dpp v61, v60 quad_perm:[2,3,0,1] row_mask:0xf bank_mask:0xf
	s_waitcnt lgkmcnt(0)
	v_add_f32_e32 v60, v60, v61
	s_nop 1
	v_mov_b32_dpp v61, v60 row_half_mirror row_mask:0xf bank_mask:0xf
	s_waitcnt lgkmcnt(0)
	v_add_f32_e32 v60, v60, v61
	s_nop 1
	v_mov_b32_dpp v61, v60 row_mirror row_mask:0xf bank_mask:0xf
	s_waitcnt lgkmcnt(0)
	v_add_f32_e32 v60, v60, v61
	ds_bpermute_b32 v61, v110, v60
	s_waitcnt lgkmcnt(0)
	v_add_f32_e32 v60, v60, v61
	v_fmamk_f32 v60, v60, 0x3b800000, v243
	v_cmp_gt_f32_e32 vcc, s3, v60
	v_mul_f32_e32 v61, 0x4b800000, v60
	s_nop 0
	v_cndmask_b32_e32 v60, v60, v61, vcc
	v_rsq_f32_e32 v60, v60
	s_nop 0
	v_mul_f32_e32 v61, 0x45800000, v60
	v_cndmask_b32_e32 v119, v60, v61, vcc
	v_mul_f32_e32 v60, v100, v119
	v_mul_f32_e32 v61, v101, v119
	v_mul_f32_e32 v58, v58, v119
	v_mul_f32_e32 v60, v70, v60
	v_mul_f32_e32 v61, v71, v61
	v_mul_f32_e32 v59, v59, v119
	v_mul_f32_e32 v58, v73, v58
	v_cvt_pk_bf16_f32 v60, v60, v61
	v_cvt_pk_bf16_f32 v99, v115, v116
	v_mul_f32_e32 v59, v72, v59
	v_cvt_pk_bf16_f32 v61, v59, v58
	v_mul_f32_e32 v58, v63, v119
	v_mul_f32_e32 v58, v66, v58
	v_mul_f32_e32 v59, v62, v119
	v_cvt_pk_bf16_f32 v100, v117, v64
	v_mul_f32_e32 v59, v67, v59
	v_cvt_pk_bf16_f32 v62, v58, v59
	v_mul_f32_e32 v58, v121, v119
	v_mul_f32_e32 v58, v68, v58
	v_mul_f32_e32 v59, v120, v119
	v_cvt_pk_bf16_f32 v101, v118, v65
	v_mul_f32_e32 v59, v69, v59
	v_cvt_pk_bf16_f32 v63, v58, v59
	v_lshlrev_b32_e32 v58, 16, v54
	v_mul_f32_e32 v59, 0x3d372713, v58
	v_mul_f32_e32 v59, v59, v58
	v_fma_f32 v59, v59, v58, v58
	v_mul_f32_e32 v59, 0x3f4c422a, v59
	v_add_f32_e32 v59, v59, v59
	v_mul_f32_e32 v59, 0x3fb8aa3b, v59
	v_exp_f32_e32 v59, v59
	ds_write_b128 v111, v[98:101]
	ds_write_b128 v112, v[60:63]
	v_mul_f32_e32 v58, 0.5, v58
	v_and_b32_e32 v54, 0xffff0000, v54
	v_add_f32_e32 v59, 1.0, v59
	v_div_scale_f32 v60, s[14:15], v59, v59, 2.0
	v_rcp_f32_e32 v61, v60
	s_nop 0
	v_fma_f32 v62, -v60, v61, 1.0
	v_fmac_f32_e32 v61, v62, v61
	v_div_scale_f32 v62, vcc, 2.0, v59, 2.0
	v_mul_f32_e32 v63, v62, v61
	v_fma_f32 v64, -v60, v63, v62
	v_fmac_f32_e32 v63, v64, v61
	v_fma_f32 v60, -v60, v63, v62
	v_div_fmas_f32 v60, v60, v61, v63
	v_div_fixup_f32 v59, v60, v59, 2.0
	v_sub_f32_e32 v59, 1.0, v59
	v_add_f32_e32 v59, 1.0, v59
	v_mul_f32_e32 v58, v58, v59
	v_mul_f32_e32 v59, 0x3d372713, v54
	v_mul_f32_e32 v59, v59, v54
	v_fma_f32 v59, v59, v54, v54
	v_mul_f32_e32 v59, 0x3f4c422a, v59
	v_add_f32_e32 v59, v59, v59
	v_mul_f32_e32 v59, 0x3fb8aa3b, v59
	v_exp_f32_e32 v59, v59
	v_mul_f32_e32 v54, 0.5, v54
	v_add_f32_e32 v59, 1.0, v59
	v_div_scale_f32 v60, s[14:15], v59, v59, 2.0
	v_rcp_f32_e32 v61, v60
	s_nop 0
	v_fma_f32 v62, -v60, v61, 1.0
	v_fmac_f32_e32 v61, v62, v61
	v_div_scale_f32 v62, vcc, 2.0, v59, 2.0
	v_mul_f32_e32 v63, v62, v61
	v_fma_f32 v64, -v60, v63, v62
	v_fmac_f32_e32 v63, v64, v61
	v_fma_f32 v60, -v60, v63, v62
	v_div_fmas_f32 v60, v60, v61, v63
	v_div_fixup_f32 v59, v60, v59, 2.0
	v_sub_f32_e32 v59, 1.0, v59
	v_add_f32_e32 v59, 1.0, v59
	v_mul_f32_e32 v59, v54, v59
	v_lshlrev_b32_e32 v54, 16, v50
	v_mul_f32_e32 v60, 0x3d372713, v54
	v_mul_f32_e32 v60, v60, v54
	v_fma_f32 v60, v60, v54, v54
	v_mul_f32_e32 v60, 0x3f4c422a, v60
	v_add_f32_e32 v60, v60, v60
	v_mul_f32_e32 v60, 0x3fb8aa3b, v60
	v_exp_f32_e32 v60, v60
	v_mul_f32_e32 v54, 0.5, v54
	v_and_b32_e32 v50, 0xffff0000, v50
	v_cvt_pk_bf16_f32 v58, v58, v59
	v_add_f32_e32 v60, 1.0, v60
	v_div_scale_f32 v61, s[14:15], v60, v60, 2.0
	v_rcp_f32_e32 v62, v61
	s_nop 0
	v_fma_f32 v63, -v61, v62, 1.0
	v_fmac_f32_e32 v62, v63, v62
	v_div_scale_f32 v63, vcc, 2.0, v60, 2.0
	v_mul_f32_e32 v64, v63, v62
	v_fma_f32 v65, -v61, v64, v63
	v_fmac_f32_e32 v64, v65, v62
	v_fma_f32 v61, -v61, v64, v63
	v_div_fmas_f32 v61, v61, v62, v64
	v_div_fixup_f32 v60, v61, v60, 2.0
	v_sub_f32_e32 v60, 1.0, v60
	v_add_f32_e32 v60, 1.0, v60
	v_mul_f32_e32 v60, v54, v60
	v_mul_f32_e32 v54, 0x3d372713, v50
	v_mul_f32_e32 v54, v54, v50
	v_fma_f32 v54, v54, v50, v50
	v_mul_f32_e32 v54, 0x3f4c422a, v54
	v_add_f32_e32 v54, v54, v54
	v_mul_f32_e32 v54, 0x3fb8aa3b, v54
	v_exp_f32_e32 v54, v54
	v_mul_f32_e32 v50, 0.5, v50
	v_add_f32_e32 v54, 1.0, v54
	v_div_scale_f32 v61, s[14:15], v54, v54, 2.0
	v_rcp_f32_e32 v62, v61
	s_nop 0
	v_fma_f32 v63, -v61, v62, 1.0
	v_fmac_f32_e32 v62, v63, v62
	v_div_scale_f32 v63, vcc, 2.0, v54, 2.0
	v_mul_f32_e32 v64, v63, v62
	v_fma_f32 v65, -v61, v64, v63
	v_fmac_f32_e32 v64, v65, v62
	v_fma_f32 v61, -v61, v64, v63
	v_div_fmas_f32 v61, v61, v62, v64
	v_div_fixup_f32 v54, v61, v54, 2.0
	v_sub_f32_e32 v54, 1.0, v54
	v_add_f32_e32 v54, 1.0, v54
	v_mul_f32_e32 v61, v50, v54
	v_lshlrev_b32_e32 v50, 16, v55
	v_mul_f32_e32 v54, 0x3d372713, v50
	v_mul_f32_e32 v54, v54, v50
	v_fma_f32 v54, v54, v50, v50
	v_mul_f32_e32 v54, 0x3f4c422a, v54
	v_add_f32_e32 v54, v54, v54
	v_mul_f32_e32 v54, 0x3fb8aa3b, v54
	v_exp_f32_e32 v54, v54
	v_mul_f32_e32 v50, 0.5, v50
	v_add_f32_e32 v54, 1.0, v54
	v_div_scale_f32 v62, s[14:15], v54, v54, 2.0
	v_rcp_f32_e32 v63, v62
	s_nop 0
	v_fma_f32 v64, -v62, v63, 1.0
	v_fmac_f32_e32 v63, v64, v63
	v_div_scale_f32 v64, vcc, 2.0, v54, 2.0
	v_mul_f32_e32 v65, v64, v63
	v_fma_f32 v98, -v62, v65, v64
	v_fmac_f32_e32 v65, v98, v63
	v_fma_f32 v62, -v62, v65, v64
	v_div_fmas_f32 v62, v62, v63, v65
	v_div_fixup_f32 v54, v62, v54, 2.0
	v_sub_f32_e32 v54, 1.0, v54
	v_add_f32_e32 v54, 1.0, v54
	v_mul_f32_e32 v62, v50, v54
	v_and_b32_e32 v50, 0xffff0000, v55
	v_mul_f32_e32 v54, 0x3d372713, v50
	v_mul_f32_e32 v54, v54, v50
	v_fma_f32 v54, v54, v50, v50
	v_mul_f32_e32 v54, 0x3f4c422a, v54
	v_add_f32_e32 v54, v54, v54
	v_mul_f32_e32 v54, 0x3fb8aa3b, v54
	v_exp_f32_e32 v54, v54
	v_mul_f32_e32 v50, 0.5, v50
	v_add_f32_e32 v54, 1.0, v54
	v_div_scale_f32 v55, s[14:15], v54, v54, 2.0
	v_rcp_f32_e32 v63, v55
	s_nop 0
	v_fma_f32 v64, -v55, v63, 1.0
	v_fmac_f32_e32 v63, v64, v63
	v_div_scale_f32 v64, vcc, 2.0, v54, 2.0
	v_mul_f32_e32 v65, v64, v63
	v_fma_f32 v98, -v55, v65, v64
	v_fmac_f32_e32 v65, v98, v63
	v_fma_f32 v55, -v55, v65, v64
	v_div_fmas_f32 v55, v55, v63, v65
	v_div_fixup_f32 v54, v55, v54, 2.0
	v_sub_f32_e32 v54, 1.0, v54
	v_add_f32_e32 v54, 1.0, v54
	v_mul_f32_e32 v63, v50, v54
	v_lshlrev_b32_e32 v50, 16, v56
	v_mul_f32_e32 v54, 0x3d372713, v50
	v_mul_f32_e32 v54, v54, v50
	v_fma_f32 v54, v54, v50, v50
	v_mul_f32_e32 v54, 0x3f4c422a, v54
	v_add_f32_e32 v54, v54, v54
	v_mul_f32_e32 v54, 0x3fb8aa3b, v54
	v_exp_f32_e32 v54, v54
	v_mul_f32_e32 v50, 0.5, v50
	v_add_f32_e32 v54, 1.0, v54
	v_div_scale_f32 v55, s[14:15], v54, v54, 2.0
	v_rcp_f32_e32 v64, v55
	s_nop 0
	v_fma_f32 v65, -v55, v64, 1.0
	v_fmac_f32_e32 v64, v65, v64
	v_div_scale_f32 v65, vcc, 2.0, v54, 2.0
	v_mul_f32_e32 v98, v65, v64
	v_fma_f32 v99, -v55, v98, v65
	v_fmac_f32_e32 v98, v99, v64
	v_fma_f32 v55, -v55, v98, v65
	v_div_fmas_f32 v55, v55, v64, v98
	v_div_fixup_f32 v54, v55, v54, 2.0
	v_sub_f32_e32 v54, 1.0, v54
	v_add_f32_e32 v54, 1.0, v54
	v_mul_f32_e32 v64, v50, v54
	v_and_b32_e32 v50, 0xffff0000, v56
	v_mul_f32_e32 v54, 0x3d372713, v50
	v_mul_f32_e32 v54, v54, v50
	v_fma_f32 v54, v54, v50, v50
	v_mul_f32_e32 v54, 0x3f4c422a, v54
	v_add_f32_e32 v54, v54, v54
	v_mul_f32_e32 v54, 0x3fb8aa3b, v54
	v_exp_f32_e32 v54, v54
	v_mul_f32_e32 v50, 0.5, v50
	v_add_f32_e32 v54, 1.0, v54
	v_div_scale_f32 v55, s[14:15], v54, v54, 2.0
	v_rcp_f32_e32 v56, v55
	s_nop 0
	v_fma_f32 v65, -v55, v56, 1.0
	v_fmac_f32_e32 v56, v65, v56
	v_div_scale_f32 v65, vcc, 2.0, v54, 2.0
	v_mul_f32_e32 v98, v65, v56
	v_fma_f32 v99, -v55, v98, v65
	v_fmac_f32_e32 v98, v99, v56
	v_fma_f32 v55, -v55, v98, v65
	v_div_fmas_f32 v55, v55, v56, v98
	v_div_fixup_f32 v54, v55, v54, 2.0
	v_sub_f32_e32 v54, 1.0, v54
	v_add_f32_e32 v54, 1.0, v54
	v_mul_f32_e32 v56, v50, v54
	v_lshlrev_b32_e32 v50, 16, v57
	v_mul_f32_e32 v54, 0x3d372713, v50
	v_mul_f32_e32 v54, v54, v50
	v_fma_f32 v54, v54, v50, v50
	v_mul_f32_e32 v54, 0x3f4c422a, v54
	v_add_f32_e32 v54, v54, v54
	v_mul_f32_e32 v54, 0x3fb8aa3b, v54
	v_exp_f32_e32 v54, v54
	v_mul_f32_e32 v50, 0.5, v50
	v_add_f32_e32 v54, 1.0, v54
	v_div_scale_f32 v55, s[14:15], v54, v54, 2.0
	v_rcp_f32_e32 v65, v55
	s_nop 0
	v_fma_f32 v98, -v55, v65, 1.0
	v_fmac_f32_e32 v65, v98, v65
	v_div_scale_f32 v98, vcc, 2.0, v54, 2.0
	v_mul_f32_e32 v99, v98, v65
	v_fma_f32 v100, -v55, v99, v98
	v_fmac_f32_e32 v99, v100, v65
	v_fma_f32 v55, -v55, v99, v98
	v_div_fmas_f32 v55, v55, v65, v99
	v_div_fixup_f32 v54, v55, v54, 2.0
	v_sub_f32_e32 v54, 1.0, v54
	v_add_f32_e32 v54, 1.0, v54
	v_mul_f32_e32 v65, v50, v54
	v_and_b32_e32 v50, 0xffff0000, v57
	v_mul_f32_e32 v54, 0x3d372713, v50
	v_mul_f32_e32 v54, v54, v50
	v_fma_f32 v54, v54, v50, v50
	v_mul_f32_e32 v54, 0x3f4c422a, v54
	v_add_f32_e32 v54, v54, v54
	v_mul_f32_e32 v54, 0x3fb8aa3b, v54
	v_exp_f32_e32 v54, v54
	v_mul_f32_e32 v50, 0.5, v50
	v_add_f32_e32 v54, 1.0, v54
	v_div_scale_f32 v55, s[14:15], v54, v54, 2.0
	v_rcp_f32_e32 v57, v55
	s_nop 0
	v_fma_f32 v98, -v55, v57, 1.0
	v_fmac_f32_e32 v57, v98, v57
	v_div_scale_f32 v98, vcc, 2.0, v54, 2.0
	v_mul_f32_e32 v99, v98, v57
	v_fma_f32 v100, -v55, v99, v98
	v_fmac_f32_e32 v99, v100, v57
	v_fma_f32 v55, -v55, v99, v98
	v_div_fmas_f32 v55, v55, v57, v99
	v_div_fixup_f32 v54, v55, v54, 2.0
	v_sub_f32_e32 v54, 1.0, v54
	v_add_f32_e32 v54, 1.0, v54
	v_mul_f32_e32 v57, v50, v54
	v_and_b32_e32 v50, 0xffff0000, v51
	v_lshlrev_b32_e32 v51, 16, v51
	v_mul_f32_e32 v54, 0x3d372713, v51
	v_mul_f32_e32 v54, v54, v51
	v_mov_b32_e32 v55, v51
	v_fmac_f32_e32 v55, v54, v55
	v_mul_f32_e32 v54, 0x3f4c422a, v55
	v_add_f32_e32 v54, v54, v54
	v_mul_f32_e32 v54, 0x3fb8aa3b, v54
	v_exp_f32_e32 v55, v54
	v_mul_f32_e32 v54, 0x3d372713, v50
	v_mul_f32_e32 v54, v54, v50
	v_mov_b32_e32 v99, v50
	v_fmac_f32_e32 v99, v54, v99
	v_mul_f32_e32 v54, 0x3f4c422a, v99
	v_add_f32_e32 v54, v54, v54
	v_mul_f32_e32 v54, 0x3fb8aa3b, v54
	v_exp_f32_e32 v54, v54
	v_pk_mul_f32 v[50:51], v[50:51], 0.5 op_sel_hi:[1,0]
	v_mul_f32_e32 v98, v61, v61
	v_fmac_f32_e32 v98, v60, v60
	v_pk_add_f32 v[54:55], v[54:55], 1.0 op_sel_hi:[1,0]
	s_nop 0
	v_div_scale_f32 v99, s[14:15], v55, v55, 2.0
	v_rcp_f32_e32 v100, v99
	s_nop 0
	v_fma_f32 v101, -v99, v100, 1.0
	v_fmac_f32_e32 v100, v101, v100
	v_div_scale_f32 v101, vcc, 2.0, v55, 2.0
	v_mul_f32_e32 v115, v101, v100
	v_fma_f32 v116, -v99, v115, v101
	v_fmac_f32_e32 v115, v116, v100
	v_fma_f32 v99, -v99, v115, v101
	v_div_fmas_f32 v99, v99, v100, v115
	v_div_fixup_f32 v55, v99, v55, 2.0
	v_div_scale_f32 v99, s[14:15], v54, v54, 2.0
	v_rcp_f32_e32 v100, v99
	s_nop 0
	v_fma_f32 v101, -v99, v100, 1.0
	v_fmac_f32_e32 v100, v101, v100
	v_div_scale_f32 v101, vcc, 2.0, v54, 2.0
	v_mul_f32_e32 v115, v101, v100
	v_fma_f32 v116, -v99, v115, v101
	v_fmac_f32_e32 v115, v116, v100
	v_fma_f32 v99, -v99, v115, v101
	v_div_fmas_f32 v99, v99, v100, v115
	v_div_fixup_f32 v54, v99, v54, 2.0
	v_pk_add_f32 v[54:55], v[54:55], 1.0 op_sel_hi:[1,0] neg_lo:[1,0] neg_hi:[1,0]
	s_nop 0
	v_pk_add_f32 v[54:55], v[54:55], 1.0 op_sel_hi:[1,0]
	s_nop 0
	v_pk_mul_f32 v[50:51], v[50:51], v[54:55]
	s_nop 0
	v_pk_mul_f32 v[54:55], v[50:51], v[50:51]
	s_nop 0
	v_add_f32_e32 v55, v55, v98
	v_add_f32_e32 v100, v54, v55
	v_lshlrev_b32_e32 v55, 16, v52
	v_and_b32_e32 v54, 0xffff0000, v52
	v_mul_f32_e32 v52, 0x3d372713, v55
	v_mul_f32_e32 v52, v52, v55
	v_mov_b32_e32 v98, v55
	v_fmac_f32_e32 v98, v52, v98
	v_mul_f32_e32 v52, 0x3f4c422a, v98
	v_add_f32_e32 v52, v52, v52
	v_mul_f32_e32 v52, 0x3fb8aa3b, v52
	v_exp_f32_e32 v99, v52
	v_mul_f32_e32 v52, 0x3d372713, v54
	v_mul_f32_e32 v52, v52, v54
	v_mov_b32_e32 v98, v54
	v_fmac_f32_e32 v98, v52, v98
	v_mul_f32_e32 v52, 0x3f4c422a, v98
	v_add_f32_e32 v52, v52, v52
	v_mul_f32_e32 v52, 0x3fb8aa3b, v52
	v_exp_f32_e32 v98, v52
	v_pk_mul_f32 v[54:55], v[54:55], 0.5 op_sel_hi:[1,0]
	v_pk_add_f32 v[98:99], v[98:99], 1.0 op_sel_hi:[1,0]
	s_nop 0
	v_div_scale_f32 v52, s[14:15], v99, v99, 2.0
	v_rcp_f32_e32 v101, v52
	s_nop 0
	v_fma_f32 v115, -v52, v101, 1.0
	v_fmac_f32_e32 v101, v115, v101
	v_div_scale_f32 v115, vcc, 2.0, v99, 2.0
	v_mul_f32_e32 v116, v115, v101
	v_fma_f32 v117, -v52, v116, v115
	v_fmac_f32_e32 v116, v117, v101
	v_fma_f32 v52, -v52, v116, v115
	v_div_fmas_f32 v52, v52, v101, v116
	v_div_fixup_f32 v99, v52, v99, 2.0
	v_div_scale_f32 v52, s[14:15], v98, v98, 2.0
	v_rcp_f32_e32 v101, v52
	s_nop 0
	v_fma_f32 v115, -v52, v101, 1.0
	v_fmac_f32_e32 v101, v115, v101
	v_div_scale_f32 v115, vcc, 2.0, v98, 2.0
	v_mul_f32_e32 v116, v115, v101
	v_fma_f32 v117, -v52, v116, v115
	v_fmac_f32_e32 v116, v117, v101
	v_fma_f32 v52, -v52, v116, v115
	v_div_fmas_f32 v52, v52, v101, v116
	v_div_fixup_f32 v98, v52, v98, 2.0
	v_pk_add_f32 v[98:99], v[98:99], 1.0 op_sel_hi:[1,0] neg_lo:[1,0] neg_hi:[1,0]
	s_nop 0
	v_pk_add_f32 v[98:99], v[98:99], 1.0 op_sel_hi:[1,0]
	s_nop 0
	v_pk_mul_f32 v[54:55], v[54:55], v[98:99]
	s_nop 0
	v_pk_mul_f32 v[98:99], v[54:55], v[54:55]
	s_nop 0
	v_add_f32_e32 v52, v99, v100
	v_add_f32_e32 v100, v98, v52
	v_and_b32_e32 v52, 0xffff0000, v53
	v_lshlrev_b32_e32 v53, 16, v53
	v_mul_f32_e32 v98, 0x3d372713, v53
	v_mul_f32_e32 v98, v98, v53
	v_mov_b32_e32 v99, v53
	v_fmac_f32_e32 v99, v98, v99
	v_mul_f32_e32 v98, 0x3f4c422a, v99
	v_add_f32_e32 v98, v98, v98
	v_mul_f32_e32 v98, 0x3fb8aa3b, v98
	v_exp_f32_e32 v99, v98
	v_mul_f32_e32 v98, 0x3d372713, v52
	v_mul_f32_e32 v98, v98, v52
	v_mov_b32_e32 v101, v52
	v_fmac_f32_e32 v101, v98, v101
	v_mul_f32_e32 v98, 0x3f4c422a, v101
	v_add_f32_e32 v98, v98, v98
	v_mul_f32_e32 v98, 0x3fb8aa3b, v98
	v_exp_f32_e32 v98, v98
	v_pk_mul_f32 v[52:53], v[52:53], 0.5 op_sel_hi:[1,0]
	v_pk_add_f32 v[98:99], v[98:99], 1.0 op_sel_hi:[1,0]
	s_nop 0
	v_div_scale_f32 v101, s[14:15], v99, v99, 2.0
	v_rcp_f32_e32 v115, v101
	s_nop 0
	v_fma_f32 v116, -v101, v115, 1.0
	v_fmac_f32_e32 v115, v116, v115
	v_div_scale_f32 v116, vcc, 2.0, v99, 2.0
	v_mul_f32_e32 v117, v116, v115
	v_fma_f32 v118, -v101, v117, v116
	v_fmac_f32_e32 v117, v118, v115
	v_fma_f32 v101, -v101, v117, v116
	v_div_fmas_f32 v101, v101, v115, v117
	v_div_fixup_f32 v99, v101, v99, 2.0
	v_div_scale_f32 v101, s[14:15], v98, v98, 2.0
	v_rcp_f32_e32 v115, v101
	s_nop 0
	v_fma_f32 v116, -v101, v115, 1.0
	v_fmac_f32_e32 v115, v116, v115
	v_div_scale_f32 v116, vcc, 2.0, v98, 2.0
	v_mul_f32_e32 v117, v116, v115
	v_fma_f32 v118, -v101, v117, v116
	v_fmac_f32_e32 v117, v118, v115
	v_fma_f32 v101, -v101, v117, v116
	v_div_fmas_f32 v101, v101, v115, v117
	v_div_fixup_f32 v98, v101, v98, 2.0
	v_pk_add_f32 v[98:99], v[98:99], 1.0 op_sel_hi:[1,0] neg_lo:[1,0] neg_hi:[1,0]
	s_nop 0
	v_pk_add_f32 v[98:99], v[98:99], 1.0 op_sel_hi:[1,0]
	s_nop 0
	v_pk_mul_f32 v[98:99], v[52:53], v[98:99]
	s_nop 0
	v_pk_mul_f32 v[52:53], v[98:99], v[98:99]
	s_nop 0
	v_add_f32_e32 v53, v53, v100
	v_add_f32_e32 v52, v52, v53
	s_nop 1
	v_mov_b32_dpp v53, v52 quad_perm:[1,0,3,2] row_mask:0xf bank_mask:0xf
	s_waitcnt lgkmcnt(0)
	v_add_f32_e32 v52, v52, v53
	s_nop 1
	v_mov_b32_dpp v53, v52 quad_perm:[2,3,0,1] row_mask:0xf bank_mask:0xf
	s_waitcnt lgkmcnt(0)
	v_add_f32_e32 v52, v52, v53
	s_nop 1
	v_mov_b32_dpp v53, v52 row_half_mirror row_mask:0xf bank_mask:0xf
	s_waitcnt lgkmcnt(0)
	v_add_f32_e32 v52, v52, v53
	s_nop 1
	v_mov_b32_dpp v53, v52 row_mirror row_mask:0xf bank_mask:0xf
	s_waitcnt lgkmcnt(0)
	v_add_f32_e32 v52, v52, v53
	ds_bpermute_b32 v53, v110, v52
	s_waitcnt lgkmcnt(0)
	v_add_f32_e32 v52, v52, v53
	v_fmamk_f32 v52, v52, 0x3b800000, v243
	v_cmp_gt_f32_e32 vcc, s3, v52
	v_mul_f32_e32 v53, 0x4b800000, v52
	s_nop 0
	v_cndmask_b32_e32 v52, v52, v53, vcc
	v_rsq_f32_e32 v52, v52
	s_nop 0
	v_mul_f32_e32 v53, 0x45800000, v52
	v_cndmask_b32_e32 v100, v52, v53, vcc
	v_mul_f32_e32 v52, v60, v100
	v_mul_f32_e32 v53, v61, v100
	v_mul_f32_e32 v50, v50, v100
	v_mul_f32_e32 v52, v70, v52
	v_mul_f32_e32 v53, v71, v53
	v_mul_f32_e32 v51, v51, v100
	v_mul_f32_e32 v50, v73, v50
	v_cvt_pk_bf16_f32 v52, v52, v53
	v_cvt_pk_bf16_f32 v59, v62, v63
	v_mul_f32_e32 v51, v72, v51
	v_cvt_pk_bf16_f32 v53, v51, v50
	v_mul_f32_e32 v50, v55, v100
	v_mul_f32_e32 v50, v66, v50
	v_mul_f32_e32 v51, v54, v100
	v_cvt_pk_bf16_f32 v60, v64, v56
	v_mul_f32_e32 v51, v67, v51
	v_cvt_pk_bf16_f32 v54, v50, v51
	v_mul_f32_e32 v50, v99, v100
	v_mul_f32_e32 v50, v68, v50
	v_mul_f32_e32 v51, v98, v100
	v_cvt_pk_bf16_f32 v61, v65, v57
	v_mul_f32_e32 v51, v69, v51
	v_cvt_pk_bf16_f32 v55, v50, v51
	v_lshlrev_b32_e32 v50, 16, v46
	v_mul_f32_e32 v51, 0x3d372713, v50
	v_mul_f32_e32 v51, v51, v50
	v_fma_f32 v51, v51, v50, v50
	v_mul_f32_e32 v51, 0x3f4c422a, v51
	v_add_f32_e32 v51, v51, v51
	v_mul_f32_e32 v51, 0x3fb8aa3b, v51
	v_exp_f32_e32 v51, v51
	ds_write_b128 v111, v[58:61] offset:8704
	ds_write_b128 v112, v[52:55] offset:8704
	v_mul_f32_e32 v50, 0.5, v50
	v_and_b32_e32 v46, 0xffff0000, v46
	v_add_f32_e32 v51, 1.0, v51
	v_div_scale_f32 v52, s[14:15], v51, v51, 2.0
	v_rcp_f32_e32 v53, v52
	v_mov_b64_e32 v[98:99], v[80:81]
	v_mov_b64_e32 v[100:101], v[78:79]
	v_fma_f32 v54, -v52, v53, 1.0
	v_fmac_f32_e32 v53, v54, v53
	v_div_scale_f32 v54, vcc, 2.0, v51, 2.0
	v_mul_f32_e32 v55, v54, v53
	v_fma_f32 v56, -v52, v55, v54
	v_fmac_f32_e32 v55, v56, v53
	v_fma_f32 v52, -v52, v55, v54
	v_div_fmas_f32 v52, v52, v53, v55
	v_div_fixup_f32 v51, v52, v51, 2.0
	v_sub_f32_e32 v51, 1.0, v51
	v_add_f32_e32 v51, 1.0, v51
	v_mul_f32_e32 v50, v50, v51
	v_mul_f32_e32 v51, 0x3d372713, v46
	v_mul_f32_e32 v51, v51, v46
	v_fma_f32 v51, v51, v46, v46
	v_mul_f32_e32 v51, 0x3f4c422a, v51
	v_add_f32_e32 v51, v51, v51
	v_mul_f32_e32 v51, 0x3fb8aa3b, v51
	v_exp_f32_e32 v51, v51
	v_mul_f32_e32 v46, 0.5, v46
	v_add_f32_e32 v51, 1.0, v51
	v_div_scale_f32 v52, s[14:15], v51, v51, 2.0
	v_rcp_f32_e32 v53, v52
	s_nop 0
	v_fma_f32 v54, -v52, v53, 1.0
	v_fmac_f32_e32 v53, v54, v53
	v_div_scale_f32 v54, vcc, 2.0, v51, 2.0
	v_mul_f32_e32 v55, v54, v53
	v_fma_f32 v56, -v52, v55, v54
	v_fmac_f32_e32 v55, v56, v53
	v_fma_f32 v52, -v52, v55, v54
	v_div_fmas_f32 v52, v52, v53, v55
	v_div_fixup_f32 v51, v52, v51, 2.0
	v_sub_f32_e32 v51, 1.0, v51
	v_add_f32_e32 v51, 1.0, v51
	v_mul_f32_e32 v51, v46, v51
	v_lshlrev_b32_e32 v46, 16, v42
	v_mul_f32_e32 v52, 0x3d372713, v46
	v_mul_f32_e32 v52, v52, v46
	v_fma_f32 v52, v52, v46, v46
	v_mul_f32_e32 v52, 0x3f4c422a, v52
	v_add_f32_e32 v52, v52, v52
	v_mul_f32_e32 v52, 0x3fb8aa3b, v52
	v_exp_f32_e32 v52, v52
	v_mul_f32_e32 v46, 0.5, v46
	v_and_b32_e32 v42, 0xffff0000, v42
	v_cvt_pk_bf16_f32 v50, v50, v51
	v_add_f32_e32 v52, 1.0, v52
	v_div_scale_f32 v53, s[14:15], v52, v52, 2.0
	v_rcp_f32_e32 v54, v53
	s_nop 0
	v_fma_f32 v55, -v53, v54, 1.0
	v_fmac_f32_e32 v54, v55, v54
	v_div_scale_f32 v55, vcc, 2.0, v52, 2.0
	v_mul_f32_e32 v56, v55, v54
	v_fma_f32 v57, -v53, v56, v55
	v_fmac_f32_e32 v56, v57, v54
	v_fma_f32 v53, -v53, v56, v55
	v_div_fmas_f32 v53, v53, v54, v56
	v_div_fixup_f32 v52, v53, v52, 2.0
	v_sub_f32_e32 v52, 1.0, v52
	v_add_f32_e32 v52, 1.0, v52
	v_mul_f32_e32 v52, v46, v52
	v_mul_f32_e32 v46, 0x3d372713, v42
	v_mul_f32_e32 v46, v46, v42
	v_fma_f32 v46, v46, v42, v42
	v_mul_f32_e32 v46, 0x3f4c422a, v46
	v_add_f32_e32 v46, v46, v46
	v_mul_f32_e32 v46, 0x3fb8aa3b, v46
	v_exp_f32_e32 v46, v46
	v_mul_f32_e32 v42, 0.5, v42
	v_add_f32_e32 v46, 1.0, v46
	v_div_scale_f32 v53, s[14:15], v46, v46, 2.0
	v_rcp_f32_e32 v54, v53
	s_nop 0
	v_fma_f32 v55, -v53, v54, 1.0
	v_fmac_f32_e32 v54, v55, v54
	v_div_scale_f32 v55, vcc, 2.0, v46, 2.0
	v_mul_f32_e32 v56, v55, v54
	v_fma_f32 v57, -v53, v56, v55
	v_fmac_f32_e32 v56, v57, v54
	v_fma_f32 v53, -v53, v56, v55
	v_div_fmas_f32 v53, v53, v54, v56
	v_div_fixup_f32 v46, v53, v46, 2.0
	v_sub_f32_e32 v46, 1.0, v46
	v_add_f32_e32 v46, 1.0, v46
	v_mul_f32_e32 v53, v42, v46
	v_lshlrev_b32_e32 v42, 16, v47
	v_mul_f32_e32 v46, 0x3d372713, v42
	v_mul_f32_e32 v46, v46, v42
	v_fma_f32 v46, v46, v42, v42
	v_mul_f32_e32 v46, 0x3f4c422a, v46
	v_add_f32_e32 v46, v46, v46
	v_mul_f32_e32 v46, 0x3fb8aa3b, v46
	v_exp_f32_e32 v46, v46
	v_mul_f32_e32 v42, 0.5, v42
	v_add_f32_e32 v46, 1.0, v46
	v_div_scale_f32 v54, s[14:15], v46, v46, 2.0
	v_rcp_f32_e32 v55, v54
	s_nop 0
	v_fma_f32 v56, -v54, v55, 1.0
	v_fmac_f32_e32 v55, v56, v55
	v_div_scale_f32 v56, vcc, 2.0, v46, 2.0
	v_mul_f32_e32 v57, v56, v55
	v_fma_f32 v58, -v54, v57, v56
	v_fmac_f32_e32 v57, v58, v55
	v_fma_f32 v54, -v54, v57, v56
	v_div_fmas_f32 v54, v54, v55, v57
	v_div_fixup_f32 v46, v54, v46, 2.0
	v_sub_f32_e32 v46, 1.0, v46
	v_add_f32_e32 v46, 1.0, v46
	v_mul_f32_e32 v54, v42, v46
	v_and_b32_e32 v42, 0xffff0000, v47
	v_mul_f32_e32 v46, 0x3d372713, v42
	v_mul_f32_e32 v46, v46, v42
	v_fma_f32 v46, v46, v42, v42
	v_mul_f32_e32 v46, 0x3f4c422a, v46
	v_add_f32_e32 v46, v46, v46
	v_mul_f32_e32 v46, 0x3fb8aa3b, v46
	v_exp_f32_e32 v46, v46
	v_mul_f32_e32 v42, 0.5, v42
	v_add_f32_e32 v46, 1.0, v46
	v_div_scale_f32 v47, s[14:15], v46, v46, 2.0
	v_rcp_f32_e32 v55, v47
	s_nop 0
	v_fma_f32 v56, -v47, v55, 1.0
	v_fmac_f32_e32 v55, v56, v55
	v_div_scale_f32 v56, vcc, 2.0, v46, 2.0
	v_mul_f32_e32 v57, v56, v55
	v_fma_f32 v58, -v47, v57, v56
	v_fmac_f32_e32 v57, v58, v55
	v_fma_f32 v47, -v47, v57, v56
	v_div_fmas_f32 v47, v47, v55, v57
	v_div_fixup_f32 v46, v47, v46, 2.0
	v_sub_f32_e32 v46, 1.0, v46
	v_add_f32_e32 v46, 1.0, v46
	v_mul_f32_e32 v55, v42, v46
	v_lshlrev_b32_e32 v42, 16, v48
	v_mul_f32_e32 v46, 0x3d372713, v42
	v_mul_f32_e32 v46, v46, v42
	v_fma_f32 v46, v46, v42, v42
	v_mul_f32_e32 v46, 0x3f4c422a, v46
	v_add_f32_e32 v46, v46, v46
	v_mul_f32_e32 v46, 0x3fb8aa3b, v46
	v_exp_f32_e32 v46, v46
	v_mul_f32_e32 v42, 0.5, v42
	v_add_f32_e32 v46, 1.0, v46
	v_div_scale_f32 v47, s[14:15], v46, v46, 2.0
	v_rcp_f32_e32 v56, v47
	s_nop 0
	v_fma_f32 v57, -v47, v56, 1.0
	v_fmac_f32_e32 v56, v57, v56
	v_div_scale_f32 v57, vcc, 2.0, v46, 2.0
	v_mul_f32_e32 v58, v57, v56
	v_fma_f32 v59, -v47, v58, v57
	v_fmac_f32_e32 v58, v59, v56
	v_fma_f32 v47, -v47, v58, v57
	v_div_fmas_f32 v47, v47, v56, v58
	v_div_fixup_f32 v46, v47, v46, 2.0
	v_sub_f32_e32 v46, 1.0, v46
	v_add_f32_e32 v46, 1.0, v46
	v_mul_f32_e32 v56, v42, v46
	v_and_b32_e32 v42, 0xffff0000, v48
	v_mul_f32_e32 v46, 0x3d372713, v42
	v_mul_f32_e32 v46, v46, v42
	v_fma_f32 v46, v46, v42, v42
	v_mul_f32_e32 v46, 0x3f4c422a, v46
	v_add_f32_e32 v46, v46, v46
	v_mul_f32_e32 v46, 0x3fb8aa3b, v46
	v_exp_f32_e32 v46, v46
	v_mul_f32_e32 v42, 0.5, v42
	v_add_f32_e32 v46, 1.0, v46
	v_div_scale_f32 v47, s[14:15], v46, v46, 2.0
	v_rcp_f32_e32 v48, v47
	s_nop 0
	v_fma_f32 v57, -v47, v48, 1.0
	v_fmac_f32_e32 v48, v57, v48
	v_div_scale_f32 v57, vcc, 2.0, v46, 2.0
	v_mul_f32_e32 v58, v57, v48
	v_fma_f32 v59, -v47, v58, v57
	v_fmac_f32_e32 v58, v59, v48
	v_fma_f32 v47, -v47, v58, v57
	v_div_fmas_f32 v47, v47, v48, v58
	v_div_fixup_f32 v46, v47, v46, 2.0
	v_sub_f32_e32 v46, 1.0, v46
	v_add_f32_e32 v46, 1.0, v46
	v_mul_f32_e32 v48, v42, v46
	v_lshlrev_b32_e32 v42, 16, v49
	v_mul_f32_e32 v46, 0x3d372713, v42
	v_mul_f32_e32 v46, v46, v42
	v_fma_f32 v46, v46, v42, v42
	v_mul_f32_e32 v46, 0x3f4c422a, v46
	v_add_f32_e32 v46, v46, v46
	v_mul_f32_e32 v46, 0x3fb8aa3b, v46
	v_exp_f32_e32 v46, v46
	v_mul_f32_e32 v42, 0.5, v42
	v_add_f32_e32 v46, 1.0, v46
	v_div_scale_f32 v47, s[14:15], v46, v46, 2.0
	v_rcp_f32_e32 v57, v47
	s_nop 0
	v_fma_f32 v58, -v47, v57, 1.0
	v_fmac_f32_e32 v57, v58, v57
	v_div_scale_f32 v58, vcc, 2.0, v46, 2.0
	v_mul_f32_e32 v59, v58, v57
	v_fma_f32 v60, -v47, v59, v58
	v_fmac_f32_e32 v59, v60, v57
	v_fma_f32 v47, -v47, v59, v58
	v_div_fmas_f32 v47, v47, v57, v59
	v_div_fixup_f32 v46, v47, v46, 2.0
	v_sub_f32_e32 v46, 1.0, v46
	v_add_f32_e32 v46, 1.0, v46
	v_mul_f32_e32 v57, v42, v46
	v_and_b32_e32 v42, 0xffff0000, v49
	v_mul_f32_e32 v46, 0x3d372713, v42
	v_mul_f32_e32 v46, v46, v42
	v_fma_f32 v46, v46, v42, v42
	v_mul_f32_e32 v46, 0x3f4c422a, v46
	v_add_f32_e32 v46, v46, v46
	v_mul_f32_e32 v46, 0x3fb8aa3b, v46
	v_exp_f32_e32 v46, v46
	v_mul_f32_e32 v42, 0.5, v42
	v_add_f32_e32 v46, 1.0, v46
	v_div_scale_f32 v47, s[14:15], v46, v46, 2.0
	v_rcp_f32_e32 v49, v47
	s_nop 0
	v_fma_f32 v58, -v47, v49, 1.0
	v_fmac_f32_e32 v49, v58, v49
	v_div_scale_f32 v58, vcc, 2.0, v46, 2.0
	v_mul_f32_e32 v59, v58, v49
	v_fma_f32 v60, -v47, v59, v58
	v_fmac_f32_e32 v59, v60, v49
	v_fma_f32 v47, -v47, v59, v58
	v_div_fmas_f32 v47, v47, v49, v59
	v_div_fixup_f32 v46, v47, v46, 2.0
	v_sub_f32_e32 v46, 1.0, v46
	v_add_f32_e32 v46, 1.0, v46
	v_mul_f32_e32 v49, v42, v46
	v_and_b32_e32 v42, 0xffff0000, v43
	v_lshlrev_b32_e32 v43, 16, v43
	v_mul_f32_e32 v46, 0x3d372713, v43
	v_mul_f32_e32 v46, v46, v43
	v_mov_b32_e32 v47, v43
	v_fmac_f32_e32 v47, v46, v47
	v_mul_f32_e32 v46, 0x3f4c422a, v47
	v_add_f32_e32 v46, v46, v46
	v_mul_f32_e32 v46, 0x3fb8aa3b, v46
	v_exp_f32_e32 v47, v46
	v_mul_f32_e32 v46, 0x3d372713, v42
	v_mul_f32_e32 v46, v46, v42
	v_mov_b32_e32 v59, v42
	v_fmac_f32_e32 v59, v46, v59
	v_mul_f32_e32 v46, 0x3f4c422a, v59
	v_add_f32_e32 v46, v46, v46
	v_mul_f32_e32 v46, 0x3fb8aa3b, v46
	v_exp_f32_e32 v46, v46
	v_pk_mul_f32 v[42:43], v[42:43], 0.5 op_sel_hi:[1,0]
	v_mul_f32_e32 v58, v53, v53
	v_fmac_f32_e32 v58, v52, v52
	v_pk_add_f32 v[46:47], v[46:47], 1.0 op_sel_hi:[1,0]
	s_nop 0
	v_div_scale_f32 v59, s[14:15], v47, v47, 2.0
	v_rcp_f32_e32 v60, v59
	s_nop 0
	v_fma_f32 v61, -v59, v60, 1.0
	v_fmac_f32_e32 v60, v61, v60
	v_div_scale_f32 v61, vcc, 2.0, v47, 2.0
	v_mul_f32_e32 v62, v61, v60
	v_fma_f32 v63, -v59, v62, v61
	v_fmac_f32_e32 v62, v63, v60
	v_fma_f32 v59, -v59, v62, v61
	v_div_fmas_f32 v59, v59, v60, v62
	v_div_fixup_f32 v47, v59, v47, 2.0
	v_div_scale_f32 v59, s[14:15], v46, v46, 2.0
	v_rcp_f32_e32 v60, v59
	s_nop 0
	v_fma_f32 v61, -v59, v60, 1.0
	v_fmac_f32_e32 v60, v61, v60
	v_div_scale_f32 v61, vcc, 2.0, v46, 2.0
	v_mul_f32_e32 v62, v61, v60
	v_fma_f32 v63, -v59, v62, v61
	v_fmac_f32_e32 v62, v63, v60
	v_fma_f32 v59, -v59, v62, v61
	v_div_fmas_f32 v59, v59, v60, v62
	v_div_fixup_f32 v46, v59, v46, 2.0
	v_pk_add_f32 v[46:47], v[46:47], 1.0 op_sel_hi:[1,0] neg_lo:[1,0] neg_hi:[1,0]
	s_nop 0
	v_pk_add_f32 v[46:47], v[46:47], 1.0 op_sel_hi:[1,0]
	s_nop 0
	v_pk_mul_f32 v[42:43], v[42:43], v[46:47]
	s_nop 0
	v_pk_mul_f32 v[46:47], v[42:43], v[42:43]
	s_nop 0
	v_add_f32_e32 v47, v47, v58
	v_add_f32_e32 v60, v46, v47
	v_lshlrev_b32_e32 v47, 16, v44
	v_and_b32_e32 v46, 0xffff0000, v44
	v_mul_f32_e32 v44, 0x3d372713, v47
	v_mul_f32_e32 v44, v44, v47
	v_mov_b32_e32 v58, v47
	v_fmac_f32_e32 v58, v44, v58
	v_mul_f32_e32 v44, 0x3f4c422a, v58
	v_add_f32_e32 v44, v44, v44
	v_mul_f32_e32 v44, 0x3fb8aa3b, v44
	v_exp_f32_e32 v59, v44
	v_mul_f32_e32 v44, 0x3d372713, v46
	v_mul_f32_e32 v44, v44, v46
	v_mov_b32_e32 v58, v46
	v_fmac_f32_e32 v58, v44, v58
	v_mul_f32_e32 v44, 0x3f4c422a, v58
	v_add_f32_e32 v44, v44, v44
	v_mul_f32_e32 v44, 0x3fb8aa3b, v44
	v_exp_f32_e32 v58, v44
	v_pk_mul_f32 v[46:47], v[46:47], 0.5 op_sel_hi:[1,0]
	v_pk_add_f32 v[58:59], v[58:59], 1.0 op_sel_hi:[1,0]
	s_nop 0
	v_div_scale_f32 v44, s[14:15], v59, v59, 2.0
	v_rcp_f32_e32 v61, v44
	s_nop 0
	v_fma_f32 v62, -v44, v61, 1.0
	v_fmac_f32_e32 v61, v62, v61
	v_div_scale_f32 v62, vcc, 2.0, v59, 2.0
	v_mul_f32_e32 v63, v62, v61
	v_fma_f32 v64, -v44, v63, v62
	v_fmac_f32_e32 v63, v64, v61
	v_fma_f32 v44, -v44, v63, v62
	v_div_fmas_f32 v44, v44, v61, v63
	v_div_fixup_f32 v59, v44, v59, 2.0
	v_div_scale_f32 v44, s[14:15], v58, v58, 2.0
	v_rcp_f32_e32 v61, v44
	s_nop 0
	v_fma_f32 v62, -v44, v61, 1.0
	v_fmac_f32_e32 v61, v62, v61
	v_div_scale_f32 v62, vcc, 2.0, v58, 2.0
	v_mul_f32_e32 v63, v62, v61
	v_fma_f32 v64, -v44, v63, v62
	v_fmac_f32_e32 v63, v64, v61
	v_fma_f32 v44, -v44, v63, v62
	v_div_fmas_f32 v44, v44, v61, v63
	v_div_fixup_f32 v58, v44, v58, 2.0
	v_pk_add_f32 v[58:59], v[58:59], 1.0 op_sel_hi:[1,0] neg_lo:[1,0] neg_hi:[1,0]
	s_nop 0
	v_pk_add_f32 v[58:59], v[58:59], 1.0 op_sel_hi:[1,0]
	s_nop 0
	v_pk_mul_f32 v[46:47], v[46:47], v[58:59]
	s_nop 0
	v_pk_mul_f32 v[58:59], v[46:47], v[46:47]
	s_nop 0
	v_add_f32_e32 v44, v59, v60
	v_add_f32_e32 v60, v58, v44
	v_and_b32_e32 v44, 0xffff0000, v45
	v_lshlrev_b32_e32 v45, 16, v45
	v_mul_f32_e32 v58, 0x3d372713, v45
	v_mul_f32_e32 v58, v58, v45
	v_mov_b32_e32 v59, v45
	v_fmac_f32_e32 v59, v58, v59
	v_mul_f32_e32 v58, 0x3f4c422a, v59
	v_add_f32_e32 v58, v58, v58
	v_mul_f32_e32 v58, 0x3fb8aa3b, v58
	v_exp_f32_e32 v59, v58
	v_mul_f32_e32 v58, 0x3d372713, v44
	v_mul_f32_e32 v58, v58, v44
	v_mov_b32_e32 v61, v44
	v_fmac_f32_e32 v61, v58, v61
	v_mul_f32_e32 v58, 0x3f4c422a, v61
	v_add_f32_e32 v58, v58, v58
	v_mul_f32_e32 v58, 0x3fb8aa3b, v58
	v_exp_f32_e32 v58, v58
	v_pk_mul_f32 v[44:45], v[44:45], 0.5 op_sel_hi:[1,0]
	v_pk_add_f32 v[58:59], v[58:59], 1.0 op_sel_hi:[1,0]
	s_nop 0
	v_div_scale_f32 v61, s[14:15], v59, v59, 2.0
	v_rcp_f32_e32 v62, v61
	s_nop 0
	v_fma_f32 v63, -v61, v62, 1.0
	v_fmac_f32_e32 v62, v63, v62
	v_div_scale_f32 v63, vcc, 2.0, v59, 2.0
	v_mul_f32_e32 v64, v63, v62
	v_fma_f32 v65, -v61, v64, v63
	v_fmac_f32_e32 v64, v65, v62
	v_fma_f32 v61, -v61, v64, v63
	v_div_fmas_f32 v61, v61, v62, v64
	v_div_fixup_f32 v59, v61, v59, 2.0
	v_div_scale_f32 v61, s[14:15], v58, v58, 2.0
	v_rcp_f32_e32 v62, v61
	s_nop 0
	v_fma_f32 v63, -v61, v62, 1.0
	v_fmac_f32_e32 v62, v63, v62
	v_div_scale_f32 v63, vcc, 2.0, v58, 2.0
	v_mul_f32_e32 v64, v63, v62
	v_fma_f32 v65, -v61, v64, v63
	v_fmac_f32_e32 v64, v65, v62
	v_fma_f32 v61, -v61, v64, v63
	v_div_fmas_f32 v61, v61, v62, v64
	v_div_fixup_f32 v58, v61, v58, 2.0
	v_pk_add_f32 v[58:59], v[58:59], 1.0 op_sel_hi:[1,0] neg_lo:[1,0] neg_hi:[1,0]
	s_nop 0
	v_pk_add_f32 v[58:59], v[58:59], 1.0 op_sel_hi:[1,0]
	s_nop 0
	v_pk_mul_f32 v[58:59], v[44:45], v[58:59]
	s_nop 0
	v_pk_mul_f32 v[44:45], v[58:59], v[58:59]
	s_nop 0
	v_add_f32_e32 v45, v45, v60
	v_add_f32_e32 v44, v44, v45
	s_nop 1
	v_mov_b32_dpp v45, v44 quad_perm:[1,0,3,2] row_mask:0xf bank_mask:0xf
	s_waitcnt lgkmcnt(0)
	v_add_f32_e32 v44, v44, v45
	s_nop 1
	v_mov_b32_dpp v45, v44 quad_perm:[2,3,0,1] row_mask:0xf bank_mask:0xf
	s_waitcnt lgkmcnt(0)
	v_add_f32_e32 v44, v44, v45
	s_nop 1
	v_mov_b32_dpp v45, v44 row_half_mirror row_mask:0xf bank_mask:0xf
	s_waitcnt lgkmcnt(0)
	v_add_f32_e32 v44, v44, v45
	s_nop 1
	v_mov_b32_dpp v45, v44 row_mirror row_mask:0xf bank_mask:0xf
	s_waitcnt lgkmcnt(0)
	v_add_f32_e32 v44, v44, v45
	ds_bpermute_b32 v45, v110, v44
	s_waitcnt lgkmcnt(0)
	v_add_f32_e32 v44, v44, v45
	v_fmamk_f32 v44, v44, 0x3b800000, v243
	v_cmp_gt_f32_e32 vcc, s3, v44
	v_mul_f32_e32 v45, 0x4b800000, v44
	s_nop 0
	v_cndmask_b32_e32 v44, v44, v45, vcc
	v_rsq_f32_e32 v44, v44
	s_nop 0
	v_mul_f32_e32 v45, 0x45800000, v44
	v_cndmask_b32_e32 v60, v44, v45, vcc
	v_mul_f32_e32 v44, v52, v60
	v_mul_f32_e32 v45, v53, v60
	v_mul_f32_e32 v42, v42, v60
	v_mul_f32_e32 v44, v70, v44
	v_mul_f32_e32 v45, v71, v45
	v_mul_f32_e32 v43, v43, v60
	v_mul_f32_e32 v42, v73, v42
	v_cvt_pk_bf16_f32 v44, v44, v45
	v_cvt_pk_bf16_f32 v51, v54, v55
	v_mul_f32_e32 v43, v72, v43
	v_cvt_pk_bf16_f32 v45, v43, v42
	v_mul_f32_e32 v42, v47, v60
	v_mul_f32_e32 v42, v66, v42
	v_mul_f32_e32 v43, v46, v60
	v_cvt_pk_bf16_f32 v52, v56, v48
	v_mul_f32_e32 v43, v67, v43
	v_cvt_pk_bf16_f32 v46, v42, v43
	v_mul_f32_e32 v42, v59, v60
	v_mul_f32_e32 v42, v68, v42
	v_mul_f32_e32 v43, v58, v60
	v_cvt_pk_bf16_f32 v53, v57, v49
	v_mul_f32_e32 v43, v69, v43
	v_cvt_pk_bf16_f32 v47, v42, v43
	v_lshlrev_b32_e32 v42, 16, v38
	v_mul_f32_e32 v43, 0x3d372713, v42
	v_mul_f32_e32 v43, v43, v42
	v_fma_f32 v43, v43, v42, v42
	v_mul_f32_e32 v43, 0x3f4c422a, v43
	v_add_f32_e32 v43, v43, v43
	v_mul_f32_e32 v43, 0x3fb8aa3b, v43
	v_exp_f32_e32 v43, v43
	ds_write_b128 v111, v[50:53] offset:17408
	ds_write_b128 v112, v[44:47] offset:17408
	v_mul_f32_e32 v42, 0.5, v42
	v_and_b32_e32 v38, 0xffff0000, v38
	v_add_f32_e32 v43, 1.0, v43
	v_div_scale_f32 v44, s[14:15], v43, v43, 2.0
	v_rcp_f32_e32 v45, v44
	s_nop 0
	v_fma_f32 v46, -v44, v45, 1.0
	v_fmac_f32_e32 v45, v46, v45
	v_div_scale_f32 v46, vcc, 2.0, v43, 2.0
	v_mul_f32_e32 v47, v46, v45
	v_fma_f32 v48, -v44, v47, v46
	v_fmac_f32_e32 v47, v48, v45
	v_fma_f32 v44, -v44, v47, v46
	v_div_fmas_f32 v44, v44, v45, v47
	v_div_fixup_f32 v43, v44, v43, 2.0
	v_sub_f32_e32 v43, 1.0, v43
	v_add_f32_e32 v43, 1.0, v43
	v_mul_f32_e32 v42, v42, v43
	v_mul_f32_e32 v43, 0x3d372713, v38
	v_mul_f32_e32 v43, v43, v38
	v_fma_f32 v43, v43, v38, v38
	v_mul_f32_e32 v43, 0x3f4c422a, v43
	v_add_f32_e32 v43, v43, v43
	v_mul_f32_e32 v43, 0x3fb8aa3b, v43
	v_exp_f32_e32 v43, v43
	v_mul_f32_e32 v38, 0.5, v38
	v_add_f32_e32 v43, 1.0, v43
	v_div_scale_f32 v44, s[14:15], v43, v43, 2.0
	v_rcp_f32_e32 v45, v44
	s_nop 0
	v_fma_f32 v46, -v44, v45, 1.0
	v_fmac_f32_e32 v45, v46, v45
	v_div_scale_f32 v46, vcc, 2.0, v43, 2.0
	v_mul_f32_e32 v47, v46, v45
	v_fma_f32 v48, -v44, v47, v46
	v_fmac_f32_e32 v47, v48, v45
	v_fma_f32 v44, -v44, v47, v46
	v_div_fmas_f32 v44, v44, v45, v47
	v_div_fixup_f32 v43, v44, v43, 2.0
	v_sub_f32_e32 v43, 1.0, v43
	v_add_f32_e32 v43, 1.0, v43
	v_mul_f32_e32 v43, v38, v43
	v_lshlrev_b32_e32 v38, 16, v34
	v_mul_f32_e32 v44, 0x3d372713, v38
	v_mul_f32_e32 v44, v44, v38
	v_fma_f32 v44, v44, v38, v38
	v_mul_f32_e32 v44, 0x3f4c422a, v44
	v_add_f32_e32 v44, v44, v44
	v_mul_f32_e32 v44, 0x3fb8aa3b, v44
	v_exp_f32_e32 v44, v44
	v_mul_f32_e32 v38, 0.5, v38
	v_and_b32_e32 v34, 0xffff0000, v34
	v_cvt_pk_bf16_f32 v42, v42, v43
	v_add_f32_e32 v44, 1.0, v44
	v_div_scale_f32 v45, s[14:15], v44, v44, 2.0
	v_rcp_f32_e32 v46, v45
	s_nop 0
	v_fma_f32 v47, -v45, v46, 1.0
	v_fmac_f32_e32 v46, v47, v46
	v_div_scale_f32 v47, vcc, 2.0, v44, 2.0
	v_mul_f32_e32 v48, v47, v46
	v_fma_f32 v49, -v45, v48, v47
	v_fmac_f32_e32 v48, v49, v46
	v_fma_f32 v45, -v45, v48, v47
	v_div_fmas_f32 v45, v45, v46, v48
	v_div_fixup_f32 v44, v45, v44, 2.0
	v_sub_f32_e32 v44, 1.0, v44
	v_add_f32_e32 v44, 1.0, v44
	v_mul_f32_e32 v44, v38, v44
	v_mul_f32_e32 v38, 0x3d372713, v34
	v_mul_f32_e32 v38, v38, v34
	v_fma_f32 v38, v38, v34, v34
	v_mul_f32_e32 v38, 0x3f4c422a, v38
	v_add_f32_e32 v38, v38, v38
	v_mul_f32_e32 v38, 0x3fb8aa3b, v38
	v_exp_f32_e32 v38, v38
	v_mul_f32_e32 v34, 0.5, v34
	v_add_f32_e32 v38, 1.0, v38
	v_div_scale_f32 v45, s[14:15], v38, v38, 2.0
	v_rcp_f32_e32 v46, v45
	s_nop 0
	v_fma_f32 v47, -v45, v46, 1.0
	v_fmac_f32_e32 v46, v47, v46
	v_div_scale_f32 v47, vcc, 2.0, v38, 2.0
	v_mul_f32_e32 v48, v47, v46
	v_fma_f32 v49, -v45, v48, v47
	v_fmac_f32_e32 v48, v49, v46
	v_fma_f32 v45, -v45, v48, v47
	v_div_fmas_f32 v45, v45, v46, v48
	v_div_fixup_f32 v38, v45, v38, 2.0
	v_sub_f32_e32 v38, 1.0, v38
	v_add_f32_e32 v38, 1.0, v38
	v_mul_f32_e32 v45, v34, v38
	v_lshlrev_b32_e32 v34, 16, v39
	v_mul_f32_e32 v38, 0x3d372713, v34
	v_mul_f32_e32 v38, v38, v34
	v_fma_f32 v38, v38, v34, v34
	v_mul_f32_e32 v38, 0x3f4c422a, v38
	v_add_f32_e32 v38, v38, v38
	v_mul_f32_e32 v38, 0x3fb8aa3b, v38
	v_exp_f32_e32 v38, v38
	v_mul_f32_e32 v34, 0.5, v34
	v_add_f32_e32 v38, 1.0, v38
	v_div_scale_f32 v46, s[14:15], v38, v38, 2.0
	v_rcp_f32_e32 v47, v46
	s_nop 0
	v_fma_f32 v48, -v46, v47, 1.0
	v_fmac_f32_e32 v47, v48, v47
	v_div_scale_f32 v48, vcc, 2.0, v38, 2.0
	v_mul_f32_e32 v49, v48, v47
	v_fma_f32 v50, -v46, v49, v48
	v_fmac_f32_e32 v49, v50, v47
	v_fma_f32 v46, -v46, v49, v48
	v_div_fmas_f32 v46, v46, v47, v49
	v_div_fixup_f32 v38, v46, v38, 2.0
	v_sub_f32_e32 v38, 1.0, v38
	v_add_f32_e32 v38, 1.0, v38
	v_mul_f32_e32 v46, v34, v38
	v_and_b32_e32 v34, 0xffff0000, v39
	v_mul_f32_e32 v38, 0x3d372713, v34
	v_mul_f32_e32 v38, v38, v34
	v_fma_f32 v38, v38, v34, v34
	v_mul_f32_e32 v38, 0x3f4c422a, v38
	v_add_f32_e32 v38, v38, v38
	v_mul_f32_e32 v38, 0x3fb8aa3b, v38
	v_exp_f32_e32 v38, v38
	v_mul_f32_e32 v34, 0.5, v34
	v_add_f32_e32 v38, 1.0, v38
	v_div_scale_f32 v39, s[14:15], v38, v38, 2.0
	v_rcp_f32_e32 v47, v39
	s_nop 0
	v_fma_f32 v48, -v39, v47, 1.0
	v_fmac_f32_e32 v47, v48, v47
	v_div_scale_f32 v48, vcc, 2.0, v38, 2.0
	v_mul_f32_e32 v49, v48, v47
	v_fma_f32 v50, -v39, v49, v48
	v_fmac_f32_e32 v49, v50, v47
	v_fma_f32 v39, -v39, v49, v48
	v_div_fmas_f32 v39, v39, v47, v49
	v_div_fixup_f32 v38, v39, v38, 2.0
	v_sub_f32_e32 v38, 1.0, v38
	v_add_f32_e32 v38, 1.0, v38
	v_mul_f32_e32 v47, v34, v38
	v_lshlrev_b32_e32 v34, 16, v40
	v_mul_f32_e32 v38, 0x3d372713, v34
	v_mul_f32_e32 v38, v38, v34
	v_fma_f32 v38, v38, v34, v34
	v_mul_f32_e32 v38, 0x3f4c422a, v38
	v_add_f32_e32 v38, v38, v38
	v_mul_f32_e32 v38, 0x3fb8aa3b, v38
	v_exp_f32_e32 v38, v38
	v_mul_f32_e32 v34, 0.5, v34
	v_add_f32_e32 v38, 1.0, v38
	v_div_scale_f32 v39, s[14:15], v38, v38, 2.0
	v_rcp_f32_e32 v48, v39
	s_nop 0
	v_fma_f32 v49, -v39, v48, 1.0
	v_fmac_f32_e32 v48, v49, v48
	v_div_scale_f32 v49, vcc, 2.0, v38, 2.0
	v_mul_f32_e32 v50, v49, v48
	v_fma_f32 v51, -v39, v50, v49
	v_fmac_f32_e32 v50, v51, v48
	v_fma_f32 v39, -v39, v50, v49
	v_div_fmas_f32 v39, v39, v48, v50
	v_div_fixup_f32 v38, v39, v38, 2.0
	v_sub_f32_e32 v38, 1.0, v38
	v_add_f32_e32 v38, 1.0, v38
	v_mul_f32_e32 v48, v34, v38
	v_and_b32_e32 v34, 0xffff0000, v40
	v_mul_f32_e32 v38, 0x3d372713, v34
	v_mul_f32_e32 v38, v38, v34
	v_fma_f32 v38, v38, v34, v34
	v_mul_f32_e32 v38, 0x3f4c422a, v38
	v_add_f32_e32 v38, v38, v38
	v_mul_f32_e32 v38, 0x3fb8aa3b, v38
	v_exp_f32_e32 v38, v38
	v_mul_f32_e32 v34, 0.5, v34
	v_add_f32_e32 v38, 1.0, v38
	v_div_scale_f32 v39, s[14:15], v38, v38, 2.0
	v_rcp_f32_e32 v40, v39
	s_nop 0
	v_fma_f32 v49, -v39, v40, 1.0
	v_fmac_f32_e32 v40, v49, v40
	v_div_scale_f32 v49, vcc, 2.0, v38, 2.0
	v_mul_f32_e32 v50, v49, v40
	v_fma_f32 v51, -v39, v50, v49
	v_fmac_f32_e32 v50, v51, v40
	v_fma_f32 v39, -v39, v50, v49
	v_div_fmas_f32 v39, v39, v40, v50
	v_div_fixup_f32 v38, v39, v38, 2.0
	v_sub_f32_e32 v38, 1.0, v38
	v_add_f32_e32 v38, 1.0, v38
	v_mul_f32_e32 v40, v34, v38
	v_lshlrev_b32_e32 v34, 16, v41
	v_mul_f32_e32 v38, 0x3d372713, v34
	v_mul_f32_e32 v38, v38, v34
	v_fma_f32 v38, v38, v34, v34
	v_mul_f32_e32 v38, 0x3f4c422a, v38
	v_add_f32_e32 v38, v38, v38
	v_mul_f32_e32 v38, 0x3fb8aa3b, v38
	v_exp_f32_e32 v38, v38
	v_mul_f32_e32 v34, 0.5, v34
	v_add_f32_e32 v38, 1.0, v38
	v_div_scale_f32 v39, s[14:15], v38, v38, 2.0
	v_rcp_f32_e32 v49, v39
	s_nop 0
	v_fma_f32 v50, -v39, v49, 1.0
	v_fmac_f32_e32 v49, v50, v49
	v_div_scale_f32 v50, vcc, 2.0, v38, 2.0
	v_mul_f32_e32 v51, v50, v49
	v_fma_f32 v52, -v39, v51, v50
	v_fmac_f32_e32 v51, v52, v49
	v_fma_f32 v39, -v39, v51, v50
	v_div_fmas_f32 v39, v39, v49, v51
	v_div_fixup_f32 v38, v39, v38, 2.0
	v_sub_f32_e32 v38, 1.0, v38
	v_add_f32_e32 v38, 1.0, v38
	v_mul_f32_e32 v49, v34, v38
	v_and_b32_e32 v34, 0xffff0000, v41
	v_mul_f32_e32 v38, 0x3d372713, v34
	v_mul_f32_e32 v38, v38, v34
	v_fma_f32 v38, v38, v34, v34
	v_mul_f32_e32 v38, 0x3f4c422a, v38
	v_add_f32_e32 v38, v38, v38
	v_mul_f32_e32 v38, 0x3fb8aa3b, v38
	v_exp_f32_e32 v38, v38
	v_mul_f32_e32 v34, 0.5, v34
	v_add_f32_e32 v38, 1.0, v38
	v_div_scale_f32 v39, s[14:15], v38, v38, 2.0
	v_rcp_f32_e32 v41, v39
	s_nop 0
	v_fma_f32 v50, -v39, v41, 1.0
	v_fmac_f32_e32 v41, v50, v41
	v_div_scale_f32 v50, vcc, 2.0, v38, 2.0
	v_mul_f32_e32 v51, v50, v41
	v_fma_f32 v52, -v39, v51, v50
	v_fmac_f32_e32 v51, v52, v41
	v_fma_f32 v39, -v39, v51, v50
	v_div_fmas_f32 v39, v39, v41, v51
	v_div_fixup_f32 v38, v39, v38, 2.0
	v_sub_f32_e32 v38, 1.0, v38
	v_add_f32_e32 v38, 1.0, v38
	v_mul_f32_e32 v41, v34, v38
	v_and_b32_e32 v34, 0xffff0000, v35
	v_lshlrev_b32_e32 v35, 16, v35
	v_mul_f32_e32 v38, 0x3d372713, v35
	v_mul_f32_e32 v38, v38, v35
	v_mov_b32_e32 v39, v35
	v_fmac_f32_e32 v39, v38, v39
	v_mul_f32_e32 v38, 0x3f4c422a, v39
	v_add_f32_e32 v38, v38, v38
	v_mul_f32_e32 v38, 0x3fb8aa3b, v38
	v_exp_f32_e32 v39, v38
	v_mul_f32_e32 v38, 0x3d372713, v34
	v_mul_f32_e32 v38, v38, v34
	v_mov_b32_e32 v51, v34
	v_fmac_f32_e32 v51, v38, v51
	v_mul_f32_e32 v38, 0x3f4c422a, v51
	v_add_f32_e32 v38, v38, v38
	v_mul_f32_e32 v38, 0x3fb8aa3b, v38
	v_exp_f32_e32 v38, v38
	v_pk_mul_f32 v[34:35], v[34:35], 0.5 op_sel_hi:[1,0]
	v_mul_f32_e32 v50, v45, v45
	v_fmac_f32_e32 v50, v44, v44
	v_pk_add_f32 v[38:39], v[38:39], 1.0 op_sel_hi:[1,0]
	s_nop 0
	v_div_scale_f32 v51, s[14:15], v39, v39, 2.0
	v_rcp_f32_e32 v52, v51
	s_nop 0
	v_fma_f32 v53, -v51, v52, 1.0
	v_fmac_f32_e32 v52, v53, v52
	v_div_scale_f32 v53, vcc, 2.0, v39, 2.0
	v_mul_f32_e32 v54, v53, v52
	v_fma_f32 v55, -v51, v54, v53
	v_fmac_f32_e32 v54, v55, v52
	v_fma_f32 v51, -v51, v54, v53
	v_div_fmas_f32 v51, v51, v52, v54
	v_div_fixup_f32 v39, v51, v39, 2.0
	v_div_scale_f32 v51, s[14:15], v38, v38, 2.0
	v_rcp_f32_e32 v52, v51
	s_nop 0
	v_fma_f32 v53, -v51, v52, 1.0
	v_fmac_f32_e32 v52, v53, v52
	v_div_scale_f32 v53, vcc, 2.0, v38, 2.0
	v_mul_f32_e32 v54, v53, v52
	v_fma_f32 v55, -v51, v54, v53
	v_fmac_f32_e32 v54, v55, v52
	v_fma_f32 v51, -v51, v54, v53
	v_div_fmas_f32 v51, v51, v52, v54
	v_div_fixup_f32 v38, v51, v38, 2.0
	v_pk_add_f32 v[38:39], v[38:39], 1.0 op_sel_hi:[1,0] neg_lo:[1,0] neg_hi:[1,0]
	s_nop 0
	v_pk_add_f32 v[38:39], v[38:39], 1.0 op_sel_hi:[1,0]
	s_nop 0
	v_pk_mul_f32 v[34:35], v[34:35], v[38:39]
	s_nop 0
	v_pk_mul_f32 v[38:39], v[34:35], v[34:35]
	s_nop 0
	v_add_f32_e32 v39, v39, v50
	v_add_f32_e32 v52, v38, v39
	v_lshlrev_b32_e32 v39, 16, v36
	v_and_b32_e32 v38, 0xffff0000, v36
	v_mul_f32_e32 v36, 0x3d372713, v39
	v_mul_f32_e32 v36, v36, v39
	v_mov_b32_e32 v50, v39
	v_fmac_f32_e32 v50, v36, v50
	v_mul_f32_e32 v36, 0x3f4c422a, v50
	v_add_f32_e32 v36, v36, v36
	v_mul_f32_e32 v36, 0x3fb8aa3b, v36
	v_exp_f32_e32 v51, v36
	v_mul_f32_e32 v36, 0x3d372713, v38
	v_mul_f32_e32 v36, v36, v38
	v_mov_b32_e32 v50, v38
	v_fmac_f32_e32 v50, v36, v50
	v_mul_f32_e32 v36, 0x3f4c422a, v50
	v_add_f32_e32 v36, v36, v36
	v_mul_f32_e32 v36, 0x3fb8aa3b, v36
	v_exp_f32_e32 v50, v36
	v_pk_mul_f32 v[38:39], v[38:39], 0.5 op_sel_hi:[1,0]
	v_pk_add_f32 v[50:51], v[50:51], 1.0 op_sel_hi:[1,0]
	s_nop 0
	v_div_scale_f32 v36, s[14:15], v51, v51, 2.0
	v_rcp_f32_e32 v53, v36
	s_nop 0
	v_fma_f32 v54, -v36, v53, 1.0
	v_fmac_f32_e32 v53, v54, v53
	v_div_scale_f32 v54, vcc, 2.0, v51, 2.0
	v_mul_f32_e32 v55, v54, v53
	v_fma_f32 v56, -v36, v55, v54
	v_fmac_f32_e32 v55, v56, v53
	v_fma_f32 v36, -v36, v55, v54
	v_div_fmas_f32 v36, v36, v53, v55
	v_div_fixup_f32 v51, v36, v51, 2.0
	v_div_scale_f32 v36, s[14:15], v50, v50, 2.0
	v_rcp_f32_e32 v53, v36
	s_nop 0
	v_fma_f32 v54, -v36, v53, 1.0
	v_fmac_f32_e32 v53, v54, v53
	v_div_scale_f32 v54, vcc, 2.0, v50, 2.0
	v_mul_f32_e32 v55, v54, v53
	v_fma_f32 v56, -v36, v55, v54
	v_fmac_f32_e32 v55, v56, v53
	v_fma_f32 v36, -v36, v55, v54
	v_div_fmas_f32 v36, v36, v53, v55
	v_div_fixup_f32 v50, v36, v50, 2.0
	v_pk_add_f32 v[50:51], v[50:51], 1.0 op_sel_hi:[1,0] neg_lo:[1,0] neg_hi:[1,0]
	s_nop 0
	v_pk_add_f32 v[50:51], v[50:51], 1.0 op_sel_hi:[1,0]
	s_nop 0
	v_pk_mul_f32 v[38:39], v[38:39], v[50:51]
	s_nop 0
	v_pk_mul_f32 v[50:51], v[38:39], v[38:39]
	s_nop 0
	v_add_f32_e32 v36, v51, v52
	v_add_f32_e32 v52, v50, v36
	v_and_b32_e32 v36, 0xffff0000, v37
	v_lshlrev_b32_e32 v37, 16, v37
	v_mul_f32_e32 v50, 0x3d372713, v37
	v_mul_f32_e32 v50, v50, v37
	v_mov_b32_e32 v51, v37
	v_fmac_f32_e32 v51, v50, v51
	v_mul_f32_e32 v50, 0x3f4c422a, v51
	v_add_f32_e32 v50, v50, v50
	v_mul_f32_e32 v50, 0x3fb8aa3b, v50
	v_exp_f32_e32 v51, v50
	v_mul_f32_e32 v50, 0x3d372713, v36
	v_mul_f32_e32 v50, v50, v36
	v_mov_b32_e32 v53, v36
	v_fmac_f32_e32 v53, v50, v53
	v_mul_f32_e32 v50, 0x3f4c422a, v53
	v_add_f32_e32 v50, v50, v50
	v_mul_f32_e32 v50, 0x3fb8aa3b, v50
	v_exp_f32_e32 v50, v50
	v_pk_mul_f32 v[36:37], v[36:37], 0.5 op_sel_hi:[1,0]
	v_pk_add_f32 v[50:51], v[50:51], 1.0 op_sel_hi:[1,0]
	s_nop 0
	v_div_scale_f32 v53, s[14:15], v51, v51, 2.0
	v_rcp_f32_e32 v54, v53
	s_nop 0
	v_fma_f32 v55, -v53, v54, 1.0
	v_fmac_f32_e32 v54, v55, v54
	v_div_scale_f32 v55, vcc, 2.0, v51, 2.0
	v_mul_f32_e32 v56, v55, v54
	v_fma_f32 v57, -v53, v56, v55
	v_fmac_f32_e32 v56, v57, v54
	v_fma_f32 v53, -v53, v56, v55
	v_div_fmas_f32 v53, v53, v54, v56
	v_div_fixup_f32 v51, v53, v51, 2.0
	v_div_scale_f32 v53, s[14:15], v50, v50, 2.0
	v_rcp_f32_e32 v54, v53
	s_nop 0
	v_fma_f32 v55, -v53, v54, 1.0
	v_fmac_f32_e32 v54, v55, v54
	v_div_scale_f32 v55, vcc, 2.0, v50, 2.0
	v_mul_f32_e32 v56, v55, v54
	v_fma_f32 v57, -v53, v56, v55
	v_fmac_f32_e32 v56, v57, v54
	v_fma_f32 v53, -v53, v56, v55
	v_div_fmas_f32 v53, v53, v54, v56
	v_div_fixup_f32 v50, v53, v50, 2.0
	v_pk_add_f32 v[50:51], v[50:51], 1.0 op_sel_hi:[1,0] neg_lo:[1,0] neg_hi:[1,0]
	s_nop 0
	v_pk_add_f32 v[50:51], v[50:51], 1.0 op_sel_hi:[1,0]
	s_nop 0
	v_pk_mul_f32 v[50:51], v[36:37], v[50:51]
	s_nop 0
	v_pk_mul_f32 v[36:37], v[50:51], v[50:51]
	s_nop 0
	v_add_f32_e32 v37, v37, v52
	v_add_f32_e32 v36, v36, v37
	s_nop 1
	v_mov_b32_dpp v37, v36 quad_perm:[1,0,3,2] row_mask:0xf bank_mask:0xf
	s_waitcnt lgkmcnt(0)
	v_add_f32_e32 v36, v36, v37
	s_nop 1
	v_mov_b32_dpp v37, v36 quad_perm:[2,3,0,1] row_mask:0xf bank_mask:0xf
	s_waitcnt lgkmcnt(0)
	v_add_f32_e32 v36, v36, v37
	s_nop 1
	v_mov_b32_dpp v37, v36 row_half_mirror row_mask:0xf bank_mask:0xf
	s_waitcnt lgkmcnt(0)
	v_add_f32_e32 v36, v36, v37
	s_nop 1
	v_mov_b32_dpp v37, v36 row_mirror row_mask:0xf bank_mask:0xf
	s_waitcnt lgkmcnt(0)
	v_add_f32_e32 v36, v36, v37
	ds_bpermute_b32 v37, v110, v36
	s_waitcnt lgkmcnt(0)
	v_add_f32_e32 v36, v36, v37
	v_fmamk_f32 v36, v36, 0x3b800000, v243
	v_cmp_gt_f32_e32 vcc, s3, v36
	v_mul_f32_e32 v37, 0x4b800000, v36
	s_nop 0
	v_cndmask_b32_e32 v36, v36, v37, vcc
	v_rsq_f32_e32 v36, v36
	s_nop 0
	v_mul_f32_e32 v37, 0x45800000, v36
	v_cndmask_b32_e32 v52, v36, v37, vcc
	v_mul_f32_e32 v36, v44, v52
	v_mul_f32_e32 v37, v45, v52
	v_mul_f32_e32 v34, v34, v52
	v_mul_f32_e32 v36, v70, v36
	v_mul_f32_e32 v37, v71, v37
	v_mul_f32_e32 v35, v35, v52
	v_mul_f32_e32 v34, v73, v34
	v_cvt_pk_bf16_f32 v36, v36, v37
	v_cvt_pk_bf16_f32 v43, v46, v47
	v_mul_f32_e32 v35, v72, v35
	v_cvt_pk_bf16_f32 v37, v35, v34
	v_mul_f32_e32 v34, v39, v52
	v_mul_f32_e32 v34, v66, v34
	v_mul_f32_e32 v35, v38, v52
	v_cvt_pk_bf16_f32 v44, v48, v40
	v_mul_f32_e32 v35, v67, v35
	v_cvt_pk_bf16_f32 v38, v34, v35
	v_mul_f32_e32 v34, v51, v52
	v_mul_f32_e32 v34, v68, v34
	v_mul_f32_e32 v35, v50, v52
	v_cvt_pk_bf16_f32 v45, v49, v41
	v_mul_f32_e32 v35, v69, v35
	v_cvt_pk_bf16_f32 v39, v34, v35
	v_lshlrev_b32_e32 v34, 16, v30
	v_mul_f32_e32 v35, 0x3d372713, v34
	v_mul_f32_e32 v35, v35, v34
	v_fma_f32 v35, v35, v34, v34
	v_mul_f32_e32 v35, 0x3f4c422a, v35
	v_add_f32_e32 v35, v35, v35
	v_mul_f32_e32 v35, 0x3fb8aa3b, v35
	v_exp_f32_e32 v35, v35
	ds_write_b128 v111, v[42:45] offset:26112
	ds_write_b128 v112, v[36:39] offset:26112
	v_mul_f32_e32 v34, 0.5, v34
	v_and_b32_e32 v30, 0xffff0000, v30
	v_add_f32_e32 v35, 1.0, v35
	v_div_scale_f32 v36, s[14:15], v35, v35, 2.0
	v_rcp_f32_e32 v37, v36
	s_nop 0
	v_fma_f32 v38, -v36, v37, 1.0
	v_fmac_f32_e32 v37, v38, v37
	v_div_scale_f32 v38, vcc, 2.0, v35, 2.0
	v_mul_f32_e32 v39, v38, v37
	v_fma_f32 v40, -v36, v39, v38
	v_fmac_f32_e32 v39, v40, v37
	v_fma_f32 v36, -v36, v39, v38
	v_div_fmas_f32 v36, v36, v37, v39
	v_div_fixup_f32 v35, v36, v35, 2.0
	v_sub_f32_e32 v35, 1.0, v35
	v_add_f32_e32 v35, 1.0, v35
	v_mul_f32_e32 v34, v34, v35
	v_mul_f32_e32 v35, 0x3d372713, v30
	v_mul_f32_e32 v35, v35, v30
	v_fma_f32 v35, v35, v30, v30
	v_mul_f32_e32 v35, 0x3f4c422a, v35
	v_add_f32_e32 v35, v35, v35
	v_mul_f32_e32 v35, 0x3fb8aa3b, v35
	v_exp_f32_e32 v35, v35
	v_mul_f32_e32 v30, 0.5, v30
	v_add_f32_e32 v35, 1.0, v35
	v_div_scale_f32 v36, s[14:15], v35, v35, 2.0
	v_rcp_f32_e32 v37, v36
	s_nop 0
	v_fma_f32 v38, -v36, v37, 1.0
	v_fmac_f32_e32 v37, v38, v37
	v_div_scale_f32 v38, vcc, 2.0, v35, 2.0
	v_mul_f32_e32 v39, v38, v37
	v_fma_f32 v40, -v36, v39, v38
	v_fmac_f32_e32 v39, v40, v37
	v_fma_f32 v36, -v36, v39, v38
	v_div_fmas_f32 v36, v36, v37, v39
	v_div_fixup_f32 v35, v36, v35, 2.0
	v_sub_f32_e32 v35, 1.0, v35
	v_add_f32_e32 v35, 1.0, v35
	v_mul_f32_e32 v35, v30, v35
	v_lshlrev_b32_e32 v30, 16, v26
	v_mul_f32_e32 v36, 0x3d372713, v30
	v_mul_f32_e32 v36, v36, v30
	v_fma_f32 v36, v36, v30, v30
	v_mul_f32_e32 v36, 0x3f4c422a, v36
	v_add_f32_e32 v36, v36, v36
	v_mul_f32_e32 v36, 0x3fb8aa3b, v36
	v_exp_f32_e32 v36, v36
	v_mul_f32_e32 v30, 0.5, v30
	v_and_b32_e32 v26, 0xffff0000, v26
	v_cvt_pk_bf16_f32 v34, v34, v35
	v_add_f32_e32 v36, 1.0, v36
	v_div_scale_f32 v37, s[14:15], v36, v36, 2.0
	v_rcp_f32_e32 v38, v37
	s_nop 0
	v_fma_f32 v39, -v37, v38, 1.0
	v_fmac_f32_e32 v38, v39, v38
	v_div_scale_f32 v39, vcc, 2.0, v36, 2.0
	v_mul_f32_e32 v40, v39, v38
	v_fma_f32 v41, -v37, v40, v39
	v_fmac_f32_e32 v40, v41, v38
	v_fma_f32 v37, -v37, v40, v39
	v_div_fmas_f32 v37, v37, v38, v40
	v_div_fixup_f32 v36, v37, v36, 2.0
	v_sub_f32_e32 v36, 1.0, v36
	v_add_f32_e32 v36, 1.0, v36
	v_mul_f32_e32 v36, v30, v36
	v_mul_f32_e32 v30, 0x3d372713, v26
	v_mul_f32_e32 v30, v30, v26
	v_fma_f32 v30, v30, v26, v26
	v_mul_f32_e32 v30, 0x3f4c422a, v30
	v_add_f32_e32 v30, v30, v30
	v_mul_f32_e32 v30, 0x3fb8aa3b, v30
	v_exp_f32_e32 v30, v30
	v_mul_f32_e32 v26, 0.5, v26
	v_add_f32_e32 v30, 1.0, v30
	v_div_scale_f32 v37, s[14:15], v30, v30, 2.0
	v_rcp_f32_e32 v38, v37
	s_nop 0
	v_fma_f32 v39, -v37, v38, 1.0
	v_fmac_f32_e32 v38, v39, v38
	v_div_scale_f32 v39, vcc, 2.0, v30, 2.0
	v_mul_f32_e32 v40, v39, v38
	v_fma_f32 v41, -v37, v40, v39
	v_fmac_f32_e32 v40, v41, v38
	v_fma_f32 v37, -v37, v40, v39
	v_div_fmas_f32 v37, v37, v38, v40
	v_div_fixup_f32 v30, v37, v30, 2.0
	v_sub_f32_e32 v30, 1.0, v30
	v_add_f32_e32 v30, 1.0, v30
	v_mul_f32_e32 v37, v26, v30
	v_lshlrev_b32_e32 v26, 16, v31
	v_mul_f32_e32 v30, 0x3d372713, v26
	v_mul_f32_e32 v30, v30, v26
	v_fma_f32 v30, v30, v26, v26
	v_mul_f32_e32 v30, 0x3f4c422a, v30
	v_add_f32_e32 v30, v30, v30
	v_mul_f32_e32 v30, 0x3fb8aa3b, v30
	v_exp_f32_e32 v30, v30
	v_mul_f32_e32 v26, 0.5, v26
	v_add_f32_e32 v30, 1.0, v30
	v_div_scale_f32 v38, s[14:15], v30, v30, 2.0
	v_rcp_f32_e32 v39, v38
	s_nop 0
	v_fma_f32 v40, -v38, v39, 1.0
	v_fmac_f32_e32 v39, v40, v39
	v_div_scale_f32 v40, vcc, 2.0, v30, 2.0
	v_mul_f32_e32 v41, v40, v39
	v_fma_f32 v42, -v38, v41, v40
	v_fmac_f32_e32 v41, v42, v39
	v_fma_f32 v38, -v38, v41, v40
	v_div_fmas_f32 v38, v38, v39, v41
	v_div_fixup_f32 v30, v38, v30, 2.0
	v_sub_f32_e32 v30, 1.0, v30
	v_add_f32_e32 v30, 1.0, v30
	v_mul_f32_e32 v38, v26, v30
	v_and_b32_e32 v26, 0xffff0000, v31
	v_mul_f32_e32 v30, 0x3d372713, v26
	v_mul_f32_e32 v30, v30, v26
	v_fma_f32 v30, v30, v26, v26
	v_mul_f32_e32 v30, 0x3f4c422a, v30
	v_add_f32_e32 v30, v30, v30
	v_mul_f32_e32 v30, 0x3fb8aa3b, v30
	v_exp_f32_e32 v30, v30
	v_mul_f32_e32 v26, 0.5, v26
	v_add_f32_e32 v30, 1.0, v30
	v_div_scale_f32 v31, s[14:15], v30, v30, 2.0
	v_rcp_f32_e32 v39, v31
	s_nop 0
	v_fma_f32 v40, -v31, v39, 1.0
	v_fmac_f32_e32 v39, v40, v39
	v_div_scale_f32 v40, vcc, 2.0, v30, 2.0
	v_mul_f32_e32 v41, v40, v39
	v_fma_f32 v42, -v31, v41, v40
	v_fmac_f32_e32 v41, v42, v39
	v_fma_f32 v31, -v31, v41, v40
	v_div_fmas_f32 v31, v31, v39, v41
	v_div_fixup_f32 v30, v31, v30, 2.0
	v_sub_f32_e32 v30, 1.0, v30
	v_add_f32_e32 v30, 1.0, v30
	v_mul_f32_e32 v39, v26, v30
	v_lshlrev_b32_e32 v26, 16, v32
	v_mul_f32_e32 v30, 0x3d372713, v26
	v_mul_f32_e32 v30, v30, v26
	v_fma_f32 v30, v30, v26, v26
	v_mul_f32_e32 v30, 0x3f4c422a, v30
	v_add_f32_e32 v30, v30, v30
	v_mul_f32_e32 v30, 0x3fb8aa3b, v30
	v_exp_f32_e32 v30, v30
	v_mul_f32_e32 v26, 0.5, v26
	v_add_f32_e32 v30, 1.0, v30
	v_div_scale_f32 v31, s[14:15], v30, v30, 2.0
	v_rcp_f32_e32 v40, v31
	s_nop 0
	v_fma_f32 v41, -v31, v40, 1.0
	v_fmac_f32_e32 v40, v41, v40
	v_div_scale_f32 v41, vcc, 2.0, v30, 2.0
	v_mul_f32_e32 v42, v41, v40
	v_fma_f32 v43, -v31, v42, v41
	v_fmac_f32_e32 v42, v43, v40
	v_fma_f32 v31, -v31, v42, v41
	v_div_fmas_f32 v31, v31, v40, v42
	v_div_fixup_f32 v30, v31, v30, 2.0
	v_sub_f32_e32 v30, 1.0, v30
	v_add_f32_e32 v30, 1.0, v30
	v_mul_f32_e32 v40, v26, v30
	v_and_b32_e32 v26, 0xffff0000, v32
	v_mul_f32_e32 v30, 0x3d372713, v26
	v_mul_f32_e32 v30, v30, v26
	v_fma_f32 v30, v30, v26, v26
	v_mul_f32_e32 v30, 0x3f4c422a, v30
	v_add_f32_e32 v30, v30, v30
	v_mul_f32_e32 v30, 0x3fb8aa3b, v30
	v_exp_f32_e32 v30, v30
	v_mul_f32_e32 v26, 0.5, v26
	v_add_f32_e32 v30, 1.0, v30
	v_div_scale_f32 v31, s[14:15], v30, v30, 2.0
	v_rcp_f32_e32 v32, v31
	s_nop 0
	v_fma_f32 v41, -v31, v32, 1.0
	v_fmac_f32_e32 v32, v41, v32
	v_div_scale_f32 v41, vcc, 2.0, v30, 2.0
	v_mul_f32_e32 v42, v41, v32
	v_fma_f32 v43, -v31, v42, v41
	v_fmac_f32_e32 v42, v43, v32
	v_fma_f32 v31, -v31, v42, v41
	v_div_fmas_f32 v31, v31, v32, v42
	v_div_fixup_f32 v30, v31, v30, 2.0
	v_sub_f32_e32 v30, 1.0, v30
	v_add_f32_e32 v30, 1.0, v30
	v_mul_f32_e32 v32, v26, v30
	v_lshlrev_b32_e32 v26, 16, v33
	v_mul_f32_e32 v30, 0x3d372713, v26
	v_mul_f32_e32 v30, v30, v26
	v_fma_f32 v30, v30, v26, v26
	v_mul_f32_e32 v30, 0x3f4c422a, v30
	v_add_f32_e32 v30, v30, v30
	v_mul_f32_e32 v30, 0x3fb8aa3b, v30
	v_exp_f32_e32 v30, v30
	v_mul_f32_e32 v26, 0.5, v26
	v_add_f32_e32 v30, 1.0, v30
	v_div_scale_f32 v31, s[14:15], v30, v30, 2.0
	v_rcp_f32_e32 v41, v31
	s_nop 0
	v_fma_f32 v42, -v31, v41, 1.0
	v_fmac_f32_e32 v41, v42, v41
	v_div_scale_f32 v42, vcc, 2.0, v30, 2.0
	v_mul_f32_e32 v43, v42, v41
	v_fma_f32 v44, -v31, v43, v42
	v_fmac_f32_e32 v43, v44, v41
	v_fma_f32 v31, -v31, v43, v42
	v_div_fmas_f32 v31, v31, v41, v43
	v_div_fixup_f32 v30, v31, v30, 2.0
	v_sub_f32_e32 v30, 1.0, v30
	v_add_f32_e32 v30, 1.0, v30
	v_mul_f32_e32 v41, v26, v30
	v_and_b32_e32 v26, 0xffff0000, v33
	v_mul_f32_e32 v30, 0x3d372713, v26
	v_mul_f32_e32 v30, v30, v26
	v_fma_f32 v30, v30, v26, v26
	v_mul_f32_e32 v30, 0x3f4c422a, v30
	v_add_f32_e32 v30, v30, v30
	v_mul_f32_e32 v30, 0x3fb8aa3b, v30
	v_exp_f32_e32 v30, v30
	v_mul_f32_e32 v26, 0.5, v26
	v_add_f32_e32 v30, 1.0, v30
	v_div_scale_f32 v31, s[14:15], v30, v30, 2.0
	v_rcp_f32_e32 v33, v31
	s_nop 0
	v_fma_f32 v42, -v31, v33, 1.0
	v_fmac_f32_e32 v33, v42, v33
	v_div_scale_f32 v42, vcc, 2.0, v30, 2.0
	v_mul_f32_e32 v43, v42, v33
	v_fma_f32 v44, -v31, v43, v42
	v_fmac_f32_e32 v43, v44, v33
	v_fma_f32 v31, -v31, v43, v42
	v_div_fmas_f32 v31, v31, v33, v43
	v_div_fixup_f32 v30, v31, v30, 2.0
	v_sub_f32_e32 v30, 1.0, v30
	v_add_f32_e32 v30, 1.0, v30
	v_mul_f32_e32 v33, v26, v30
	v_and_b32_e32 v26, 0xffff0000, v27
	v_lshlrev_b32_e32 v27, 16, v27
	v_mul_f32_e32 v30, 0x3d372713, v27
	v_mul_f32_e32 v30, v30, v27
	v_mov_b32_e32 v31, v27
	v_fmac_f32_e32 v31, v30, v31
	v_mul_f32_e32 v30, 0x3f4c422a, v31
	v_add_f32_e32 v30, v30, v30
	v_mul_f32_e32 v30, 0x3fb8aa3b, v30
	v_exp_f32_e32 v31, v30
	v_mul_f32_e32 v30, 0x3d372713, v26
	v_mul_f32_e32 v30, v30, v26
	v_mov_b32_e32 v43, v26
	v_fmac_f32_e32 v43, v30, v43
	v_mul_f32_e32 v30, 0x3f4c422a, v43
	v_add_f32_e32 v30, v30, v30
	v_mul_f32_e32 v30, 0x3fb8aa3b, v30
	v_exp_f32_e32 v30, v30
	v_pk_mul_f32 v[26:27], v[26:27], 0.5 op_sel_hi:[1,0]
	v_mul_f32_e32 v42, v37, v37
	v_fmac_f32_e32 v42, v36, v36
	v_pk_add_f32 v[30:31], v[30:31], 1.0 op_sel_hi:[1,0]
	s_nop 0
	v_div_scale_f32 v43, s[14:15], v31, v31, 2.0
	v_rcp_f32_e32 v44, v43
	s_nop 0
	v_fma_f32 v45, -v43, v44, 1.0
	v_fmac_f32_e32 v44, v45, v44
	v_div_scale_f32 v45, vcc, 2.0, v31, 2.0
	v_mul_f32_e32 v46, v45, v44
	v_fma_f32 v47, -v43, v46, v45
	v_fmac_f32_e32 v46, v47, v44
	v_fma_f32 v43, -v43, v46, v45
	v_div_fmas_f32 v43, v43, v44, v46
	v_div_fixup_f32 v31, v43, v31, 2.0
	v_div_scale_f32 v43, s[14:15], v30, v30, 2.0
	v_rcp_f32_e32 v44, v43
	s_nop 0
	v_fma_f32 v45, -v43, v44, 1.0
	v_fmac_f32_e32 v44, v45, v44
	v_div_scale_f32 v45, vcc, 2.0, v30, 2.0
	v_mul_f32_e32 v46, v45, v44
	v_fma_f32 v47, -v43, v46, v45
	v_fmac_f32_e32 v46, v47, v44
	v_fma_f32 v43, -v43, v46, v45
	v_div_fmas_f32 v43, v43, v44, v46
	v_div_fixup_f32 v30, v43, v30, 2.0
	v_pk_add_f32 v[30:31], v[30:31], 1.0 op_sel_hi:[1,0] neg_lo:[1,0] neg_hi:[1,0]
	s_nop 0
	v_pk_add_f32 v[30:31], v[30:31], 1.0 op_sel_hi:[1,0]
	s_nop 0
	v_pk_mul_f32 v[26:27], v[26:27], v[30:31]
	s_nop 0
	v_pk_mul_f32 v[30:31], v[26:27], v[26:27]
	s_nop 0
	v_add_f32_e32 v31, v31, v42
	v_add_f32_e32 v44, v30, v31
	v_lshlrev_b32_e32 v31, 16, v28
	v_and_b32_e32 v30, 0xffff0000, v28
	v_mul_f32_e32 v28, 0x3d372713, v31
	v_mul_f32_e32 v28, v28, v31
	v_mov_b32_e32 v42, v31
	v_fmac_f32_e32 v42, v28, v42
	v_mul_f32_e32 v28, 0x3f4c422a, v42
	v_add_f32_e32 v28, v28, v28
	v_mul_f32_e32 v28, 0x3fb8aa3b, v28
	v_exp_f32_e32 v43, v28
	v_mul_f32_e32 v28, 0x3d372713, v30
	v_mul_f32_e32 v28, v28, v30
	v_mov_b32_e32 v42, v30
	v_fmac_f32_e32 v42, v28, v42
	v_mul_f32_e32 v28, 0x3f4c422a, v42
	v_add_f32_e32 v28, v28, v28
	v_mul_f32_e32 v28, 0x3fb8aa3b, v28
	v_exp_f32_e32 v42, v28
	v_pk_mul_f32 v[30:31], v[30:31], 0.5 op_sel_hi:[1,0]
	v_pk_add_f32 v[42:43], v[42:43], 1.0 op_sel_hi:[1,0]
	s_nop 0
	v_div_scale_f32 v28, s[14:15], v43, v43, 2.0
	v_rcp_f32_e32 v45, v28
	s_nop 0
	v_fma_f32 v46, -v28, v45, 1.0
	v_fmac_f32_e32 v45, v46, v45
	v_div_scale_f32 v46, vcc, 2.0, v43, 2.0
	v_mul_f32_e32 v47, v46, v45
	v_fma_f32 v48, -v28, v47, v46
	v_fmac_f32_e32 v47, v48, v45
	v_fma_f32 v28, -v28, v47, v46
	v_div_fmas_f32 v28, v28, v45, v47
	v_div_fixup_f32 v43, v28, v43, 2.0
	v_div_scale_f32 v28, s[14:15], v42, v42, 2.0
	v_rcp_f32_e32 v45, v28
	s_nop 0
	v_fma_f32 v46, -v28, v45, 1.0
	v_fmac_f32_e32 v45, v46, v45
	v_div_scale_f32 v46, vcc, 2.0, v42, 2.0
	v_mul_f32_e32 v47, v46, v45
	v_fma_f32 v48, -v28, v47, v46
	v_fmac_f32_e32 v47, v48, v45
	v_fma_f32 v28, -v28, v47, v46
	v_div_fmas_f32 v28, v28, v45, v47
	v_div_fixup_f32 v42, v28, v42, 2.0
	v_pk_add_f32 v[42:43], v[42:43], 1.0 op_sel_hi:[1,0] neg_lo:[1,0] neg_hi:[1,0]
	s_nop 0
	v_pk_add_f32 v[42:43], v[42:43], 1.0 op_sel_hi:[1,0]
	s_nop 0
	v_pk_mul_f32 v[30:31], v[30:31], v[42:43]
	s_nop 0
	v_pk_mul_f32 v[42:43], v[30:31], v[30:31]
	s_nop 0
	v_add_f32_e32 v28, v43, v44
	v_add_f32_e32 v44, v42, v28
	v_and_b32_e32 v28, 0xffff0000, v29
	v_lshlrev_b32_e32 v29, 16, v29
	v_mul_f32_e32 v42, 0x3d372713, v29
	v_mul_f32_e32 v42, v42, v29
	v_mov_b32_e32 v43, v29
	v_fmac_f32_e32 v43, v42, v43
	v_mul_f32_e32 v42, 0x3f4c422a, v43
	v_add_f32_e32 v42, v42, v42
	v_mul_f32_e32 v42, 0x3fb8aa3b, v42
	v_exp_f32_e32 v43, v42
	v_mul_f32_e32 v42, 0x3d372713, v28
	v_mul_f32_e32 v42, v42, v28
	v_mov_b32_e32 v45, v28
	v_fmac_f32_e32 v45, v42, v45
	v_mul_f32_e32 v42, 0x3f4c422a, v45
	v_add_f32_e32 v42, v42, v42
	v_mul_f32_e32 v42, 0x3fb8aa3b, v42
	v_exp_f32_e32 v42, v42
	v_pk_mul_f32 v[28:29], v[28:29], 0.5 op_sel_hi:[1,0]
	v_pk_add_f32 v[42:43], v[42:43], 1.0 op_sel_hi:[1,0]
	s_nop 0
	v_div_scale_f32 v45, s[14:15], v43, v43, 2.0
	v_rcp_f32_e32 v46, v45
	s_nop 0
	v_fma_f32 v47, -v45, v46, 1.0
	v_fmac_f32_e32 v46, v47, v46
	v_div_scale_f32 v47, vcc, 2.0, v43, 2.0
	v_mul_f32_e32 v48, v47, v46
	v_fma_f32 v49, -v45, v48, v47
	v_fmac_f32_e32 v48, v49, v46
	v_fma_f32 v45, -v45, v48, v47
	v_div_fmas_f32 v45, v45, v46, v48
	v_div_fixup_f32 v43, v45, v43, 2.0
	v_div_scale_f32 v45, s[14:15], v42, v42, 2.0
	v_rcp_f32_e32 v46, v45
	s_nop 0
	v_fma_f32 v47, -v45, v46, 1.0
	v_fmac_f32_e32 v46, v47, v46
	v_div_scale_f32 v47, vcc, 2.0, v42, 2.0
	v_mul_f32_e32 v48, v47, v46
	v_fma_f32 v49, -v45, v48, v47
	v_fmac_f32_e32 v48, v49, v46
	v_fma_f32 v45, -v45, v48, v47
	v_div_fmas_f32 v45, v45, v46, v48
	v_div_fixup_f32 v42, v45, v42, 2.0
	v_pk_add_f32 v[42:43], v[42:43], 1.0 op_sel_hi:[1,0] neg_lo:[1,0] neg_hi:[1,0]
	s_nop 0
	v_pk_add_f32 v[42:43], v[42:43], 1.0 op_sel_hi:[1,0]
	s_nop 0
	v_pk_mul_f32 v[42:43], v[28:29], v[42:43]
	s_nop 0
	v_pk_mul_f32 v[28:29], v[42:43], v[42:43]
	s_nop 0
	v_add_f32_e32 v29, v29, v44
	v_add_f32_e32 v28, v28, v29
	s_nop 1
	v_mov_b32_dpp v29, v28 quad_perm:[1,0,3,2] row_mask:0xf bank_mask:0xf
	s_waitcnt lgkmcnt(0)
	v_add_f32_e32 v28, v28, v29
	s_nop 1
	v_mov_b32_dpp v29, v28 quad_perm:[2,3,0,1] row_mask:0xf bank_mask:0xf
	s_waitcnt lgkmcnt(0)
	v_add_f32_e32 v28, v28, v29
	s_nop 1
	v_mov_b32_dpp v29, v28 row_half_mirror row_mask:0xf bank_mask:0xf
	s_waitcnt lgkmcnt(0)
	v_add_f32_e32 v28, v28, v29
	s_nop 1
	v_mov_b32_dpp v29, v28 row_mirror row_mask:0xf bank_mask:0xf
	s_waitcnt lgkmcnt(0)
	v_add_f32_e32 v28, v28, v29
	ds_bpermute_b32 v29, v110, v28
	s_waitcnt lgkmcnt(0)
	v_add_f32_e32 v28, v28, v29
	v_fmamk_f32 v28, v28, 0x3b800000, v243
	v_cmp_gt_f32_e32 vcc, s3, v28
	v_mul_f32_e32 v29, 0x4b800000, v28
	s_nop 0
	v_cndmask_b32_e32 v28, v28, v29, vcc
	v_rsq_f32_e32 v28, v28
	s_nop 0
	v_mul_f32_e32 v29, 0x45800000, v28
	v_cndmask_b32_e32 v44, v28, v29, vcc
	v_mul_f32_e32 v28, v36, v44
	v_mul_f32_e32 v29, v37, v44
	v_mul_f32_e32 v26, v26, v44
	v_mul_f32_e32 v28, v70, v28
	v_mul_f32_e32 v29, v71, v29
	v_mul_f32_e32 v27, v27, v44
	v_mul_f32_e32 v26, v73, v26
	v_cvt_pk_bf16_f32 v28, v28, v29
	v_cvt_pk_bf16_f32 v35, v38, v39
	v_mul_f32_e32 v27, v72, v27
	v_cvt_pk_bf16_f32 v29, v27, v26
	v_mul_f32_e32 v26, v31, v44
	v_mul_f32_e32 v26, v66, v26
	v_mul_f32_e32 v27, v30, v44
	v_cvt_pk_bf16_f32 v36, v40, v32
	v_mul_f32_e32 v27, v67, v27
	v_cvt_pk_bf16_f32 v30, v26, v27
	v_mul_f32_e32 v26, v43, v44
	v_mul_f32_e32 v26, v68, v26
	v_mul_f32_e32 v27, v42, v44
	v_cvt_pk_bf16_f32 v37, v41, v33
	v_mul_f32_e32 v27, v69, v27
	v_cvt_pk_bf16_f32 v31, v26, v27
	v_lshlrev_b32_e32 v26, 16, v22
	v_mul_f32_e32 v27, 0x3d372713, v26
	v_mul_f32_e32 v27, v27, v26
	v_fma_f32 v27, v27, v26, v26
	v_mul_f32_e32 v27, 0x3f4c422a, v27
	v_add_f32_e32 v27, v27, v27
	v_mul_f32_e32 v27, 0x3fb8aa3b, v27
	v_exp_f32_e32 v27, v27
	ds_write_b128 v111, v[34:37] offset:34816
	ds_write_b128 v112, v[28:31] offset:34816
	v_mul_f32_e32 v26, 0.5, v26
	v_and_b32_e32 v22, 0xffff0000, v22
	v_add_f32_e32 v27, 1.0, v27
	v_div_scale_f32 v28, s[14:15], v27, v27, 2.0
	v_rcp_f32_e32 v29, v28
	s_nop 0
	v_fma_f32 v30, -v28, v29, 1.0
	v_fmac_f32_e32 v29, v30, v29
	v_div_scale_f32 v30, vcc, 2.0, v27, 2.0
	v_mul_f32_e32 v31, v30, v29
	v_fma_f32 v32, -v28, v31, v30
	v_fmac_f32_e32 v31, v32, v29
	v_fma_f32 v28, -v28, v31, v30
	v_div_fmas_f32 v28, v28, v29, v31
	v_div_fixup_f32 v27, v28, v27, 2.0
	v_sub_f32_e32 v27, 1.0, v27
	v_add_f32_e32 v27, 1.0, v27
	v_mul_f32_e32 v26, v26, v27
	v_mul_f32_e32 v27, 0x3d372713, v22
	v_mul_f32_e32 v27, v27, v22
	v_fma_f32 v27, v27, v22, v22
	v_mul_f32_e32 v27, 0x3f4c422a, v27
	v_add_f32_e32 v27, v27, v27
	v_mul_f32_e32 v27, 0x3fb8aa3b, v27
	v_exp_f32_e32 v27, v27
	v_mul_f32_e32 v22, 0.5, v22
	v_add_f32_e32 v27, 1.0, v27
	v_div_scale_f32 v28, s[14:15], v27, v27, 2.0
	v_rcp_f32_e32 v29, v28
	s_nop 0
	v_fma_f32 v30, -v28, v29, 1.0
	v_fmac_f32_e32 v29, v30, v29
	v_div_scale_f32 v30, vcc, 2.0, v27, 2.0
	v_mul_f32_e32 v31, v30, v29
	v_fma_f32 v32, -v28, v31, v30
	v_fmac_f32_e32 v31, v32, v29
	v_fma_f32 v28, -v28, v31, v30
	v_div_fmas_f32 v28, v28, v29, v31
	v_div_fixup_f32 v27, v28, v27, 2.0
	v_sub_f32_e32 v27, 1.0, v27
	v_add_f32_e32 v27, 1.0, v27
	v_mul_f32_e32 v27, v22, v27
	v_lshlrev_b32_e32 v22, 16, v18
	v_mul_f32_e32 v28, 0x3d372713, v22
	v_mul_f32_e32 v28, v28, v22
	v_fma_f32 v28, v28, v22, v22
	v_mul_f32_e32 v28, 0x3f4c422a, v28
	v_add_f32_e32 v28, v28, v28
	v_mul_f32_e32 v28, 0x3fb8aa3b, v28
	v_exp_f32_e32 v28, v28
	v_mul_f32_e32 v22, 0.5, v22
	v_and_b32_e32 v18, 0xffff0000, v18
	v_cvt_pk_bf16_f32 v26, v26, v27
	v_add_f32_e32 v28, 1.0, v28
	v_div_scale_f32 v29, s[14:15], v28, v28, 2.0
	v_rcp_f32_e32 v30, v29
	s_nop 0
	v_fma_f32 v31, -v29, v30, 1.0
	v_fmac_f32_e32 v30, v31, v30
	v_div_scale_f32 v31, vcc, 2.0, v28, 2.0
	v_mul_f32_e32 v32, v31, v30
	v_fma_f32 v33, -v29, v32, v31
	v_fmac_f32_e32 v32, v33, v30
	v_fma_f32 v29, -v29, v32, v31
	v_div_fmas_f32 v29, v29, v30, v32
	v_div_fixup_f32 v28, v29, v28, 2.0
	v_sub_f32_e32 v28, 1.0, v28
	v_add_f32_e32 v28, 1.0, v28
	v_mul_f32_e32 v28, v22, v28
	v_mul_f32_e32 v22, 0x3d372713, v18
	v_mul_f32_e32 v22, v22, v18
	v_fma_f32 v22, v22, v18, v18
	v_mul_f32_e32 v22, 0x3f4c422a, v22
	v_add_f32_e32 v22, v22, v22
	v_mul_f32_e32 v22, 0x3fb8aa3b, v22
	v_exp_f32_e32 v22, v22
	v_mul_f32_e32 v18, 0.5, v18
	v_add_f32_e32 v22, 1.0, v22
	v_div_scale_f32 v29, s[14:15], v22, v22, 2.0
	v_rcp_f32_e32 v30, v29
	s_nop 0
	v_fma_f32 v31, -v29, v30, 1.0
	v_fmac_f32_e32 v30, v31, v30
	v_div_scale_f32 v31, vcc, 2.0, v22, 2.0
	v_mul_f32_e32 v32, v31, v30
	v_fma_f32 v33, -v29, v32, v31
	v_fmac_f32_e32 v32, v33, v30
	v_fma_f32 v29, -v29, v32, v31
	v_div_fmas_f32 v29, v29, v30, v32
	v_div_fixup_f32 v22, v29, v22, 2.0
	v_sub_f32_e32 v22, 1.0, v22
	v_add_f32_e32 v22, 1.0, v22
	v_mul_f32_e32 v29, v18, v22
	v_lshlrev_b32_e32 v18, 16, v23
	v_mul_f32_e32 v22, 0x3d372713, v18
	v_mul_f32_e32 v22, v22, v18
	v_fma_f32 v22, v22, v18, v18
	v_mul_f32_e32 v22, 0x3f4c422a, v22
	v_add_f32_e32 v22, v22, v22
	v_mul_f32_e32 v22, 0x3fb8aa3b, v22
	v_exp_f32_e32 v22, v22
	v_mul_f32_e32 v18, 0.5, v18
	v_add_f32_e32 v22, 1.0, v22
	v_div_scale_f32 v30, s[14:15], v22, v22, 2.0
	v_rcp_f32_e32 v31, v30
	s_nop 0
	v_fma_f32 v32, -v30, v31, 1.0
	v_fmac_f32_e32 v31, v32, v31
	v_div_scale_f32 v32, vcc, 2.0, v22, 2.0
	v_mul_f32_e32 v33, v32, v31
	v_fma_f32 v34, -v30, v33, v32
	v_fmac_f32_e32 v33, v34, v31
	v_fma_f32 v30, -v30, v33, v32
	v_div_fmas_f32 v30, v30, v31, v33
	v_div_fixup_f32 v22, v30, v22, 2.0
	v_sub_f32_e32 v22, 1.0, v22
	v_add_f32_e32 v22, 1.0, v22
	v_mul_f32_e32 v30, v18, v22
	v_and_b32_e32 v18, 0xffff0000, v23
	v_mul_f32_e32 v22, 0x3d372713, v18
	v_mul_f32_e32 v22, v22, v18
	v_fma_f32 v22, v22, v18, v18
	v_mul_f32_e32 v22, 0x3f4c422a, v22
	v_add_f32_e32 v22, v22, v22
	v_mul_f32_e32 v22, 0x3fb8aa3b, v22
	v_exp_f32_e32 v22, v22
	v_mul_f32_e32 v18, 0.5, v18
	v_add_f32_e32 v22, 1.0, v22
	v_div_scale_f32 v23, s[14:15], v22, v22, 2.0
	v_rcp_f32_e32 v31, v23
	s_nop 0
	v_fma_f32 v32, -v23, v31, 1.0
	v_fmac_f32_e32 v31, v32, v31
	v_div_scale_f32 v32, vcc, 2.0, v22, 2.0
	v_mul_f32_e32 v33, v32, v31
	v_fma_f32 v34, -v23, v33, v32
	v_fmac_f32_e32 v33, v34, v31
	v_fma_f32 v23, -v23, v33, v32
	v_div_fmas_f32 v23, v23, v31, v33
	v_div_fixup_f32 v22, v23, v22, 2.0
	v_sub_f32_e32 v22, 1.0, v22
	v_add_f32_e32 v22, 1.0, v22
	v_mul_f32_e32 v31, v18, v22
	v_lshlrev_b32_e32 v18, 16, v24
	v_mul_f32_e32 v22, 0x3d372713, v18
	v_mul_f32_e32 v22, v22, v18
	v_fma_f32 v22, v22, v18, v18
	v_mul_f32_e32 v22, 0x3f4c422a, v22
	v_add_f32_e32 v22, v22, v22
	v_mul_f32_e32 v22, 0x3fb8aa3b, v22
	v_exp_f32_e32 v22, v22
	v_mul_f32_e32 v18, 0.5, v18
	v_add_f32_e32 v22, 1.0, v22
	v_div_scale_f32 v23, s[14:15], v22, v22, 2.0
	v_rcp_f32_e32 v32, v23
	s_nop 0
	v_fma_f32 v33, -v23, v32, 1.0
	v_fmac_f32_e32 v32, v33, v32
	v_div_scale_f32 v33, vcc, 2.0, v22, 2.0
	v_mul_f32_e32 v34, v33, v32
	v_fma_f32 v35, -v23, v34, v33
	v_fmac_f32_e32 v34, v35, v32
	v_fma_f32 v23, -v23, v34, v33
	v_div_fmas_f32 v23, v23, v32, v34
	v_div_fixup_f32 v22, v23, v22, 2.0
	v_sub_f32_e32 v22, 1.0, v22
	v_add_f32_e32 v22, 1.0, v22
	v_mul_f32_e32 v32, v18, v22
	v_and_b32_e32 v18, 0xffff0000, v24
	v_mul_f32_e32 v22, 0x3d372713, v18
	v_mul_f32_e32 v22, v22, v18
	v_fma_f32 v22, v22, v18, v18
	v_mul_f32_e32 v22, 0x3f4c422a, v22
	v_add_f32_e32 v22, v22, v22
	v_mul_f32_e32 v22, 0x3fb8aa3b, v22
	v_exp_f32_e32 v22, v22
	v_mul_f32_e32 v18, 0.5, v18
	v_add_f32_e32 v22, 1.0, v22
	v_div_scale_f32 v23, s[14:15], v22, v22, 2.0
	v_rcp_f32_e32 v24, v23
	s_nop 0
	v_fma_f32 v33, -v23, v24, 1.0
	v_fmac_f32_e32 v24, v33, v24
	v_div_scale_f32 v33, vcc, 2.0, v22, 2.0
	v_mul_f32_e32 v34, v33, v24
	v_fma_f32 v35, -v23, v34, v33
	v_fmac_f32_e32 v34, v35, v24
	v_fma_f32 v23, -v23, v34, v33
	v_div_fmas_f32 v23, v23, v24, v34
	v_div_fixup_f32 v22, v23, v22, 2.0
	v_sub_f32_e32 v22, 1.0, v22
	v_add_f32_e32 v22, 1.0, v22
	v_mul_f32_e32 v24, v18, v22
	v_lshlrev_b32_e32 v18, 16, v25
	v_mul_f32_e32 v22, 0x3d372713, v18
	v_mul_f32_e32 v22, v22, v18
	v_fma_f32 v22, v22, v18, v18
	v_mul_f32_e32 v22, 0x3f4c422a, v22
	v_add_f32_e32 v22, v22, v22
	v_mul_f32_e32 v22, 0x3fb8aa3b, v22
	v_exp_f32_e32 v22, v22
	v_mul_f32_e32 v18, 0.5, v18
	v_add_f32_e32 v22, 1.0, v22
	v_div_scale_f32 v23, s[14:15], v22, v22, 2.0
	v_rcp_f32_e32 v33, v23
	s_nop 0
	v_fma_f32 v34, -v23, v33, 1.0
	v_fmac_f32_e32 v33, v34, v33
	v_div_scale_f32 v34, vcc, 2.0, v22, 2.0
	v_mul_f32_e32 v35, v34, v33
	v_fma_f32 v36, -v23, v35, v34
	v_fmac_f32_e32 v35, v36, v33
	v_fma_f32 v23, -v23, v35, v34
	v_div_fmas_f32 v23, v23, v33, v35
	v_div_fixup_f32 v22, v23, v22, 2.0
	v_sub_f32_e32 v22, 1.0, v22
	v_add_f32_e32 v22, 1.0, v22
	v_mul_f32_e32 v33, v18, v22
	v_and_b32_e32 v18, 0xffff0000, v25
	v_mul_f32_e32 v22, 0x3d372713, v18
	v_mul_f32_e32 v22, v22, v18
	v_fma_f32 v22, v22, v18, v18
	v_mul_f32_e32 v22, 0x3f4c422a, v22
	v_add_f32_e32 v22, v22, v22
	v_mul_f32_e32 v22, 0x3fb8aa3b, v22
	v_exp_f32_e32 v22, v22
	v_mul_f32_e32 v18, 0.5, v18
	v_add_f32_e32 v22, 1.0, v22
	v_div_scale_f32 v23, s[14:15], v22, v22, 2.0
	v_rcp_f32_e32 v25, v23
	s_nop 0
	v_fma_f32 v34, -v23, v25, 1.0
	v_fmac_f32_e32 v25, v34, v25
	v_div_scale_f32 v34, vcc, 2.0, v22, 2.0
	v_mul_f32_e32 v35, v34, v25
	v_fma_f32 v36, -v23, v35, v34
	v_fmac_f32_e32 v35, v36, v25
	v_fma_f32 v23, -v23, v35, v34
	v_div_fmas_f32 v23, v23, v25, v35
	v_div_fixup_f32 v22, v23, v22, 2.0
	v_sub_f32_e32 v22, 1.0, v22
	v_add_f32_e32 v22, 1.0, v22
	v_mul_f32_e32 v25, v18, v22
	v_and_b32_e32 v18, 0xffff0000, v19
	v_lshlrev_b32_e32 v19, 16, v19
	v_mul_f32_e32 v22, 0x3d372713, v19
	v_mul_f32_e32 v22, v22, v19
	v_mov_b32_e32 v23, v19
	v_fmac_f32_e32 v23, v22, v23
	v_mul_f32_e32 v22, 0x3f4c422a, v23
	v_add_f32_e32 v22, v22, v22
	v_mul_f32_e32 v22, 0x3fb8aa3b, v22
	v_exp_f32_e32 v23, v22
	v_mul_f32_e32 v22, 0x3d372713, v18
	v_mul_f32_e32 v22, v22, v18
	v_mov_b32_e32 v35, v18
	v_fmac_f32_e32 v35, v22, v35
	v_mul_f32_e32 v22, 0x3f4c422a, v35
	v_add_f32_e32 v22, v22, v22
	v_mul_f32_e32 v22, 0x3fb8aa3b, v22
	v_exp_f32_e32 v22, v22
	v_pk_mul_f32 v[18:19], v[18:19], 0.5 op_sel_hi:[1,0]
	v_mul_f32_e32 v34, v29, v29
	v_fmac_f32_e32 v34, v28, v28
	v_pk_add_f32 v[22:23], v[22:23], 1.0 op_sel_hi:[1,0]
	s_nop 0
	v_div_scale_f32 v35, s[14:15], v23, v23, 2.0
	v_rcp_f32_e32 v36, v35
	s_nop 0
	v_fma_f32 v37, -v35, v36, 1.0
	v_fmac_f32_e32 v36, v37, v36
	v_div_scale_f32 v37, vcc, 2.0, v23, 2.0
	v_mul_f32_e32 v38, v37, v36
	v_fma_f32 v39, -v35, v38, v37
	v_fmac_f32_e32 v38, v39, v36
	v_fma_f32 v35, -v35, v38, v37
	v_div_fmas_f32 v35, v35, v36, v38
	v_div_fixup_f32 v23, v35, v23, 2.0
	v_div_scale_f32 v35, s[14:15], v22, v22, 2.0
	v_rcp_f32_e32 v36, v35
	s_nop 0
	v_fma_f32 v37, -v35, v36, 1.0
	v_fmac_f32_e32 v36, v37, v36
	v_div_scale_f32 v37, vcc, 2.0, v22, 2.0
	v_mul_f32_e32 v38, v37, v36
	v_fma_f32 v39, -v35, v38, v37
	v_fmac_f32_e32 v38, v39, v36
	v_fma_f32 v35, -v35, v38, v37
	v_div_fmas_f32 v35, v35, v36, v38
	v_div_fixup_f32 v22, v35, v22, 2.0
	v_pk_add_f32 v[22:23], v[22:23], 1.0 op_sel_hi:[1,0] neg_lo:[1,0] neg_hi:[1,0]
	s_nop 0
	v_pk_add_f32 v[22:23], v[22:23], 1.0 op_sel_hi:[1,0]
	s_nop 0
	v_pk_mul_f32 v[18:19], v[18:19], v[22:23]
	s_nop 0
	v_pk_mul_f32 v[22:23], v[18:19], v[18:19]
	s_nop 0
	v_add_f32_e32 v23, v23, v34
	v_add_f32_e32 v36, v22, v23
	v_lshlrev_b32_e32 v23, 16, v20
	v_and_b32_e32 v22, 0xffff0000, v20
	v_mul_f32_e32 v20, 0x3d372713, v23
	v_mul_f32_e32 v20, v20, v23
	v_mov_b32_e32 v34, v23
	v_fmac_f32_e32 v34, v20, v34
	v_mul_f32_e32 v20, 0x3f4c422a, v34
	v_add_f32_e32 v20, v20, v20
	v_mul_f32_e32 v20, 0x3fb8aa3b, v20
	v_exp_f32_e32 v35, v20
	v_mul_f32_e32 v20, 0x3d372713, v22
	v_mul_f32_e32 v20, v20, v22
	v_mov_b32_e32 v34, v22
	v_fmac_f32_e32 v34, v20, v34
	v_mul_f32_e32 v20, 0x3f4c422a, v34
	v_add_f32_e32 v20, v20, v20
	v_mul_f32_e32 v20, 0x3fb8aa3b, v20
	v_exp_f32_e32 v34, v20
	v_pk_mul_f32 v[22:23], v[22:23], 0.5 op_sel_hi:[1,0]
	v_pk_add_f32 v[34:35], v[34:35], 1.0 op_sel_hi:[1,0]
	s_nop 0
	v_div_scale_f32 v20, s[14:15], v35, v35, 2.0
	v_rcp_f32_e32 v37, v20
	s_nop 0
	v_fma_f32 v38, -v20, v37, 1.0
	v_fmac_f32_e32 v37, v38, v37
	v_div_scale_f32 v38, vcc, 2.0, v35, 2.0
	v_mul_f32_e32 v39, v38, v37
	v_fma_f32 v40, -v20, v39, v38
	v_fmac_f32_e32 v39, v40, v37
	v_fma_f32 v20, -v20, v39, v38
	v_div_fmas_f32 v20, v20, v37, v39
	v_div_fixup_f32 v35, v20, v35, 2.0
	v_div_scale_f32 v20, s[14:15], v34, v34, 2.0
	v_rcp_f32_e32 v37, v20
	s_nop 0
	v_fma_f32 v38, -v20, v37, 1.0
	v_fmac_f32_e32 v37, v38, v37
	v_div_scale_f32 v38, vcc, 2.0, v34, 2.0
	v_mul_f32_e32 v39, v38, v37
	v_fma_f32 v40, -v20, v39, v38
	v_fmac_f32_e32 v39, v40, v37
	v_fma_f32 v20, -v20, v39, v38
	v_div_fmas_f32 v20, v20, v37, v39
	v_div_fixup_f32 v34, v20, v34, 2.0
	v_pk_add_f32 v[34:35], v[34:35], 1.0 op_sel_hi:[1,0] neg_lo:[1,0] neg_hi:[1,0]
	s_nop 0
	v_pk_add_f32 v[34:35], v[34:35], 1.0 op_sel_hi:[1,0]
	s_nop 0
	v_pk_mul_f32 v[22:23], v[22:23], v[34:35]
	s_nop 0
	v_pk_mul_f32 v[34:35], v[22:23], v[22:23]
	s_nop 0
	v_add_f32_e32 v20, v35, v36
	v_add_f32_e32 v36, v34, v20
	v_and_b32_e32 v20, 0xffff0000, v21
	v_lshlrev_b32_e32 v21, 16, v21
	v_mul_f32_e32 v34, 0x3d372713, v21
	v_mul_f32_e32 v34, v34, v21
	v_mov_b32_e32 v35, v21
	v_fmac_f32_e32 v35, v34, v35
	v_mul_f32_e32 v34, 0x3f4c422a, v35
	v_add_f32_e32 v34, v34, v34
	v_mul_f32_e32 v34, 0x3fb8aa3b, v34
	v_exp_f32_e32 v35, v34
	v_mul_f32_e32 v34, 0x3d372713, v20
	v_mul_f32_e32 v34, v34, v20
	v_mov_b32_e32 v37, v20
	v_fmac_f32_e32 v37, v34, v37
	v_mul_f32_e32 v34, 0x3f4c422a, v37
	v_add_f32_e32 v34, v34, v34
	v_mul_f32_e32 v34, 0x3fb8aa3b, v34
	v_exp_f32_e32 v34, v34
	v_pk_mul_f32 v[20:21], v[20:21], 0.5 op_sel_hi:[1,0]
	v_pk_add_f32 v[34:35], v[34:35], 1.0 op_sel_hi:[1,0]
	s_nop 0
	v_div_scale_f32 v37, s[14:15], v35, v35, 2.0
	v_rcp_f32_e32 v38, v37
	s_nop 0
	v_fma_f32 v39, -v37, v38, 1.0
	v_fmac_f32_e32 v38, v39, v38
	v_div_scale_f32 v39, vcc, 2.0, v35, 2.0
	v_mul_f32_e32 v40, v39, v38
	v_fma_f32 v41, -v37, v40, v39
	v_fmac_f32_e32 v40, v41, v38
	v_fma_f32 v37, -v37, v40, v39
	v_div_fmas_f32 v37, v37, v38, v40
	v_div_fixup_f32 v35, v37, v35, 2.0
	v_div_scale_f32 v37, s[14:15], v34, v34, 2.0
	v_rcp_f32_e32 v38, v37
	s_nop 0
	v_fma_f32 v39, -v37, v38, 1.0
	v_fmac_f32_e32 v38, v39, v38
	v_div_scale_f32 v39, vcc, 2.0, v34, 2.0
	v_mul_f32_e32 v40, v39, v38
	v_fma_f32 v41, -v37, v40, v39
	v_fmac_f32_e32 v40, v41, v38
	v_fma_f32 v37, -v37, v40, v39
	v_div_fmas_f32 v37, v37, v38, v40
	v_div_fixup_f32 v34, v37, v34, 2.0
	v_pk_add_f32 v[34:35], v[34:35], 1.0 op_sel_hi:[1,0] neg_lo:[1,0] neg_hi:[1,0]
	s_nop 0
	v_pk_add_f32 v[34:35], v[34:35], 1.0 op_sel_hi:[1,0]
	s_nop 0
	v_pk_mul_f32 v[34:35], v[20:21], v[34:35]
	s_nop 0
	v_pk_mul_f32 v[20:21], v[34:35], v[34:35]
	s_nop 0
	v_add_f32_e32 v21, v21, v36
	v_add_f32_e32 v20, v20, v21
	s_nop 1
	v_mov_b32_dpp v21, v20 quad_perm:[1,0,3,2] row_mask:0xf bank_mask:0xf
	s_waitcnt lgkmcnt(0)
	v_add_f32_e32 v20, v20, v21
	s_nop 1
	v_mov_b32_dpp v21, v20 quad_perm:[2,3,0,1] row_mask:0xf bank_mask:0xf
	s_waitcnt lgkmcnt(0)
	v_add_f32_e32 v20, v20, v21
	s_nop 1
	v_mov_b32_dpp v21, v20 row_half_mirror row_mask:0xf bank_mask:0xf
	s_waitcnt lgkmcnt(0)
	v_add_f32_e32 v20, v20, v21
	s_nop 1
	v_mov_b32_dpp v21, v20 row_mirror row_mask:0xf bank_mask:0xf
	s_waitcnt lgkmcnt(0)
	v_add_f32_e32 v20, v20, v21
	ds_bpermute_b32 v21, v110, v20
	s_waitcnt lgkmcnt(0)
	v_add_f32_e32 v20, v20, v21
	v_fmamk_f32 v20, v20, 0x3b800000, v243
	v_cmp_gt_f32_e32 vcc, s3, v20
	v_mul_f32_e32 v21, 0x4b800000, v20
	s_nop 0
	v_cndmask_b32_e32 v20, v20, v21, vcc
	v_rsq_f32_e32 v20, v20
	s_nop 0
	v_mul_f32_e32 v21, 0x45800000, v20
	v_cndmask_b32_e32 v36, v20, v21, vcc
	v_mul_f32_e32 v20, v28, v36
	v_mul_f32_e32 v21, v29, v36
	v_mul_f32_e32 v18, v18, v36
	v_mul_f32_e32 v20, v70, v20
	v_mul_f32_e32 v21, v71, v21
	v_mul_f32_e32 v19, v19, v36
	v_mul_f32_e32 v18, v73, v18
	v_cvt_pk_bf16_f32 v20, v20, v21
	v_cvt_pk_bf16_f32 v27, v30, v31
	v_mul_f32_e32 v19, v72, v19
	v_cvt_pk_bf16_f32 v21, v19, v18
	v_mul_f32_e32 v18, v23, v36
	v_mul_f32_e32 v18, v66, v18
	v_mul_f32_e32 v19, v22, v36
	v_cvt_pk_bf16_f32 v28, v32, v24
	v_mul_f32_e32 v19, v67, v19
	v_cvt_pk_bf16_f32 v22, v18, v19
	v_mul_f32_e32 v18, v35, v36
	v_mul_f32_e32 v18, v68, v18
	v_mul_f32_e32 v19, v34, v36
	v_cvt_pk_bf16_f32 v29, v33, v25
	v_mul_f32_e32 v19, v69, v19
	v_cvt_pk_bf16_f32 v23, v18, v19
	v_lshlrev_b32_e32 v18, 16, v14
	v_mul_f32_e32 v19, 0x3d372713, v18
	v_mul_f32_e32 v19, v19, v18
	v_fma_f32 v19, v19, v18, v18
	v_mul_f32_e32 v19, 0x3f4c422a, v19
	v_add_f32_e32 v19, v19, v19
	v_mul_f32_e32 v19, 0x3fb8aa3b, v19
	v_exp_f32_e32 v19, v19
	ds_write_b128 v111, v[26:29] offset:43520
	ds_write_b128 v112, v[20:23] offset:43520
	v_mul_f32_e32 v18, 0.5, v18
	v_and_b32_e32 v14, 0xffff0000, v14
	v_add_f32_e32 v19, 1.0, v19
	v_div_scale_f32 v20, s[14:15], v19, v19, 2.0
	v_rcp_f32_e32 v21, v20
	s_nop 0
	v_fma_f32 v22, -v20, v21, 1.0
	v_fmac_f32_e32 v21, v22, v21
	v_div_scale_f32 v22, vcc, 2.0, v19, 2.0
	v_mul_f32_e32 v23, v22, v21
	v_fma_f32 v24, -v20, v23, v22
	v_fmac_f32_e32 v23, v24, v21
	v_fma_f32 v20, -v20, v23, v22
	v_div_fmas_f32 v20, v20, v21, v23
	v_div_fixup_f32 v19, v20, v19, 2.0
	v_sub_f32_e32 v19, 1.0, v19
	v_add_f32_e32 v19, 1.0, v19
	v_mul_f32_e32 v18, v18, v19
	v_mul_f32_e32 v19, 0x3d372713, v14
	v_mul_f32_e32 v19, v19, v14
	v_fma_f32 v19, v19, v14, v14
	v_mul_f32_e32 v19, 0x3f4c422a, v19
	v_add_f32_e32 v19, v19, v19
	v_mul_f32_e32 v19, 0x3fb8aa3b, v19
	v_exp_f32_e32 v19, v19
	v_mul_f32_e32 v14, 0.5, v14
	v_add_f32_e32 v19, 1.0, v19
	v_div_scale_f32 v20, s[14:15], v19, v19, 2.0
	v_rcp_f32_e32 v21, v20
	s_nop 0
	v_fma_f32 v22, -v20, v21, 1.0
	v_fmac_f32_e32 v21, v22, v21
	v_div_scale_f32 v22, vcc, 2.0, v19, 2.0
	v_mul_f32_e32 v23, v22, v21
	v_fma_f32 v24, -v20, v23, v22
	v_fmac_f32_e32 v23, v24, v21
	v_fma_f32 v20, -v20, v23, v22
	v_div_fmas_f32 v20, v20, v21, v23
	v_div_fixup_f32 v19, v20, v19, 2.0
	v_sub_f32_e32 v19, 1.0, v19
	v_add_f32_e32 v19, 1.0, v19
	v_mul_f32_e32 v19, v14, v19
	v_lshlrev_b32_e32 v14, 16, v10
	v_mul_f32_e32 v20, 0x3d372713, v14
	v_mul_f32_e32 v20, v20, v14
	v_fma_f32 v20, v20, v14, v14
	v_mul_f32_e32 v20, 0x3f4c422a, v20
	v_add_f32_e32 v20, v20, v20
	v_mul_f32_e32 v20, 0x3fb8aa3b, v20
	v_exp_f32_e32 v20, v20
	v_mul_f32_e32 v14, 0.5, v14
	v_and_b32_e32 v10, 0xffff0000, v10
	v_cvt_pk_bf16_f32 v18, v18, v19
	v_add_f32_e32 v20, 1.0, v20
	v_div_scale_f32 v21, s[14:15], v20, v20, 2.0
	v_rcp_f32_e32 v22, v21
	s_nop 0
	v_fma_f32 v23, -v21, v22, 1.0
	v_fmac_f32_e32 v22, v23, v22
	v_div_scale_f32 v23, vcc, 2.0, v20, 2.0
	v_mul_f32_e32 v24, v23, v22
	v_fma_f32 v25, -v21, v24, v23
	v_fmac_f32_e32 v24, v25, v22
	v_fma_f32 v21, -v21, v24, v23
	v_div_fmas_f32 v21, v21, v22, v24
	v_div_fixup_f32 v20, v21, v20, 2.0
	v_sub_f32_e32 v20, 1.0, v20
	v_add_f32_e32 v20, 1.0, v20
	v_mul_f32_e32 v20, v14, v20
	v_mul_f32_e32 v14, 0x3d372713, v10
	v_mul_f32_e32 v14, v14, v10
	v_fma_f32 v14, v14, v10, v10
	v_mul_f32_e32 v14, 0x3f4c422a, v14
	v_add_f32_e32 v14, v14, v14
	v_mul_f32_e32 v14, 0x3fb8aa3b, v14
	v_exp_f32_e32 v14, v14
	v_mul_f32_e32 v10, 0.5, v10
	v_add_f32_e32 v14, 1.0, v14
	v_div_scale_f32 v21, s[14:15], v14, v14, 2.0
	v_rcp_f32_e32 v22, v21
	s_nop 0
	v_fma_f32 v23, -v21, v22, 1.0
	v_fmac_f32_e32 v22, v23, v22
	v_div_scale_f32 v23, vcc, 2.0, v14, 2.0
	v_mul_f32_e32 v24, v23, v22
	v_fma_f32 v25, -v21, v24, v23
	v_fmac_f32_e32 v24, v25, v22
	v_fma_f32 v21, -v21, v24, v23
	v_div_fmas_f32 v21, v21, v22, v24
	v_div_fixup_f32 v14, v21, v14, 2.0
	v_sub_f32_e32 v14, 1.0, v14
	v_add_f32_e32 v14, 1.0, v14
	v_mul_f32_e32 v21, v10, v14
	v_lshlrev_b32_e32 v10, 16, v15
	v_mul_f32_e32 v14, 0x3d372713, v10
	v_mul_f32_e32 v14, v14, v10
	v_fma_f32 v14, v14, v10, v10
	v_mul_f32_e32 v14, 0x3f4c422a, v14
	v_add_f32_e32 v14, v14, v14
	v_mul_f32_e32 v14, 0x3fb8aa3b, v14
	v_exp_f32_e32 v14, v14
	v_mul_f32_e32 v10, 0.5, v10
	v_add_f32_e32 v14, 1.0, v14
	v_div_scale_f32 v22, s[14:15], v14, v14, 2.0
	v_rcp_f32_e32 v23, v22
	s_nop 0
	v_fma_f32 v24, -v22, v23, 1.0
	v_fmac_f32_e32 v23, v24, v23
	v_div_scale_f32 v24, vcc, 2.0, v14, 2.0
	v_mul_f32_e32 v25, v24, v23
	v_fma_f32 v26, -v22, v25, v24
	v_fmac_f32_e32 v25, v26, v23
	v_fma_f32 v22, -v22, v25, v24
	v_div_fmas_f32 v22, v22, v23, v25
	v_div_fixup_f32 v14, v22, v14, 2.0
	v_sub_f32_e32 v14, 1.0, v14
	v_add_f32_e32 v14, 1.0, v14
	v_mul_f32_e32 v22, v10, v14
	v_and_b32_e32 v10, 0xffff0000, v15
	v_mul_f32_e32 v14, 0x3d372713, v10
	v_mul_f32_e32 v14, v14, v10
	v_fma_f32 v14, v14, v10, v10
	v_mul_f32_e32 v14, 0x3f4c422a, v14
	v_add_f32_e32 v14, v14, v14
	v_mul_f32_e32 v14, 0x3fb8aa3b, v14
	v_exp_f32_e32 v14, v14
	v_mul_f32_e32 v10, 0.5, v10
	v_add_f32_e32 v14, 1.0, v14
	v_div_scale_f32 v15, s[14:15], v14, v14, 2.0
	v_rcp_f32_e32 v23, v15
	s_nop 0
	v_fma_f32 v24, -v15, v23, 1.0
	v_fmac_f32_e32 v23, v24, v23
	v_div_scale_f32 v24, vcc, 2.0, v14, 2.0
	v_mul_f32_e32 v25, v24, v23
	v_fma_f32 v26, -v15, v25, v24
	v_fmac_f32_e32 v25, v26, v23
	v_fma_f32 v15, -v15, v25, v24
	v_div_fmas_f32 v15, v15, v23, v25
	v_div_fixup_f32 v14, v15, v14, 2.0
	v_sub_f32_e32 v14, 1.0, v14
	v_add_f32_e32 v14, 1.0, v14
	v_mul_f32_e32 v23, v10, v14
	v_lshlrev_b32_e32 v10, 16, v16
	v_mul_f32_e32 v14, 0x3d372713, v10
	v_mul_f32_e32 v14, v14, v10
	v_fma_f32 v14, v14, v10, v10
	v_mul_f32_e32 v14, 0x3f4c422a, v14
	v_add_f32_e32 v14, v14, v14
	v_mul_f32_e32 v14, 0x3fb8aa3b, v14
	v_exp_f32_e32 v14, v14
	v_mul_f32_e32 v10, 0.5, v10
	v_add_f32_e32 v14, 1.0, v14
	v_div_scale_f32 v15, s[14:15], v14, v14, 2.0
	v_rcp_f32_e32 v24, v15
	s_nop 0
	v_fma_f32 v25, -v15, v24, 1.0
	v_fmac_f32_e32 v24, v25, v24
	v_div_scale_f32 v25, vcc, 2.0, v14, 2.0
	v_mul_f32_e32 v26, v25, v24
	v_fma_f32 v27, -v15, v26, v25
	v_fmac_f32_e32 v26, v27, v24
	v_fma_f32 v15, -v15, v26, v25
	v_div_fmas_f32 v15, v15, v24, v26
	v_div_fixup_f32 v14, v15, v14, 2.0
	v_sub_f32_e32 v14, 1.0, v14
	v_add_f32_e32 v14, 1.0, v14
	v_mul_f32_e32 v24, v10, v14
	v_and_b32_e32 v10, 0xffff0000, v16
	v_mul_f32_e32 v14, 0x3d372713, v10
	v_mul_f32_e32 v14, v14, v10
	v_fma_f32 v14, v14, v10, v10
	v_mul_f32_e32 v14, 0x3f4c422a, v14
	v_add_f32_e32 v14, v14, v14
	v_mul_f32_e32 v14, 0x3fb8aa3b, v14
	v_exp_f32_e32 v14, v14
	v_mul_f32_e32 v10, 0.5, v10
	v_add_f32_e32 v14, 1.0, v14
	v_div_scale_f32 v15, s[14:15], v14, v14, 2.0
	v_rcp_f32_e32 v16, v15
	s_nop 0
	v_fma_f32 v25, -v15, v16, 1.0
	v_fmac_f32_e32 v16, v25, v16
	v_div_scale_f32 v25, vcc, 2.0, v14, 2.0
	v_mul_f32_e32 v26, v25, v16
	v_fma_f32 v27, -v15, v26, v25
	v_fmac_f32_e32 v26, v27, v16
	v_fma_f32 v15, -v15, v26, v25
	v_div_fmas_f32 v15, v15, v16, v26
	v_div_fixup_f32 v14, v15, v14, 2.0
	v_sub_f32_e32 v14, 1.0, v14
	v_add_f32_e32 v14, 1.0, v14
	v_mul_f32_e32 v16, v10, v14
	v_lshlrev_b32_e32 v10, 16, v17
	v_mul_f32_e32 v14, 0x3d372713, v10
	v_mul_f32_e32 v14, v14, v10
	v_fma_f32 v14, v14, v10, v10
	v_mul_f32_e32 v14, 0x3f4c422a, v14
	v_add_f32_e32 v14, v14, v14
	v_mul_f32_e32 v14, 0x3fb8aa3b, v14
	v_exp_f32_e32 v14, v14
	v_mul_f32_e32 v10, 0.5, v10
	v_add_f32_e32 v14, 1.0, v14
	v_div_scale_f32 v15, s[14:15], v14, v14, 2.0
	v_rcp_f32_e32 v25, v15
	s_nop 0
	v_fma_f32 v26, -v15, v25, 1.0
	v_fmac_f32_e32 v25, v26, v25
	v_div_scale_f32 v26, vcc, 2.0, v14, 2.0
	v_mul_f32_e32 v27, v26, v25
	v_fma_f32 v28, -v15, v27, v26
	v_fmac_f32_e32 v27, v28, v25
	v_fma_f32 v15, -v15, v27, v26
	v_div_fmas_f32 v15, v15, v25, v27
	v_div_fixup_f32 v14, v15, v14, 2.0
	v_sub_f32_e32 v14, 1.0, v14
	v_add_f32_e32 v14, 1.0, v14
	v_mul_f32_e32 v25, v10, v14
	v_and_b32_e32 v10, 0xffff0000, v17
	v_mul_f32_e32 v14, 0x3d372713, v10
	v_mul_f32_e32 v14, v14, v10
	v_fma_f32 v14, v14, v10, v10
	v_mul_f32_e32 v14, 0x3f4c422a, v14
	v_add_f32_e32 v14, v14, v14
	v_mul_f32_e32 v14, 0x3fb8aa3b, v14
	v_exp_f32_e32 v14, v14
	v_mul_f32_e32 v10, 0.5, v10
	v_add_f32_e32 v14, 1.0, v14
	v_div_scale_f32 v15, s[14:15], v14, v14, 2.0
	v_rcp_f32_e32 v17, v15
	s_nop 0
	v_fma_f32 v26, -v15, v17, 1.0
	v_fmac_f32_e32 v17, v26, v17
	v_div_scale_f32 v26, vcc, 2.0, v14, 2.0
	v_mul_f32_e32 v27, v26, v17
	v_fma_f32 v28, -v15, v27, v26
	v_fmac_f32_e32 v27, v28, v17
	v_fma_f32 v15, -v15, v27, v26
	v_div_fmas_f32 v15, v15, v17, v27
	v_div_fixup_f32 v14, v15, v14, 2.0
	v_sub_f32_e32 v14, 1.0, v14
	v_add_f32_e32 v14, 1.0, v14
	v_mul_f32_e32 v17, v10, v14
	v_and_b32_e32 v10, 0xffff0000, v11
	v_lshlrev_b32_e32 v11, 16, v11
	v_mul_f32_e32 v14, 0x3d372713, v11
	v_mul_f32_e32 v14, v14, v11
	v_mov_b32_e32 v15, v11
	v_fmac_f32_e32 v15, v14, v15
	v_mul_f32_e32 v14, 0x3f4c422a, v15
	v_add_f32_e32 v14, v14, v14
	v_mul_f32_e32 v14, 0x3fb8aa3b, v14
	v_exp_f32_e32 v15, v14
	v_mul_f32_e32 v14, 0x3d372713, v10
	v_mul_f32_e32 v14, v14, v10
	v_mov_b32_e32 v27, v10
	v_fmac_f32_e32 v27, v14, v27
	v_mul_f32_e32 v14, 0x3f4c422a, v27
	v_add_f32_e32 v14, v14, v14
	v_mul_f32_e32 v14, 0x3fb8aa3b, v14
	v_exp_f32_e32 v14, v14
	v_pk_mul_f32 v[10:11], v[10:11], 0.5 op_sel_hi:[1,0]
	v_mul_f32_e32 v26, v21, v21
	v_fmac_f32_e32 v26, v20, v20
	v_pk_add_f32 v[14:15], v[14:15], 1.0 op_sel_hi:[1,0]
	s_nop 0
	v_div_scale_f32 v27, s[14:15], v15, v15, 2.0
	v_rcp_f32_e32 v28, v27
	s_nop 0
	v_fma_f32 v29, -v27, v28, 1.0
	v_fmac_f32_e32 v28, v29, v28
	v_div_scale_f32 v29, vcc, 2.0, v15, 2.0
	v_mul_f32_e32 v30, v29, v28
	v_fma_f32 v31, -v27, v30, v29
	v_fmac_f32_e32 v30, v31, v28
	v_fma_f32 v27, -v27, v30, v29
	v_div_fmas_f32 v27, v27, v28, v30
	v_div_fixup_f32 v15, v27, v15, 2.0
	v_div_scale_f32 v27, s[14:15], v14, v14, 2.0
	v_rcp_f32_e32 v28, v27
	s_nop 0
	v_fma_f32 v29, -v27, v28, 1.0
	v_fmac_f32_e32 v28, v29, v28
	v_div_scale_f32 v29, vcc, 2.0, v14, 2.0
	v_mul_f32_e32 v30, v29, v28
	v_fma_f32 v31, -v27, v30, v29
	v_fmac_f32_e32 v30, v31, v28
	v_fma_f32 v27, -v27, v30, v29
	v_div_fmas_f32 v27, v27, v28, v30
	v_div_fixup_f32 v14, v27, v14, 2.0
	v_pk_add_f32 v[14:15], v[14:15], 1.0 op_sel_hi:[1,0] neg_lo:[1,0] neg_hi:[1,0]
	s_nop 0
	v_pk_add_f32 v[14:15], v[14:15], 1.0 op_sel_hi:[1,0]
	s_nop 0
	v_pk_mul_f32 v[10:11], v[10:11], v[14:15]
	s_nop 0
	v_pk_mul_f32 v[14:15], v[10:11], v[10:11]
	s_nop 0
	v_add_f32_e32 v15, v15, v26
	v_add_f32_e32 v28, v14, v15
	v_lshlrev_b32_e32 v15, 16, v12
	v_and_b32_e32 v14, 0xffff0000, v12
	v_mul_f32_e32 v12, 0x3d372713, v15
	v_mul_f32_e32 v12, v12, v15
	v_mov_b32_e32 v26, v15
	v_fmac_f32_e32 v26, v12, v26
	v_mul_f32_e32 v12, 0x3f4c422a, v26
	v_add_f32_e32 v12, v12, v12
	v_mul_f32_e32 v12, 0x3fb8aa3b, v12
	v_exp_f32_e32 v27, v12
	v_mul_f32_e32 v12, 0x3d372713, v14
	v_mul_f32_e32 v12, v12, v14
	v_mov_b32_e32 v26, v14
	v_fmac_f32_e32 v26, v12, v26
	v_mul_f32_e32 v12, 0x3f4c422a, v26
	v_add_f32_e32 v12, v12, v12
	v_mul_f32_e32 v12, 0x3fb8aa3b, v12
	v_exp_f32_e32 v26, v12
	v_pk_mul_f32 v[14:15], v[14:15], 0.5 op_sel_hi:[1,0]
	v_pk_add_f32 v[26:27], v[26:27], 1.0 op_sel_hi:[1,0]
	s_nop 0
	v_div_scale_f32 v12, s[14:15], v27, v27, 2.0
	v_rcp_f32_e32 v29, v12
	s_nop 0
	v_fma_f32 v30, -v12, v29, 1.0
	v_fmac_f32_e32 v29, v30, v29
	v_div_scale_f32 v30, vcc, 2.0, v27, 2.0
	v_mul_f32_e32 v31, v30, v29
	v_fma_f32 v32, -v12, v31, v30
	v_fmac_f32_e32 v31, v32, v29
	v_fma_f32 v12, -v12, v31, v30
	v_div_fmas_f32 v12, v12, v29, v31
	v_div_fixup_f32 v27, v12, v27, 2.0
	v_div_scale_f32 v12, s[14:15], v26, v26, 2.0
	v_rcp_f32_e32 v29, v12
	s_nop 0
	v_fma_f32 v30, -v12, v29, 1.0
	v_fmac_f32_e32 v29, v30, v29
	v_div_scale_f32 v30, vcc, 2.0, v26, 2.0
	v_mul_f32_e32 v31, v30, v29
	v_fma_f32 v32, -v12, v31, v30
	v_fmac_f32_e32 v31, v32, v29
	v_fma_f32 v12, -v12, v31, v30
	v_div_fmas_f32 v12, v12, v29, v31
	v_div_fixup_f32 v26, v12, v26, 2.0
	v_pk_add_f32 v[26:27], v[26:27], 1.0 op_sel_hi:[1,0] neg_lo:[1,0] neg_hi:[1,0]
	s_nop 0
	v_pk_add_f32 v[26:27], v[26:27], 1.0 op_sel_hi:[1,0]
	s_nop 0
	v_pk_mul_f32 v[14:15], v[14:15], v[26:27]
	s_nop 0
	v_pk_mul_f32 v[26:27], v[14:15], v[14:15]
	s_nop 0
	v_add_f32_e32 v12, v27, v28
	v_add_f32_e32 v28, v26, v12
	v_and_b32_e32 v12, 0xffff0000, v13
	v_lshlrev_b32_e32 v13, 16, v13
	v_mul_f32_e32 v26, 0x3d372713, v13
	v_mul_f32_e32 v26, v26, v13
	v_mov_b32_e32 v27, v13
	v_fmac_f32_e32 v27, v26, v27
	v_mul_f32_e32 v26, 0x3f4c422a, v27
	v_add_f32_e32 v26, v26, v26
	v_mul_f32_e32 v26, 0x3fb8aa3b, v26
	v_exp_f32_e32 v27, v26
	v_mul_f32_e32 v26, 0x3d372713, v12
	v_mul_f32_e32 v26, v26, v12
	v_mov_b32_e32 v29, v12
	v_fmac_f32_e32 v29, v26, v29
	v_mul_f32_e32 v26, 0x3f4c422a, v29
	v_add_f32_e32 v26, v26, v26
	v_mul_f32_e32 v26, 0x3fb8aa3b, v26
	v_exp_f32_e32 v26, v26
	v_pk_mul_f32 v[12:13], v[12:13], 0.5 op_sel_hi:[1,0]
	v_pk_add_f32 v[26:27], v[26:27], 1.0 op_sel_hi:[1,0]
	s_nop 0
	v_div_scale_f32 v29, s[14:15], v27, v27, 2.0
	v_rcp_f32_e32 v30, v29
	s_nop 0
	v_fma_f32 v31, -v29, v30, 1.0
	v_fmac_f32_e32 v30, v31, v30
	v_div_scale_f32 v31, vcc, 2.0, v27, 2.0
	v_mul_f32_e32 v32, v31, v30
	v_fma_f32 v33, -v29, v32, v31
	v_fmac_f32_e32 v32, v33, v30
	v_fma_f32 v29, -v29, v32, v31
	v_div_fmas_f32 v29, v29, v30, v32
	v_div_fixup_f32 v27, v29, v27, 2.0
	v_div_scale_f32 v29, s[14:15], v26, v26, 2.0
	v_rcp_f32_e32 v30, v29
	s_nop 0
	v_fma_f32 v31, -v29, v30, 1.0
	v_fmac_f32_e32 v30, v31, v30
	v_div_scale_f32 v31, vcc, 2.0, v26, 2.0
	v_mul_f32_e32 v32, v31, v30
	v_fma_f32 v33, -v29, v32, v31
	v_fmac_f32_e32 v32, v33, v30
	v_fma_f32 v29, -v29, v32, v31
	v_div_fmas_f32 v29, v29, v30, v32
	v_div_fixup_f32 v26, v29, v26, 2.0
	v_pk_add_f32 v[26:27], v[26:27], 1.0 op_sel_hi:[1,0] neg_lo:[1,0] neg_hi:[1,0]
	s_nop 0
	v_pk_add_f32 v[26:27], v[26:27], 1.0 op_sel_hi:[1,0]
	s_nop 0
	v_pk_mul_f32 v[26:27], v[12:13], v[26:27]
	s_nop 0
	v_pk_mul_f32 v[12:13], v[26:27], v[26:27]
	s_nop 0
	v_add_f32_e32 v13, v13, v28
	v_add_f32_e32 v12, v12, v13
	s_nop 1
	v_mov_b32_dpp v13, v12 quad_perm:[1,0,3,2] row_mask:0xf bank_mask:0xf
	s_waitcnt lgkmcnt(0)
	v_add_f32_e32 v12, v12, v13
	s_nop 1
	v_mov_b32_dpp v13, v12 quad_perm:[2,3,0,1] row_mask:0xf bank_mask:0xf
	s_waitcnt lgkmcnt(0)
	v_add_f32_e32 v12, v12, v13
	s_nop 1
	v_mov_b32_dpp v13, v12 row_half_mirror row_mask:0xf bank_mask:0xf
	s_waitcnt lgkmcnt(0)
	v_add_f32_e32 v12, v12, v13
	s_nop 1
	v_mov_b32_dpp v13, v12 row_mirror row_mask:0xf bank_mask:0xf
	s_waitcnt lgkmcnt(0)
	v_add_f32_e32 v12, v12, v13
	ds_bpermute_b32 v13, v110, v12
	s_waitcnt lgkmcnt(0)
	v_add_f32_e32 v12, v12, v13
	v_fmamk_f32 v12, v12, 0x3b800000, v243
	v_cmp_gt_f32_e32 vcc, s3, v12
	v_mul_f32_e32 v13, 0x4b800000, v12
	s_nop 0
	v_cndmask_b32_e32 v12, v12, v13, vcc
	v_rsq_f32_e32 v12, v12
	s_nop 0
	v_mul_f32_e32 v13, 0x45800000, v12
	v_cndmask_b32_e32 v28, v12, v13, vcc
	v_mul_f32_e32 v12, v20, v28
	v_mul_f32_e32 v13, v21, v28
	v_mul_f32_e32 v10, v10, v28
	v_mul_f32_e32 v12, v70, v12
	v_mul_f32_e32 v13, v71, v13
	v_mul_f32_e32 v11, v11, v28
	v_mul_f32_e32 v10, v73, v10
	v_cvt_pk_bf16_f32 v12, v12, v13
	v_cvt_pk_bf16_f32 v19, v22, v23
	v_mul_f32_e32 v11, v72, v11
	v_cvt_pk_bf16_f32 v13, v11, v10
	v_mul_f32_e32 v10, v15, v28
	v_mul_f32_e32 v10, v66, v10
	v_mul_f32_e32 v11, v14, v28
	v_cvt_pk_bf16_f32 v20, v24, v16
	v_mul_f32_e32 v11, v67, v11
	v_cvt_pk_bf16_f32 v14, v10, v11
	v_mul_f32_e32 v10, v27, v28
	v_mul_f32_e32 v10, v68, v10
	v_mul_f32_e32 v11, v26, v28
	v_cvt_pk_bf16_f32 v21, v25, v17
	v_mul_f32_e32 v11, v69, v11
	v_cvt_pk_bf16_f32 v15, v10, v11
	v_lshlrev_b32_e32 v10, 16, v6
	v_mul_f32_e32 v11, 0x3d372713, v10
	v_mul_f32_e32 v11, v11, v10
	v_fma_f32 v11, v11, v10, v10
	v_mul_f32_e32 v11, 0x3f4c422a, v11
	v_add_f32_e32 v11, v11, v11
	v_mul_f32_e32 v11, 0x3fb8aa3b, v11
	v_exp_f32_e32 v11, v11
	ds_write_b128 v111, v[18:21] offset:52224
	ds_write_b128 v112, v[12:15] offset:52224
	v_mul_f32_e32 v10, 0.5, v10
	v_and_b32_e32 v6, 0xffff0000, v6
	v_add_f32_e32 v11, 1.0, v11
	v_div_scale_f32 v12, s[14:15], v11, v11, 2.0
	v_rcp_f32_e32 v13, v12
	s_nop 0
	v_fma_f32 v14, -v12, v13, 1.0
	v_fmac_f32_e32 v13, v14, v13
	v_div_scale_f32 v14, vcc, 2.0, v11, 2.0
	v_mul_f32_e32 v15, v14, v13
	v_fma_f32 v16, -v12, v15, v14
	v_fmac_f32_e32 v15, v16, v13
	v_fma_f32 v12, -v12, v15, v14
	v_div_fmas_f32 v12, v12, v13, v15
	v_div_fixup_f32 v11, v12, v11, 2.0
	v_sub_f32_e32 v11, 1.0, v11
	v_add_f32_e32 v11, 1.0, v11
	v_mul_f32_e32 v10, v10, v11
	v_mul_f32_e32 v11, 0x3d372713, v6
	v_mul_f32_e32 v11, v11, v6
	v_fma_f32 v11, v11, v6, v6
	v_mul_f32_e32 v11, 0x3f4c422a, v11
	v_add_f32_e32 v11, v11, v11
	v_mul_f32_e32 v11, 0x3fb8aa3b, v11
	v_exp_f32_e32 v11, v11
	v_mul_f32_e32 v6, 0.5, v6
	v_add_f32_e32 v11, 1.0, v11
	v_div_scale_f32 v12, s[14:15], v11, v11, 2.0
	v_rcp_f32_e32 v13, v12
	s_nop 0
	v_fma_f32 v14, -v12, v13, 1.0
	v_fmac_f32_e32 v13, v14, v13
	v_div_scale_f32 v14, vcc, 2.0, v11, 2.0
	v_mul_f32_e32 v15, v14, v13
	v_fma_f32 v16, -v12, v15, v14
	v_fmac_f32_e32 v15, v16, v13
	v_fma_f32 v12, -v12, v15, v14
	v_div_fmas_f32 v12, v12, v13, v15
	v_div_fixup_f32 v11, v12, v11, 2.0
	v_sub_f32_e32 v11, 1.0, v11
	v_add_f32_e32 v11, 1.0, v11
	v_mul_f32_e32 v11, v6, v11
	v_lshlrev_b32_e32 v6, 16, v2
	v_mul_f32_e32 v12, 0x3d372713, v6
	v_mul_f32_e32 v12, v12, v6
	v_fma_f32 v12, v12, v6, v6
	v_mul_f32_e32 v12, 0x3f4c422a, v12
	v_add_f32_e32 v12, v12, v12
	v_mul_f32_e32 v12, 0x3fb8aa3b, v12
	v_exp_f32_e32 v12, v12
	v_mul_f32_e32 v6, 0.5, v6
	v_and_b32_e32 v2, 0xffff0000, v2
	v_cvt_pk_bf16_f32 v10, v10, v11
	v_add_f32_e32 v12, 1.0, v12
	v_div_scale_f32 v13, s[14:15], v12, v12, 2.0
	v_rcp_f32_e32 v14, v13
	s_nop 0
	v_fma_f32 v15, -v13, v14, 1.0
	v_fmac_f32_e32 v14, v15, v14
	v_div_scale_f32 v15, vcc, 2.0, v12, 2.0
	v_mul_f32_e32 v16, v15, v14
	v_fma_f32 v17, -v13, v16, v15
	v_fmac_f32_e32 v16, v17, v14
	v_fma_f32 v13, -v13, v16, v15
	v_div_fmas_f32 v13, v13, v14, v16
	v_div_fixup_f32 v12, v13, v12, 2.0
	v_sub_f32_e32 v12, 1.0, v12
	v_add_f32_e32 v12, 1.0, v12
	v_mul_f32_e32 v12, v6, v12
	v_mul_f32_e32 v6, 0x3d372713, v2
	v_mul_f32_e32 v6, v6, v2
	v_fma_f32 v6, v6, v2, v2
	v_mul_f32_e32 v6, 0x3f4c422a, v6
	v_add_f32_e32 v6, v6, v6
	v_mul_f32_e32 v6, 0x3fb8aa3b, v6
	v_exp_f32_e32 v6, v6
	v_mul_f32_e32 v2, 0.5, v2
	v_add_f32_e32 v6, 1.0, v6
	v_div_scale_f32 v13, s[14:15], v6, v6, 2.0
	v_rcp_f32_e32 v14, v13
	s_nop 0
	v_fma_f32 v15, -v13, v14, 1.0
	v_fmac_f32_e32 v14, v15, v14
	v_div_scale_f32 v15, vcc, 2.0, v6, 2.0
	v_mul_f32_e32 v16, v15, v14
	v_fma_f32 v17, -v13, v16, v15
	v_fmac_f32_e32 v16, v17, v14
	v_fma_f32 v13, -v13, v16, v15
	v_div_fmas_f32 v13, v13, v14, v16
	v_div_fixup_f32 v6, v13, v6, 2.0
	v_sub_f32_e32 v6, 1.0, v6
	v_add_f32_e32 v6, 1.0, v6
	v_mul_f32_e32 v13, v2, v6
	v_lshlrev_b32_e32 v2, 16, v7
	v_mul_f32_e32 v6, 0x3d372713, v2
	v_mul_f32_e32 v6, v6, v2
	v_fma_f32 v6, v6, v2, v2
	v_mul_f32_e32 v6, 0x3f4c422a, v6
	v_add_f32_e32 v6, v6, v6
	v_mul_f32_e32 v6, 0x3fb8aa3b, v6
	v_exp_f32_e32 v6, v6
	v_mul_f32_e32 v2, 0.5, v2
	v_add_f32_e32 v6, 1.0, v6
	v_div_scale_f32 v14, s[14:15], v6, v6, 2.0
	v_rcp_f32_e32 v15, v14
	s_nop 0
	v_fma_f32 v16, -v14, v15, 1.0
	v_fmac_f32_e32 v15, v16, v15
	v_div_scale_f32 v16, vcc, 2.0, v6, 2.0
	v_mul_f32_e32 v17, v16, v15
	v_fma_f32 v18, -v14, v17, v16
	v_fmac_f32_e32 v17, v18, v15
	v_fma_f32 v14, -v14, v17, v16
	v_div_fmas_f32 v14, v14, v15, v17
	v_div_fixup_f32 v6, v14, v6, 2.0
	v_sub_f32_e32 v6, 1.0, v6
	v_add_f32_e32 v6, 1.0, v6
	v_mul_f32_e32 v14, v2, v6
	v_and_b32_e32 v2, 0xffff0000, v7
	v_mul_f32_e32 v6, 0x3d372713, v2
	v_mul_f32_e32 v6, v6, v2
	v_fma_f32 v6, v6, v2, v2
	v_mul_f32_e32 v6, 0x3f4c422a, v6
	v_add_f32_e32 v6, v6, v6
	v_mul_f32_e32 v6, 0x3fb8aa3b, v6
	v_exp_f32_e32 v6, v6
	v_mul_f32_e32 v2, 0.5, v2
	v_add_f32_e32 v6, 1.0, v6
	v_div_scale_f32 v7, s[14:15], v6, v6, 2.0
	v_rcp_f32_e32 v15, v7
	s_nop 0
	v_fma_f32 v16, -v7, v15, 1.0
	v_fmac_f32_e32 v15, v16, v15
	v_div_scale_f32 v16, vcc, 2.0, v6, 2.0
	v_mul_f32_e32 v17, v16, v15
	v_fma_f32 v18, -v7, v17, v16
	v_fmac_f32_e32 v17, v18, v15
	v_fma_f32 v7, -v7, v17, v16
	v_div_fmas_f32 v7, v7, v15, v17
	v_div_fixup_f32 v6, v7, v6, 2.0
	v_sub_f32_e32 v6, 1.0, v6
	v_add_f32_e32 v6, 1.0, v6
	v_mul_f32_e32 v15, v2, v6
	v_lshlrev_b32_e32 v2, 16, v8
	v_mul_f32_e32 v6, 0x3d372713, v2
	v_mul_f32_e32 v6, v6, v2
	v_fma_f32 v6, v6, v2, v2
	v_mul_f32_e32 v6, 0x3f4c422a, v6
	v_add_f32_e32 v6, v6, v6
	v_mul_f32_e32 v6, 0x3fb8aa3b, v6
	v_exp_f32_e32 v6, v6
	v_mul_f32_e32 v2, 0.5, v2
	v_add_f32_e32 v6, 1.0, v6
	v_div_scale_f32 v7, s[14:15], v6, v6, 2.0
	v_rcp_f32_e32 v16, v7
	s_nop 0
	v_fma_f32 v17, -v7, v16, 1.0
	v_fmac_f32_e32 v16, v17, v16
	v_div_scale_f32 v17, vcc, 2.0, v6, 2.0
	v_mul_f32_e32 v18, v17, v16
	v_fma_f32 v19, -v7, v18, v17
	v_fmac_f32_e32 v18, v19, v16
	v_fma_f32 v7, -v7, v18, v17
	v_div_fmas_f32 v7, v7, v16, v18
	v_div_fixup_f32 v6, v7, v6, 2.0
	v_sub_f32_e32 v6, 1.0, v6
	v_add_f32_e32 v6, 1.0, v6
	v_mul_f32_e32 v16, v2, v6
	v_and_b32_e32 v2, 0xffff0000, v8
	v_mul_f32_e32 v6, 0x3d372713, v2
	v_mul_f32_e32 v6, v6, v2
	v_fma_f32 v6, v6, v2, v2
	v_mul_f32_e32 v6, 0x3f4c422a, v6
	v_add_f32_e32 v6, v6, v6
	v_mul_f32_e32 v6, 0x3fb8aa3b, v6
	v_exp_f32_e32 v6, v6
	v_mul_f32_e32 v2, 0.5, v2
	v_add_f32_e32 v6, 1.0, v6
	v_div_scale_f32 v7, s[14:15], v6, v6, 2.0
	v_rcp_f32_e32 v8, v7
	s_nop 0
	v_fma_f32 v17, -v7, v8, 1.0
	v_fmac_f32_e32 v8, v17, v8
	v_div_scale_f32 v17, vcc, 2.0, v6, 2.0
	v_mul_f32_e32 v18, v17, v8
	v_fma_f32 v19, -v7, v18, v17
	v_fmac_f32_e32 v18, v19, v8
	v_fma_f32 v7, -v7, v18, v17
	v_div_fmas_f32 v7, v7, v8, v18
	v_div_fixup_f32 v6, v7, v6, 2.0
	v_sub_f32_e32 v6, 1.0, v6
	v_add_f32_e32 v6, 1.0, v6
	v_mul_f32_e32 v8, v2, v6
	v_lshlrev_b32_e32 v2, 16, v9
	v_mul_f32_e32 v6, 0x3d372713, v2
	v_mul_f32_e32 v6, v6, v2
	v_fma_f32 v6, v6, v2, v2
	v_mul_f32_e32 v6, 0x3f4c422a, v6
	v_add_f32_e32 v6, v6, v6
	v_mul_f32_e32 v6, 0x3fb8aa3b, v6
	v_exp_f32_e32 v6, v6
	v_mul_f32_e32 v2, 0.5, v2
	v_add_f32_e32 v6, 1.0, v6
	v_div_scale_f32 v7, s[14:15], v6, v6, 2.0
	v_rcp_f32_e32 v17, v7
	s_nop 0
	v_fma_f32 v18, -v7, v17, 1.0
	v_fmac_f32_e32 v17, v18, v17
	v_div_scale_f32 v18, vcc, 2.0, v6, 2.0
	v_mul_f32_e32 v19, v18, v17
	v_fma_f32 v20, -v7, v19, v18
	v_fmac_f32_e32 v19, v20, v17
	v_fma_f32 v7, -v7, v19, v18
	v_div_fmas_f32 v7, v7, v17, v19
	v_div_fixup_f32 v6, v7, v6, 2.0
	v_sub_f32_e32 v6, 1.0, v6
	v_add_f32_e32 v6, 1.0, v6
	v_mul_f32_e32 v17, v2, v6
	v_and_b32_e32 v2, 0xffff0000, v9
	v_mul_f32_e32 v6, 0x3d372713, v2
	v_mul_f32_e32 v6, v6, v2
	v_fma_f32 v6, v6, v2, v2
	v_mul_f32_e32 v6, 0x3f4c422a, v6
	v_add_f32_e32 v6, v6, v6
	v_mul_f32_e32 v6, 0x3fb8aa3b, v6
	v_exp_f32_e32 v6, v6
	v_mul_f32_e32 v2, 0.5, v2
	v_add_f32_e32 v6, 1.0, v6
	v_div_scale_f32 v7, s[14:15], v6, v6, 2.0
	v_rcp_f32_e32 v9, v7
	s_nop 0
	v_fma_f32 v18, -v7, v9, 1.0
	v_fmac_f32_e32 v9, v18, v9
	v_div_scale_f32 v18, vcc, 2.0, v6, 2.0
	v_mul_f32_e32 v19, v18, v9
	v_fma_f32 v20, -v7, v19, v18
	v_fmac_f32_e32 v19, v20, v9
	v_fma_f32 v7, -v7, v19, v18
	v_div_fmas_f32 v7, v7, v9, v19
	v_div_fixup_f32 v6, v7, v6, 2.0
	v_sub_f32_e32 v6, 1.0, v6
	v_add_f32_e32 v6, 1.0, v6
	v_mul_f32_e32 v9, v2, v6
	v_and_b32_e32 v2, 0xffff0000, v3
	v_lshlrev_b32_e32 v3, 16, v3
	v_mul_f32_e32 v6, 0x3d372713, v3
	v_mul_f32_e32 v6, v6, v3
	v_mov_b32_e32 v7, v3
	v_fmac_f32_e32 v7, v6, v7
	v_mul_f32_e32 v6, 0x3f4c422a, v7
	v_add_f32_e32 v6, v6, v6
	v_mul_f32_e32 v6, 0x3fb8aa3b, v6
	v_exp_f32_e32 v7, v6
	v_mul_f32_e32 v6, 0x3d372713, v2
	v_mul_f32_e32 v6, v6, v2
	v_mov_b32_e32 v19, v2
	v_fmac_f32_e32 v19, v6, v19
	v_mul_f32_e32 v6, 0x3f4c422a, v19
	v_add_f32_e32 v6, v6, v6
	v_mul_f32_e32 v6, 0x3fb8aa3b, v6
	v_exp_f32_e32 v6, v6
	v_pk_mul_f32 v[2:3], v[2:3], 0.5 op_sel_hi:[1,0]
	v_mul_f32_e32 v18, v13, v13
	v_fmac_f32_e32 v18, v12, v12
	v_pk_add_f32 v[6:7], v[6:7], 1.0 op_sel_hi:[1,0]
	s_nop 0
	v_div_scale_f32 v19, s[14:15], v7, v7, 2.0
	v_rcp_f32_e32 v20, v19
	s_nop 0
	v_fma_f32 v21, -v19, v20, 1.0
	v_fmac_f32_e32 v20, v21, v20
	v_div_scale_f32 v21, vcc, 2.0, v7, 2.0
	v_mul_f32_e32 v22, v21, v20
	v_fma_f32 v23, -v19, v22, v21
	v_fmac_f32_e32 v22, v23, v20
	v_fma_f32 v19, -v19, v22, v21
	v_div_fmas_f32 v19, v19, v20, v22
	v_div_fixup_f32 v7, v19, v7, 2.0
	v_div_scale_f32 v19, s[14:15], v6, v6, 2.0
	v_rcp_f32_e32 v20, v19
	s_nop 0
	v_fma_f32 v21, -v19, v20, 1.0
	v_fmac_f32_e32 v20, v21, v20
	v_div_scale_f32 v21, vcc, 2.0, v6, 2.0
	v_mul_f32_e32 v22, v21, v20
	v_fma_f32 v23, -v19, v22, v21
	v_fmac_f32_e32 v22, v23, v20
	v_fma_f32 v19, -v19, v22, v21
	v_div_fmas_f32 v19, v19, v20, v22
	v_div_fixup_f32 v6, v19, v6, 2.0
	v_pk_add_f32 v[6:7], v[6:7], 1.0 op_sel_hi:[1,0] neg_lo:[1,0] neg_hi:[1,0]
	s_nop 0
	v_pk_add_f32 v[6:7], v[6:7], 1.0 op_sel_hi:[1,0]
	s_nop 0
	v_pk_mul_f32 v[2:3], v[2:3], v[6:7]
	s_nop 0
	v_pk_mul_f32 v[6:7], v[2:3], v[2:3]
	s_nop 0
	v_add_f32_e32 v7, v7, v18
	v_add_f32_e32 v20, v6, v7
	v_lshlrev_b32_e32 v7, 16, v4
	v_and_b32_e32 v6, 0xffff0000, v4
	v_mul_f32_e32 v4, 0x3d372713, v7
	v_mul_f32_e32 v4, v4, v7
	v_mov_b32_e32 v18, v7
	v_fmac_f32_e32 v18, v4, v18
	v_mul_f32_e32 v4, 0x3f4c422a, v18
	v_add_f32_e32 v4, v4, v4
	v_mul_f32_e32 v4, 0x3fb8aa3b, v4
	v_exp_f32_e32 v19, v4
	v_mul_f32_e32 v4, 0x3d372713, v6
	v_mul_f32_e32 v4, v4, v6
	v_mov_b32_e32 v18, v6
	v_fmac_f32_e32 v18, v4, v18
	v_mul_f32_e32 v4, 0x3f4c422a, v18
	v_add_f32_e32 v4, v4, v4
	v_mul_f32_e32 v4, 0x3fb8aa3b, v4
	v_exp_f32_e32 v18, v4
	v_pk_mul_f32 v[6:7], v[6:7], 0.5 op_sel_hi:[1,0]
	v_pk_add_f32 v[18:19], v[18:19], 1.0 op_sel_hi:[1,0]
	s_nop 0
	v_div_scale_f32 v4, s[14:15], v19, v19, 2.0
	v_rcp_f32_e32 v21, v4
	s_nop 0
	v_fma_f32 v22, -v4, v21, 1.0
	v_fmac_f32_e32 v21, v22, v21
	v_div_scale_f32 v22, vcc, 2.0, v19, 2.0
	v_mul_f32_e32 v23, v22, v21
	v_fma_f32 v24, -v4, v23, v22
	v_fmac_f32_e32 v23, v24, v21
	v_fma_f32 v4, -v4, v23, v22
	v_div_fmas_f32 v4, v4, v21, v23
	v_div_fixup_f32 v19, v4, v19, 2.0
	v_div_scale_f32 v4, s[14:15], v18, v18, 2.0
	v_rcp_f32_e32 v21, v4
	s_nop 0
	v_fma_f32 v22, -v4, v21, 1.0
	v_fmac_f32_e32 v21, v22, v21
	v_div_scale_f32 v22, vcc, 2.0, v18, 2.0
	v_mul_f32_e32 v23, v22, v21
	v_fma_f32 v24, -v4, v23, v22
	v_fmac_f32_e32 v23, v24, v21
	v_fma_f32 v4, -v4, v23, v22
	v_div_fmas_f32 v4, v4, v21, v23
	v_div_fixup_f32 v18, v4, v18, 2.0
	v_pk_add_f32 v[18:19], v[18:19], 1.0 op_sel_hi:[1,0] neg_lo:[1,0] neg_hi:[1,0]
	s_nop 0
	v_pk_add_f32 v[18:19], v[18:19], 1.0 op_sel_hi:[1,0]
	s_nop 0
	v_pk_mul_f32 v[6:7], v[6:7], v[18:19]
	s_nop 0
	v_pk_mul_f32 v[18:19], v[6:7], v[6:7]
	s_nop 0
	v_add_f32_e32 v4, v19, v20
	v_add_f32_e32 v20, v18, v4
	v_and_b32_e32 v4, 0xffff0000, v5
	v_lshlrev_b32_e32 v5, 16, v5
	v_mul_f32_e32 v18, 0x3d372713, v5
	v_mul_f32_e32 v18, v18, v5
	v_mov_b32_e32 v19, v5
	v_fmac_f32_e32 v19, v18, v19
	v_mul_f32_e32 v18, 0x3f4c422a, v19
	v_add_f32_e32 v18, v18, v18
	v_mul_f32_e32 v18, 0x3fb8aa3b, v18
	v_exp_f32_e32 v19, v18
	v_mul_f32_e32 v18, 0x3d372713, v4
	v_mul_f32_e32 v18, v18, v4
	v_mov_b32_e32 v21, v4
	v_fmac_f32_e32 v21, v18, v21
	v_mul_f32_e32 v18, 0x3f4c422a, v21
	v_add_f32_e32 v18, v18, v18
	v_mul_f32_e32 v18, 0x3fb8aa3b, v18
	v_exp_f32_e32 v18, v18
	v_pk_mul_f32 v[4:5], v[4:5], 0.5 op_sel_hi:[1,0]
	v_pk_add_f32 v[18:19], v[18:19], 1.0 op_sel_hi:[1,0]
	s_nop 0
	v_div_scale_f32 v21, s[14:15], v19, v19, 2.0
	v_rcp_f32_e32 v22, v21
	s_nop 0
	v_fma_f32 v23, -v21, v22, 1.0
	v_fmac_f32_e32 v22, v23, v22
	v_div_scale_f32 v23, vcc, 2.0, v19, 2.0
	v_mul_f32_e32 v24, v23, v22
	v_fma_f32 v25, -v21, v24, v23
	v_fmac_f32_e32 v24, v25, v22
	v_fma_f32 v21, -v21, v24, v23
	v_div_fmas_f32 v21, v21, v22, v24
	v_div_fixup_f32 v19, v21, v19, 2.0
	v_div_scale_f32 v21, s[14:15], v18, v18, 2.0
	v_rcp_f32_e32 v22, v21
	s_nop 0
	v_fma_f32 v23, -v21, v22, 1.0
	v_fmac_f32_e32 v22, v23, v22
	v_div_scale_f32 v23, vcc, 2.0, v18, 2.0
	v_mul_f32_e32 v24, v23, v22
	v_fma_f32 v25, -v21, v24, v23
	v_fmac_f32_e32 v24, v25, v22
	v_fma_f32 v21, -v21, v24, v23
	v_div_fmas_f32 v21, v21, v22, v24
	v_div_fixup_f32 v18, v21, v18, 2.0
	v_pk_add_f32 v[18:19], v[18:19], 1.0 op_sel_hi:[1,0] neg_lo:[1,0] neg_hi:[1,0]
	s_nop 0
	v_pk_add_f32 v[18:19], v[18:19], 1.0 op_sel_hi:[1,0]
	s_nop 0
	v_pk_mul_f32 v[18:19], v[4:5], v[18:19]
	s_nop 0
	v_pk_mul_f32 v[4:5], v[18:19], v[18:19]
	s_nop 0
	v_add_f32_e32 v5, v5, v20
	v_add_f32_e32 v4, v4, v5
	s_nop 1
	v_mov_b32_dpp v5, v4 quad_perm:[1,0,3,2] row_mask:0xf bank_mask:0xf
	s_waitcnt lgkmcnt(0)
	v_add_f32_e32 v4, v4, v5
	s_nop 1
	v_mov_b32_dpp v5, v4 quad_perm:[2,3,0,1] row_mask:0xf bank_mask:0xf
	s_waitcnt lgkmcnt(0)
	v_add_f32_e32 v4, v4, v5
	s_nop 1
	v_mov_b32_dpp v5, v4 row_half_mirror row_mask:0xf bank_mask:0xf
	s_waitcnt lgkmcnt(0)
	v_add_f32_e32 v4, v4, v5
	s_nop 1
	v_mov_b32_dpp v5, v4 row_mirror row_mask:0xf bank_mask:0xf
	s_waitcnt lgkmcnt(0)
	v_add_f32_e32 v4, v4, v5
	ds_bpermute_b32 v5, v110, v4
	s_waitcnt lgkmcnt(0)
	v_add_f32_e32 v4, v4, v5
	v_fmamk_f32 v4, v4, 0x3b800000, v243
	v_cmp_gt_f32_e32 vcc, s3, v4
	v_mul_f32_e32 v5, 0x4b800000, v4
	s_nop 0
	v_cndmask_b32_e32 v4, v4, v5, vcc
	v_rsq_f32_e32 v4, v4
	s_nop 0
	v_mul_f32_e32 v5, 0x45800000, v4
	v_cndmask_b32_e32 v20, v4, v5, vcc
	v_mul_f32_e32 v4, v12, v20
	v_mul_f32_e32 v5, v13, v20
	v_mul_f32_e32 v2, v2, v20
	v_mul_f32_e32 v4, v70, v4
	v_mul_f32_e32 v5, v71, v5
	v_mul_f32_e32 v3, v3, v20
	v_mul_f32_e32 v2, v73, v2
	v_cvt_pk_bf16_f32 v4, v4, v5
	v_cvt_pk_bf16_f32 v11, v14, v15
	v_mul_f32_e32 v3, v72, v3
	v_cvt_pk_bf16_f32 v5, v3, v2
	v_mul_f32_e32 v2, v7, v20
	v_mul_f32_e32 v2, v66, v2
	v_mul_f32_e32 v3, v6, v20
	v_cvt_pk_bf16_f32 v12, v16, v8
	v_mul_f32_e32 v3, v67, v3
	v_cvt_pk_bf16_f32 v6, v2, v3
	v_mul_f32_e32 v2, v19, v20
	v_mul_f32_e32 v2, v68, v2
	v_mul_f32_e32 v3, v18, v20
	v_cvt_pk_bf16_f32 v13, v17, v9
	v_mul_f32_e32 v3, v69, v3
	v_cvt_pk_bf16_f32 v7, v2, v3
	v_mov_b32_e32 v2, 0
	ds_write_b128 v111, v[10:13] offset:60928
	ds_write_b128 v112, v[4:7] offset:60928
	v_mov_b32_e32 v3, v2
	v_mov_b32_e32 v4, v2
	v_mov_b32_e32 v5, v2
	v_mov_b32_e32 v6, v2
	v_mov_b32_e32 v7, v2
	v_mov_b32_e32 v8, v2
	v_mov_b32_e32 v9, v2
	v_mov_b32_e32 v10, v2
	v_mov_b32_e32 v11, v2
	v_mov_b32_e32 v12, v2
	v_mov_b32_e32 v13, v2
	v_mov_b32_e32 v14, v2
	v_mov_b32_e32 v15, v2
	v_mov_b32_e32 v16, v2
	v_mov_b32_e32 v17, v2
	v_mov_b32_e32 v18, v2
	v_mov_b32_e32 v19, v2
	v_mov_b32_e32 v20, v2
	v_mov_b32_e32 v21, v2
	v_mov_b32_e32 v22, v2
	v_mov_b32_e32 v23, v2
	v_mov_b32_e32 v24, v2
	v_mov_b32_e32 v25, v2
	v_mov_b32_e32 v26, v2
	v_mov_b32_e32 v27, v2
	v_mov_b32_e32 v28, v2
	v_mov_b32_e32 v29, v2
	v_mov_b32_e32 v30, v2
	v_mov_b32_e32 v31, v2
	v_mov_b32_e32 v32, v2
	v_mov_b32_e32 v33, v2
	v_mov_b32_e32 v34, v2
	v_mov_b32_e32 v35, v2
	v_mov_b32_e32 v36, v2
	v_mov_b32_e32 v37, v2
	v_mov_b32_e32 v38, v2
	v_mov_b32_e32 v39, v2
	v_mov_b32_e32 v40, v2
	v_mov_b32_e32 v41, v2
	v_mov_b32_e32 v42, v2
	v_mov_b32_e32 v43, v2
	v_mov_b32_e32 v44, v2
	v_mov_b32_e32 v45, v2
	v_mov_b32_e32 v46, v2
	v_mov_b32_e32 v47, v2
	v_mov_b32_e32 v48, v2
	v_mov_b32_e32 v49, v2
	v_mov_b32_e32 v50, v2
	v_mov_b32_e32 v51, v2
	v_mov_b32_e32 v52, v2
	v_mov_b32_e32 v53, v2
	v_mov_b32_e32 v54, v2
	v_mov_b32_e32 v55, v2
	v_mov_b32_e32 v56, v2
	v_mov_b32_e32 v57, v2
	v_mov_b32_e32 v58, v2
	v_mov_b32_e32 v59, v2
	v_mov_b32_e32 v60, v2
	v_mov_b32_e32 v61, v2
	v_mov_b32_e32 v62, v2
	v_mov_b32_e32 v63, v2
	v_mov_b32_e32 v64, v2
	v_mov_b32_e32 v65, v2
	s_waitcnt lgkmcnt(0)
	s_barrier
